# EpiZ misc path: forget-gate biases preloaded once (16 bytes) instead of 32 serialized load/wait round trips per tile
# speedup vs baseline: 1.0044x; 1.0007x over previous
.LBB0_943:
	s_add_u32 s36, s52, s24
	s_addc_u32 s37, s53, s25
	s_add_u32 s40, s29, 0x10200000
	s_addc_u32 s41, s45, 0
	s_and_saveexec_b64 s[44:45], s[38:39]
	s_mov_b32 s29, 0xbfb8aa3b
	s_movk_i32 s53, 0x5ff
	s_mov_b32 s50, 0x3f2aaaab
	s_mov_b32 s51, 0x3f317218
	s_mov_b32 s52, 0x7f800000
	s_cbranch_execz .LBB0_961
	global_load_dwordx4 v[248:251], v1, s[36:37]
	s_and_saveexec_b64 s[46:47], s[2:3]
	s_xor_b64 s[46:47], exec, s[46:47]
	s_cbranch_execz .LBB0_946
	v_mul_f32_e32 v114, 0xbfb8aa3b, v148
	v_exp_f32_e32 v114, v114
	s_nop 0
	v_add_f32_e32 v114, 1.0, v114
	v_rcp_f32_e32 v114, v114
.LBB0_946:
	s_andn2_saveexec_b64 s[46:47], s[46:47]
	s_cbranch_execz .LBB0_948
	s_mov_b32 s48, 0x33800000
	s_waitcnt vmcnt(0)
	v_mov_b32_e32 v114, v248
	v_add_f32_e32 v115, v148, v114
	v_min_f32_e32 v114, 0, v115
	v_mul_f32_e64 v115, |v115|, s29
	v_exp_f32_e32 v115, v115
	s_nop 0
	v_add_f32_e32 v132, 1.0, v115
	v_add_f32_e32 v116, -1.0, v132
	v_sub_f32_e32 v117, v116, v132
	v_add_f32_e32 v117, 1.0, v117
	v_sub_f32_e32 v116, v115, v116
	v_add_f32_e32 v133, v116, v117
	v_frexp_mant_f32_e32 v116, v132
	v_cmp_gt_f32_e32 vcc, s50, v116
	v_cvt_f64_f32_e32 v[116:117], v132
	v_frexp_exp_i32_f64_e32 v116, v[116:117]
	v_subbrev_co_u32_e32 v140, vcc, 0, v116, vcc
	v_sub_u32_e32 v116, 0, v140
	v_ldexp_f32 v117, v132, v116
	v_add_f32_e32 v132, -1.0, v117
	v_add_f32_e32 v136, 1.0, v117
	v_ldexp_f32 v116, v133, v116
	v_add_f32_e32 v133, 1.0, v132
	v_add_f32_e32 v137, -1.0, v136
	v_sub_f32_e32 v133, v117, v133
	v_sub_f32_e32 v117, v117, v137
	v_add_f32_e32 v133, v116, v133
	v_add_f32_e32 v116, v116, v117
	v_add_f32_e32 v141, v136, v116
	v_rcp_f32_e32 v143, v141
	v_sub_f32_e32 v117, v141, v136
	v_sub_f32_e32 v142, v116, v117
	v_add_f32_e32 v117, v132, v133
	v_mul_f32_e32 v145, v117, v143
	v_sub_f32_e32 v116, v117, v132
	v_mul_f32_e32 v132, v141, v145
	v_fma_f32 v136, v145, v141, -v132
	v_fmac_f32_e32 v136, v145, v142
	v_sub_f32_e32 v144, v133, v116
	v_add_f32_e32 v116, v132, v136
	v_sub_f32_e32 v133, v117, v116
	v_pk_add_f32 v[138:139], v[116:117], v[132:133] neg_lo:[0,1] neg_hi:[0,1]
	v_mov_b32_e32 v137, v116
	v_pk_add_f32 v[116:117], v[138:139], v[136:137] neg_lo:[0,1] neg_hi:[0,1]
	v_cmp_neq_f32_e32 vcc, s52, v115
	v_add_f32_e32 v117, v144, v117
	v_add_f32_e32 v116, v116, v117
	v_add_f32_e32 v117, v133, v116
	v_mul_f32_e32 v144, v143, v117
	v_mul_f32_e32 v132, v141, v144
	v_fma_f32 v136, v144, v141, -v132
	v_fmac_f32_e32 v136, v144, v142
	v_sub_f32_e32 v133, v133, v117
	v_add_f32_e32 v141, v116, v133
	v_add_f32_e32 v116, v132, v136
	v_sub_f32_e32 v133, v117, v116
	v_pk_add_f32 v[138:139], v[116:117], v[132:133] neg_lo:[0,1] neg_hi:[0,1]
	v_mov_b32_e32 v137, v116
	v_pk_add_f32 v[116:117], v[138:139], v[136:137] neg_lo:[0,1] neg_hi:[0,1]
	s_nop 0
	v_add_f32_e32 v117, v141, v117
	v_add_f32_e32 v116, v116, v117
	v_add_f32_e32 v117, v145, v144
	v_add_f32_e32 v116, v133, v116
	v_sub_f32_e32 v132, v117, v145
	v_mul_f32_e32 v116, v143, v116
	v_sub_f32_e32 v132, v144, v132
	v_add_f32_e32 v132, v132, v116
	v_add_f32_e32 v136, v117, v132
	v_mul_f32_e32 v137, v136, v136
	v_fmamk_f32 v116, v137, 0x3e9b6dac, v233
	v_fmaak_f32 v185, v137, v116, 0x3f2aaada
	v_cvt_f32_i32_e32 v116, v140
	v_sub_f32_e32 v117, v136, v117
	v_sub_f32_e32 v117, v132, v117
	v_ldexp_f32 v138, v117, 1
	v_mul_f32_e32 v117, v136, v137
	v_ldexp_f32 v133, v136, 1
	v_pk_mul_f32 v[136:137], v[116:117], v[184:185]
	s_nop 0
	v_fma_f32 v132, v116, s51, -v136
	v_fmac_f32_e32 v132, 0xb102e308, v116
	v_pk_add_f32 v[116:117], v[136:137], v[132:133]
	s_nop 0
	v_sub_f32_e32 v133, v117, v133
	v_sub_f32_e32 v133, v137, v133
	v_add_f32_e32 v139, v138, v133
	v_mov_b32_e32 v138, v136
	v_pk_add_f32 v[136:137], v[116:117], v[136:137] neg_lo:[0,1] neg_hi:[0,1]
	v_pk_add_f32 v[140:141], v[116:117], v[138:139]
	v_mov_b32_e32 v133, v116
	v_mov_b32_e32 v137, v141
	v_pk_add_f32 v[142:143], v[132:133], v[136:137] neg_lo:[0,1] neg_hi:[0,1]
	v_pk_add_f32 v[132:133], v[132:133], v[136:137]
	v_mov_b32_e32 v138, v139
	v_pk_add_f32 v[136:137], v[132:133], v[116:117] op_sel:[1,0] op_sel_hi:[0,1] neg_lo:[0,1] neg_hi:[0,1]
	v_pk_add_f32 v[144:145], v[140:141], v[136:137] op_sel_hi:[1,0] neg_lo:[0,1] neg_hi:[0,1]
	v_mov_b32_e32 v140, v141
	v_mov_b32_e32 v141, v133
	v_pk_mov_b32 v[136:137], v[116:117], v[136:137] op_sel:[1,0]
	v_mov_b32_e32 v139, v116
	v_pk_add_f32 v[136:137], v[140:141], v[136:137] neg_lo:[0,1] neg_hi:[0,1]
	v_mov_b32_e32 v144, v142
	v_pk_add_f32 v[116:117], v[138:139], v[136:137] neg_lo:[0,1] neg_hi:[0,1]
	v_mov_b32_e32 v143, v133
	v_pk_add_f32 v[136:137], v[144:145], v[116:117]
	s_nop 0
	v_pk_add_f32 v[138:139], v[136:137], v[136:137] op_sel:[0,1] op_sel_hi:[1,0]
	s_nop 0
	v_pk_add_f32 v[132:133], v[132:133], v[138:139] op_sel:[1,0] op_sel_hi:[0,1]
	v_mov_b32_e32 v137, v132
	v_pk_add_f32 v[140:141], v[136:137], v[142:143] neg_lo:[0,1] neg_hi:[0,1]
	v_mov_b32_e32 v117, v138
	v_sub_f32_e32 v133, v136, v140
	v_pk_add_f32 v[116:117], v[116:117], v[140:141] neg_lo:[0,1] neg_hi:[0,1]
	v_sub_f32_e32 v133, v142, v133
	v_add_f32_e32 v116, v116, v133
	v_add_f32_e32 v116, v116, v117
	v_add_f32_e32 v116, v132, v116
	v_cndmask_b32_e32 v116, v226, v116, vcc
	v_cmp_ngt_f32_e32 vcc, -1.0, v115
	s_nop 1
	v_cndmask_b32_e32 v116, v227, v116, vcc
	v_cmp_neq_f32_e32 vcc, -1.0, v115
	s_nop 1
	v_cndmask_b32_e32 v116, v236, v116, vcc
	v_cmp_lt_f32_e64 vcc, |v115|, s48
	s_nop 1
	v_cndmask_b32_e32 v115, v116, v115, vcc
	v_sub_f32_e32 v114, v114, v115

.LBB0_950:
	s_andn2_saveexec_b64 s[46:47], s[46:47]
	s_cbranch_execz .LBB0_952
	s_mov_b32 s48, 0x33800000
	s_waitcnt vmcnt(0)
	v_mov_b32_e32 v114, v249
	v_add_f32_e32 v115, v149, v114
	v_min_f32_e32 v114, 0, v115
	v_mul_f32_e64 v115, |v115|, s29
	v_exp_f32_e32 v115, v115
	s_nop 0
	v_add_f32_e32 v136, 1.0, v115
	v_add_f32_e32 v116, -1.0, v136
	v_sub_f32_e32 v117, v116, v136
	v_add_f32_e32 v117, 1.0, v117
	v_sub_f32_e32 v116, v115, v116
	v_add_f32_e32 v137, v116, v117
	v_frexp_mant_f32_e32 v116, v136
	v_cmp_gt_f32_e32 vcc, s50, v116
	v_cvt_f64_f32_e32 v[116:117], v136
	v_frexp_exp_i32_f64_e32 v116, v[116:117]
	v_subbrev_co_u32_e32 v142, vcc, 0, v116, vcc
	v_sub_u32_e32 v116, 0, v142
	v_ldexp_f32 v117, v136, v116
	v_add_f32_e32 v136, -1.0, v117
	v_add_f32_e32 v138, 1.0, v117
	v_ldexp_f32 v116, v137, v116
	v_add_f32_e32 v137, 1.0, v136
	v_add_f32_e32 v139, -1.0, v138
	v_sub_f32_e32 v137, v117, v137
	v_sub_f32_e32 v117, v117, v139
	v_add_f32_e32 v137, v116, v137
	v_add_f32_e32 v116, v116, v117
	v_add_f32_e32 v143, v138, v116
	v_rcp_f32_e32 v145, v143
	v_sub_f32_e32 v117, v143, v138
	v_sub_f32_e32 v144, v116, v117
	v_add_f32_e32 v117, v136, v137
	v_mul_f32_e32 v177, v117, v145
	v_sub_f32_e32 v116, v117, v136
	v_mul_f32_e32 v136, v143, v177
	v_fma_f32 v138, v177, v143, -v136
	v_fmac_f32_e32 v138, v177, v144
	v_sub_f32_e32 v176, v137, v116
	v_add_f32_e32 v116, v136, v138
	v_sub_f32_e32 v137, v117, v116
	v_pk_add_f32 v[140:141], v[116:117], v[136:137] neg_lo:[0,1] neg_hi:[0,1]
	v_mov_b32_e32 v139, v116
	v_pk_add_f32 v[116:117], v[140:141], v[138:139] neg_lo:[0,1] neg_hi:[0,1]
	v_cmp_neq_f32_e32 vcc, s52, v115
	v_add_f32_e32 v117, v176, v117
	v_add_f32_e32 v116, v116, v117
	v_add_f32_e32 v117, v137, v116
	v_mul_f32_e32 v176, v145, v117
	v_mul_f32_e32 v136, v143, v176
	v_fma_f32 v138, v176, v143, -v136
	v_fmac_f32_e32 v138, v176, v144
	v_sub_f32_e32 v137, v137, v117
	v_add_f32_e32 v143, v116, v137
	v_add_f32_e32 v116, v136, v138
	v_sub_f32_e32 v137, v117, v116
	v_pk_add_f32 v[140:141], v[116:117], v[136:137] neg_lo:[0,1] neg_hi:[0,1]
	v_mov_b32_e32 v139, v116
	v_pk_add_f32 v[116:117], v[140:141], v[138:139] neg_lo:[0,1] neg_hi:[0,1]
	s_nop 0
	v_add_f32_e32 v117, v143, v117
	v_add_f32_e32 v116, v116, v117
	v_add_f32_e32 v117, v177, v176
	v_add_f32_e32 v116, v137, v116
	v_sub_f32_e32 v136, v117, v177
	v_mul_f32_e32 v116, v145, v116
	v_sub_f32_e32 v136, v176, v136
	v_add_f32_e32 v136, v136, v116
	v_add_f32_e32 v138, v117, v136
	v_mul_f32_e32 v139, v138, v138
	v_fmamk_f32 v116, v139, 0x3e9b6dac, v233
	v_fmaak_f32 v185, v139, v116, 0x3f2aaada
	v_cvt_f32_i32_e32 v116, v142
	v_sub_f32_e32 v117, v138, v117
	v_sub_f32_e32 v117, v136, v117
	v_ldexp_f32 v140, v117, 1
	v_mul_f32_e32 v117, v138, v139
	v_ldexp_f32 v137, v138, 1
	v_pk_mul_f32 v[138:139], v[116:117], v[184:185]
	s_nop 0
	v_fma_f32 v136, v116, s51, -v138
	v_fmac_f32_e32 v136, 0xb102e308, v116
	v_pk_add_f32 v[116:117], v[138:139], v[136:137]
	s_nop 0
	v_sub_f32_e32 v137, v117, v137
	v_sub_f32_e32 v137, v139, v137
	v_add_f32_e32 v141, v140, v137
	v_mov_b32_e32 v140, v138
	v_pk_add_f32 v[138:139], v[116:117], v[138:139] neg_lo:[0,1] neg_hi:[0,1]
	v_pk_add_f32 v[142:143], v[116:117], v[140:141]
	v_mov_b32_e32 v137, v116
	v_mov_b32_e32 v139, v143
	v_pk_add_f32 v[144:145], v[136:137], v[138:139] neg_lo:[0,1] neg_hi:[0,1]
	v_pk_add_f32 v[136:137], v[136:137], v[138:139]
	v_mov_b32_e32 v140, v141
	v_pk_add_f32 v[138:139], v[136:137], v[116:117] op_sel:[1,0] op_sel_hi:[0,1] neg_lo:[0,1] neg_hi:[0,1]
	v_pk_add_f32 v[176:177], v[142:143], v[138:139] op_sel_hi:[1,0] neg_lo:[0,1] neg_hi:[0,1]
	v_mov_b32_e32 v142, v143
	v_mov_b32_e32 v143, v137
	v_pk_mov_b32 v[138:139], v[116:117], v[138:139] op_sel:[1,0]
	v_mov_b32_e32 v141, v116
	v_pk_add_f32 v[138:139], v[142:143], v[138:139] neg_lo:[0,1] neg_hi:[0,1]
	v_mov_b32_e32 v176, v144
	v_pk_add_f32 v[116:117], v[140:141], v[138:139] neg_lo:[0,1] neg_hi:[0,1]
	v_mov_b32_e32 v145, v137
	v_pk_add_f32 v[138:139], v[176:177], v[116:117]
	s_nop 0
	v_pk_add_f32 v[140:141], v[138:139], v[138:139] op_sel:[0,1] op_sel_hi:[1,0]
	s_nop 0
	v_pk_add_f32 v[136:137], v[136:137], v[140:141] op_sel:[1,0] op_sel_hi:[0,1]
	v_mov_b32_e32 v139, v136
	v_pk_add_f32 v[142:143], v[138:139], v[144:145] neg_lo:[0,1] neg_hi:[0,1]
	v_mov_b32_e32 v117, v140
	v_sub_f32_e32 v137, v138, v142
	v_pk_add_f32 v[116:117], v[116:117], v[142:143] neg_lo:[0,1] neg_hi:[0,1]
	v_sub_f32_e32 v137, v144, v137
	v_add_f32_e32 v116, v116, v137
	v_add_f32_e32 v116, v116, v117
	v_add_f32_e32 v116, v136, v116
	v_cndmask_b32_e32 v116, v226, v116, vcc
	v_cmp_ngt_f32_e32 vcc, -1.0, v115
	s_nop 1
	v_cndmask_b32_e32 v116, v227, v116, vcc
	v_cmp_neq_f32_e32 vcc, -1.0, v115
	s_nop 1
	v_cndmask_b32_e32 v116, v236, v116, vcc
	v_cmp_lt_f32_e64 vcc, |v115|, s48
	s_nop 1
	v_cndmask_b32_e32 v115, v116, v115, vcc
	v_sub_f32_e32 v114, v114, v115

.LBB0_954:
	s_andn2_saveexec_b64 s[46:47], s[46:47]
	s_cbranch_execz .LBB0_956
	s_mov_b32 s48, 0x33800000
	s_waitcnt vmcnt(0)
	v_mov_b32_e32 v114, v250
	v_add_f32_e32 v115, v158, v114
	v_min_f32_e32 v114, 0, v115
	v_mul_f32_e64 v115, |v115|, s29
	v_exp_f32_e32 v115, v115
	s_nop 0
	v_add_f32_e32 v136, 1.0, v115
	v_add_f32_e32 v116, -1.0, v136
	v_sub_f32_e32 v117, v116, v136
	v_add_f32_e32 v117, 1.0, v117
	v_sub_f32_e32 v116, v115, v116
	v_add_f32_e32 v137, v116, v117
	v_frexp_mant_f32_e32 v116, v136
	v_cmp_gt_f32_e32 vcc, s50, v116
	v_cvt_f64_f32_e32 v[116:117], v136
	v_frexp_exp_i32_f64_e32 v116, v[116:117]
	v_subbrev_co_u32_e32 v142, vcc, 0, v116, vcc
	v_sub_u32_e32 v116, 0, v142
	v_ldexp_f32 v117, v136, v116
	v_add_f32_e32 v136, -1.0, v117
	v_add_f32_e32 v138, 1.0, v117
	v_ldexp_f32 v116, v137, v116
	v_add_f32_e32 v137, 1.0, v136
	v_add_f32_e32 v139, -1.0, v138
	v_sub_f32_e32 v137, v117, v137
	v_sub_f32_e32 v117, v117, v139
	v_add_f32_e32 v137, v116, v137
	v_add_f32_e32 v116, v116, v117
	v_add_f32_e32 v143, v138, v116
	v_rcp_f32_e32 v145, v143
	v_sub_f32_e32 v117, v143, v138
	v_sub_f32_e32 v144, v116, v117
	v_add_f32_e32 v117, v136, v137
	v_mul_f32_e32 v177, v117, v145
	v_sub_f32_e32 v116, v117, v136
	v_mul_f32_e32 v136, v143, v177
	v_fma_f32 v138, v177, v143, -v136
	v_fmac_f32_e32 v138, v177, v144
	v_sub_f32_e32 v176, v137, v116
	v_add_f32_e32 v116, v136, v138
	v_sub_f32_e32 v137, v117, v116
	v_pk_add_f32 v[140:141], v[116:117], v[136:137] neg_lo:[0,1] neg_hi:[0,1]
	v_mov_b32_e32 v139, v116
	v_pk_add_f32 v[116:117], v[140:141], v[138:139] neg_lo:[0,1] neg_hi:[0,1]
	v_cmp_neq_f32_e32 vcc, s52, v115
	v_add_f32_e32 v117, v176, v117
	v_add_f32_e32 v116, v116, v117
	v_add_f32_e32 v117, v137, v116
	v_mul_f32_e32 v176, v145, v117
	v_mul_f32_e32 v136, v143, v176
	v_fma_f32 v138, v176, v143, -v136
	v_fmac_f32_e32 v138, v176, v144
	v_sub_f32_e32 v137, v137, v117
	v_add_f32_e32 v143, v116, v137
	v_add_f32_e32 v116, v136, v138
	v_sub_f32_e32 v137, v117, v116
	v_pk_add_f32 v[140:141], v[116:117], v[136:137] neg_lo:[0,1] neg_hi:[0,1]
	v_mov_b32_e32 v139, v116
	v_pk_add_f32 v[116:117], v[140:141], v[138:139] neg_lo:[0,1] neg_hi:[0,1]
	s_nop 0
	v_add_f32_e32 v117, v143, v117
	v_add_f32_e32 v116, v116, v117
	v_add_f32_e32 v117, v177, v176
	v_add_f32_e32 v116, v137, v116
	v_sub_f32_e32 v136, v117, v177
	v_mul_f32_e32 v116, v145, v116
	v_sub_f32_e32 v136, v176, v136
	v_add_f32_e32 v136, v136, v116
	v_add_f32_e32 v138, v117, v136
	v_mul_f32_e32 v139, v138, v138
	v_fmamk_f32 v116, v139, 0x3e9b6dac, v233
	v_fmaak_f32 v185, v139, v116, 0x3f2aaada
	v_cvt_f32_i32_e32 v116, v142
	v_sub_f32_e32 v117, v138, v117
	v_sub_f32_e32 v117, v136, v117
	v_ldexp_f32 v140, v117, 1
	v_mul_f32_e32 v117, v138, v139
	v_ldexp_f32 v137, v138, 1
	v_pk_mul_f32 v[138:139], v[116:117], v[184:185]
	s_nop 0
	v_fma_f32 v136, v116, s51, -v138
	v_fmac_f32_e32 v136, 0xb102e308, v116
	v_pk_add_f32 v[116:117], v[138:139], v[136:137]
	s_nop 0
	v_sub_f32_e32 v137, v117, v137
	v_sub_f32_e32 v137, v139, v137
	v_add_f32_e32 v141, v140, v137
	v_mov_b32_e32 v140, v138
	v_pk_add_f32 v[138:139], v[116:117], v[138:139] neg_lo:[0,1] neg_hi:[0,1]
	v_pk_add_f32 v[142:143], v[116:117], v[140:141]
	v_mov_b32_e32 v137, v116
	v_mov_b32_e32 v139, v143
	v_pk_add_f32 v[144:145], v[136:137], v[138:139] neg_lo:[0,1] neg_hi:[0,1]
	v_pk_add_f32 v[136:137], v[136:137], v[138:139]
	v_mov_b32_e32 v140, v141
	v_pk_add_f32 v[138:139], v[136:137], v[116:117] op_sel:[1,0] op_sel_hi:[0,1] neg_lo:[0,1] neg_hi:[0,1]
	v_pk_add_f32 v[176:177], v[142:143], v[138:139] op_sel_hi:[1,0] neg_lo:[0,1] neg_hi:[0,1]
	v_mov_b32_e32 v142, v143
	v_mov_b32_e32 v143, v137
	v_pk_mov_b32 v[138:139], v[116:117], v[138:139] op_sel:[1,0]
	v_mov_b32_e32 v141, v116
	v_pk_add_f32 v[138:139], v[142:143], v[138:139] neg_lo:[0,1] neg_hi:[0,1]
	v_mov_b32_e32 v176, v144
	v_pk_add_f32 v[116:117], v[140:141], v[138:139] neg_lo:[0,1] neg_hi:[0,1]
	v_mov_b32_e32 v145, v137
	v_pk_add_f32 v[138:139], v[176:177], v[116:117]
	s_nop 0
	v_pk_add_f32 v[140:141], v[138:139], v[138:139] op_sel:[0,1] op_sel_hi:[1,0]
	s_nop 0
	v_pk_add_f32 v[136:137], v[136:137], v[140:141] op_sel:[1,0] op_sel_hi:[0,1]
	v_mov_b32_e32 v139, v136
	v_pk_add_f32 v[142:143], v[138:139], v[144:145] neg_lo:[0,1] neg_hi:[0,1]
	v_mov_b32_e32 v117, v140
	v_sub_f32_e32 v137, v138, v142
	v_pk_add_f32 v[116:117], v[116:117], v[142:143] neg_lo:[0,1] neg_hi:[0,1]
	v_sub_f32_e32 v137, v144, v137
	v_add_f32_e32 v116, v116, v137
	v_add_f32_e32 v116, v116, v117
	v_add_f32_e32 v116, v136, v116
	v_cndmask_b32_e32 v116, v226, v116, vcc
	v_cmp_ngt_f32_e32 vcc, -1.0, v115
	s_nop 1
	v_cndmask_b32_e32 v116, v227, v116, vcc
	v_cmp_neq_f32_e32 vcc, -1.0, v115
	s_nop 1
	v_cndmask_b32_e32 v116, v236, v116, vcc
	v_cmp_lt_f32_e64 vcc, |v115|, s48
	s_nop 1
	v_cndmask_b32_e32 v115, v116, v115, vcc
	v_sub_f32_e32 v114, v114, v115

.LBB0_958:
	s_andn2_saveexec_b64 s[46:47], s[46:47]
	s_cbranch_execz .LBB0_960
	s_mov_b32 s48, 0x33800000
	s_waitcnt vmcnt(0)
	v_mov_b32_e32 v114, v251
	v_add_f32_e32 v115, v159, v114
	v_min_f32_e32 v114, 0, v115
	v_mul_f32_e64 v115, |v115|, s29
	v_exp_f32_e32 v115, v115
	s_nop 0
	v_add_f32_e32 v136, 1.0, v115
	v_add_f32_e32 v116, -1.0, v136
	v_sub_f32_e32 v117, v116, v136
	v_add_f32_e32 v117, 1.0, v117
	v_sub_f32_e32 v116, v115, v116
	v_add_f32_e32 v137, v116, v117
	v_frexp_mant_f32_e32 v116, v136
	v_cmp_gt_f32_e32 vcc, s50, v116
	v_cvt_f64_f32_e32 v[116:117], v136
	v_frexp_exp_i32_f64_e32 v116, v[116:117]
	v_subbrev_co_u32_e32 v142, vcc, 0, v116, vcc
	v_sub_u32_e32 v116, 0, v142
	v_ldexp_f32 v117, v136, v116
	v_add_f32_e32 v136, -1.0, v117
	v_add_f32_e32 v138, 1.0, v117
	v_ldexp_f32 v116, v137, v116
	v_add_f32_e32 v137, 1.0, v136
	v_add_f32_e32 v139, -1.0, v138
	v_sub_f32_e32 v137, v117, v137
	v_sub_f32_e32 v117, v117, v139
	v_add_f32_e32 v137, v116, v137
	v_add_f32_e32 v116, v116, v117
	v_add_f32_e32 v143, v138, v116
	v_rcp_f32_e32 v145, v143
	v_sub_f32_e32 v117, v143, v138
	v_sub_f32_e32 v144, v116, v117
	v_add_f32_e32 v117, v136, v137
	v_mul_f32_e32 v177, v117, v145
	v_sub_f32_e32 v116, v117, v136
	v_mul_f32_e32 v136, v143, v177
	v_fma_f32 v138, v177, v143, -v136
	v_fmac_f32_e32 v138, v177, v144
	v_sub_f32_e32 v176, v137, v116
	v_add_f32_e32 v116, v136, v138
	v_sub_f32_e32 v137, v117, v116
	v_pk_add_f32 v[140:141], v[116:117], v[136:137] neg_lo:[0,1] neg_hi:[0,1]
	v_mov_b32_e32 v139, v116
	v_pk_add_f32 v[116:117], v[140:141], v[138:139] neg_lo:[0,1] neg_hi:[0,1]
	v_cmp_neq_f32_e32 vcc, s52, v115
	v_add_f32_e32 v117, v176, v117
	v_add_f32_e32 v116, v116, v117
	v_add_f32_e32 v117, v137, v116
	v_mul_f32_e32 v176, v145, v117
	v_mul_f32_e32 v136, v143, v176
	v_fma_f32 v138, v176, v143, -v136
	v_fmac_f32_e32 v138, v176, v144
	v_sub_f32_e32 v137, v137, v117
	v_add_f32_e32 v143, v116, v137
	v_add_f32_e32 v116, v136, v138
	v_sub_f32_e32 v137, v117, v116
	v_pk_add_f32 v[140:141], v[116:117], v[136:137] neg_lo:[0,1] neg_hi:[0,1]
	v_mov_b32_e32 v139, v116
	v_pk_add_f32 v[116:117], v[140:141], v[138:139] neg_lo:[0,1] neg_hi:[0,1]
	s_nop 0
	v_add_f32_e32 v117, v143, v117
	v_add_f32_e32 v116, v116, v117
	v_add_f32_e32 v117, v177, v176
	v_add_f32_e32 v116, v137, v116
	v_sub_f32_e32 v136, v117, v177
	v_mul_f32_e32 v116, v145, v116
	v_sub_f32_e32 v136, v176, v136
	v_add_f32_e32 v136, v136, v116
	v_add_f32_e32 v138, v117, v136
	v_mul_f32_e32 v139, v138, v138
	v_fmamk_f32 v116, v139, 0x3e9b6dac, v233
	v_fmaak_f32 v185, v139, v116, 0x3f2aaada
	v_cvt_f32_i32_e32 v116, v142
	v_sub_f32_e32 v117, v138, v117
	v_sub_f32_e32 v117, v136, v117
	v_ldexp_f32 v140, v117, 1
	v_mul_f32_e32 v117, v138, v139
	v_ldexp_f32 v137, v138, 1
	v_pk_mul_f32 v[138:139], v[116:117], v[184:185]
	s_nop 0
	v_fma_f32 v136, v116, s51, -v138
	v_fmac_f32_e32 v136, 0xb102e308, v116
	v_pk_add_f32 v[116:117], v[138:139], v[136:137]
	s_nop 0
	v_sub_f32_e32 v137, v117, v137
	v_sub_f32_e32 v137, v139, v137
	v_add_f32_e32 v141, v140, v137
	v_mov_b32_e32 v140, v138
	v_pk_add_f32 v[138:139], v[116:117], v[138:139] neg_lo:[0,1] neg_hi:[0,1]
	v_pk_add_f32 v[142:143], v[116:117], v[140:141]
	v_mov_b32_e32 v137, v116
	v_mov_b32_e32 v139, v143
	v_pk_add_f32 v[144:145], v[136:137], v[138:139] neg_lo:[0,1] neg_hi:[0,1]
	v_pk_add_f32 v[136:137], v[136:137], v[138:139]
	v_mov_b32_e32 v140, v141
	v_pk_add_f32 v[138:139], v[136:137], v[116:117] op_sel:[1,0] op_sel_hi:[0,1] neg_lo:[0,1] neg_hi:[0,1]
	v_pk_add_f32 v[176:177], v[142:143], v[138:139] op_sel_hi:[1,0] neg_lo:[0,1] neg_hi:[0,1]
	v_mov_b32_e32 v142, v143
	v_mov_b32_e32 v143, v137
	v_pk_mov_b32 v[138:139], v[116:117], v[138:139] op_sel:[1,0]
	v_mov_b32_e32 v141, v116
	v_pk_add_f32 v[138:139], v[142:143], v[138:139] neg_lo:[0,1] neg_hi:[0,1]
	v_mov_b32_e32 v176, v144
	v_pk_add_f32 v[116:117], v[140:141], v[138:139] neg_lo:[0,1] neg_hi:[0,1]
	v_mov_b32_e32 v145, v137
	v_pk_add_f32 v[138:139], v[176:177], v[116:117]
	s_nop 0
	v_pk_add_f32 v[140:141], v[138:139], v[138:139] op_sel:[0,1] op_sel_hi:[1,0]
	s_nop 0
	v_pk_add_f32 v[136:137], v[136:137], v[140:141] op_sel:[1,0] op_sel_hi:[0,1]
	v_mov_b32_e32 v139, v136
	v_pk_add_f32 v[142:143], v[138:139], v[144:145] neg_lo:[0,1] neg_hi:[0,1]
	v_mov_b32_e32 v117, v140
	v_sub_f32_e32 v137, v138, v142
	v_pk_add_f32 v[116:117], v[116:117], v[142:143] neg_lo:[0,1] neg_hi:[0,1]
	v_sub_f32_e32 v137, v144, v137
	v_add_f32_e32 v116, v116, v137
	v_add_f32_e32 v116, v116, v117
	v_add_f32_e32 v116, v136, v116
	v_cndmask_b32_e32 v116, v226, v116, vcc
	v_cmp_ngt_f32_e32 vcc, -1.0, v115
	s_nop 1
	v_cndmask_b32_e32 v116, v227, v116, vcc
	v_cmp_neq_f32_e32 vcc, -1.0, v115
	s_nop 1
	v_cndmask_b32_e32 v116, v236, v116, vcc
	v_cmp_lt_f32_e64 vcc, |v115|, s48
	s_nop 1
	v_cndmask_b32_e32 v115, v116, v115, vcc
	v_sub_f32_e32 v114, v114, v115

.LBB0_972:
	s_andn2_saveexec_b64 s[44:45], s[44:45]
	s_cbranch_execz .LBB0_974
	s_mov_b32 s27, 0x33800000
	s_waitcnt vmcnt(0)
	v_mov_b32_e32 v98, v248
	v_add_f32_e32 v99, v110, v98
	v_min_f32_e32 v98, 0, v99
	v_mul_f32_e64 v99, |v99|, s29
	v_exp_f32_e32 v99, v99
	s_nop 0
	v_add_f32_e32 v136, 1.0, v99
	v_add_f32_e32 v100, -1.0, v136
	v_sub_f32_e32 v101, v100, v136
	v_add_f32_e32 v101, 1.0, v101
	v_sub_f32_e32 v100, v99, v100
	v_add_f32_e32 v137, v100, v101
	v_frexp_mant_f32_e32 v100, v136
	v_cmp_gt_f32_e32 vcc, s50, v100
	v_cvt_f64_f32_e32 v[100:101], v136
	v_frexp_exp_i32_f64_e32 v100, v[100:101]
	v_subbrev_co_u32_e32 v142, vcc, 0, v100, vcc
	v_sub_u32_e32 v100, 0, v142
	v_ldexp_f32 v101, v136, v100
	v_add_f32_e32 v136, -1.0, v101
	v_add_f32_e32 v138, 1.0, v101
	v_ldexp_f32 v100, v137, v100
	v_add_f32_e32 v137, 1.0, v136
	v_add_f32_e32 v139, -1.0, v138
	v_sub_f32_e32 v137, v101, v137
	v_sub_f32_e32 v101, v101, v139
	v_add_f32_e32 v137, v100, v137
	v_add_f32_e32 v100, v100, v101
	v_add_f32_e32 v143, v138, v100
	v_rcp_f32_e32 v145, v143
	v_sub_f32_e32 v101, v143, v138
	v_sub_f32_e32 v144, v100, v101
	v_add_f32_e32 v101, v136, v137
	v_mul_f32_e32 v147, v101, v145
	v_sub_f32_e32 v100, v101, v136
	v_mul_f32_e32 v136, v143, v147
	v_fma_f32 v138, v147, v143, -v136
	v_fmac_f32_e32 v138, v147, v144
	v_sub_f32_e32 v146, v137, v100
	v_add_f32_e32 v100, v136, v138
	v_sub_f32_e32 v137, v101, v100
	v_pk_add_f32 v[140:141], v[100:101], v[136:137] neg_lo:[0,1] neg_hi:[0,1]
	v_mov_b32_e32 v139, v100
	v_pk_add_f32 v[100:101], v[140:141], v[138:139] neg_lo:[0,1] neg_hi:[0,1]
	v_cmp_neq_f32_e32 vcc, s52, v99
	v_add_f32_e32 v101, v146, v101
	v_add_f32_e32 v100, v100, v101
	v_add_f32_e32 v101, v137, v100
	v_mul_f32_e32 v146, v145, v101
	v_mul_f32_e32 v136, v143, v146
	v_fma_f32 v138, v146, v143, -v136
	v_fmac_f32_e32 v138, v146, v144
	v_sub_f32_e32 v137, v137, v101
	v_add_f32_e32 v143, v100, v137
	v_add_f32_e32 v100, v136, v138
	v_sub_f32_e32 v137, v101, v100
	v_pk_add_f32 v[140:141], v[100:101], v[136:137] neg_lo:[0,1] neg_hi:[0,1]
	v_mov_b32_e32 v139, v100
	v_pk_add_f32 v[100:101], v[140:141], v[138:139] neg_lo:[0,1] neg_hi:[0,1]
	s_nop 0
	v_add_f32_e32 v101, v143, v101
	v_add_f32_e32 v100, v100, v101
	v_add_f32_e32 v101, v147, v146
	v_add_f32_e32 v100, v137, v100
	v_sub_f32_e32 v136, v101, v147
	v_mul_f32_e32 v100, v145, v100
	v_sub_f32_e32 v136, v146, v136
	v_add_f32_e32 v136, v136, v100
	v_add_f32_e32 v138, v101, v136
	v_mul_f32_e32 v139, v138, v138
	v_fmamk_f32 v100, v139, 0x3e9b6dac, v233
	v_fmaak_f32 v185, v139, v100, 0x3f2aaada
	v_cvt_f32_i32_e32 v100, v142
	v_sub_f32_e32 v101, v138, v101
	v_sub_f32_e32 v101, v136, v101
	v_ldexp_f32 v140, v101, 1
	v_mul_f32_e32 v101, v138, v139
	v_ldexp_f32 v137, v138, 1
	v_pk_mul_f32 v[138:139], v[100:101], v[184:185]
	s_nop 0
	v_fma_f32 v136, v100, s51, -v138
	v_fmac_f32_e32 v136, 0xb102e308, v100
	v_pk_add_f32 v[100:101], v[138:139], v[136:137]
	s_nop 0
	v_sub_f32_e32 v137, v101, v137
	v_sub_f32_e32 v137, v139, v137
	v_add_f32_e32 v141, v140, v137
	v_mov_b32_e32 v140, v138
	v_pk_add_f32 v[138:139], v[100:101], v[138:139] neg_lo:[0,1] neg_hi:[0,1]
	v_pk_add_f32 v[142:143], v[100:101], v[140:141]
	v_mov_b32_e32 v137, v100
	v_mov_b32_e32 v139, v143
	v_pk_add_f32 v[144:145], v[136:137], v[138:139] neg_lo:[0,1] neg_hi:[0,1]
	v_pk_add_f32 v[136:137], v[136:137], v[138:139]
	v_mov_b32_e32 v140, v141
	v_pk_add_f32 v[138:139], v[136:137], v[100:101] op_sel:[1,0] op_sel_hi:[0,1] neg_lo:[0,1] neg_hi:[0,1]
	v_pk_add_f32 v[146:147], v[142:143], v[138:139] op_sel_hi:[1,0] neg_lo:[0,1] neg_hi:[0,1]
	v_mov_b32_e32 v142, v143
	v_mov_b32_e32 v143, v137
	v_pk_mov_b32 v[138:139], v[100:101], v[138:139] op_sel:[1,0]
	v_mov_b32_e32 v141, v100
	v_pk_add_f32 v[138:139], v[142:143], v[138:139] neg_lo:[0,1] neg_hi:[0,1]
	v_mov_b32_e32 v146, v144
	v_pk_add_f32 v[100:101], v[140:141], v[138:139] neg_lo:[0,1] neg_hi:[0,1]
	v_mov_b32_e32 v145, v137
	v_pk_add_f32 v[138:139], v[146:147], v[100:101]
	s_nop 0
	v_pk_add_f32 v[140:141], v[138:139], v[138:139] op_sel:[0,1] op_sel_hi:[1,0]
	s_nop 0
	v_pk_add_f32 v[136:137], v[136:137], v[140:141] op_sel:[1,0] op_sel_hi:[0,1]
	v_mov_b32_e32 v139, v136
	v_pk_add_f32 v[142:143], v[138:139], v[144:145] neg_lo:[0,1] neg_hi:[0,1]
	v_mov_b32_e32 v101, v140
	v_sub_f32_e32 v137, v138, v142
	v_pk_add_f32 v[100:101], v[100:101], v[142:143] neg_lo:[0,1] neg_hi:[0,1]
	v_sub_f32_e32 v137, v144, v137
	v_add_f32_e32 v100, v100, v137
	v_add_f32_e32 v100, v100, v101
	v_add_f32_e32 v100, v136, v100
	v_cndmask_b32_e32 v100, v226, v100, vcc
	v_cmp_ngt_f32_e32 vcc, -1.0, v99
	s_nop 1
	v_cndmask_b32_e32 v100, v227, v100, vcc
	v_cmp_neq_f32_e32 vcc, -1.0, v99
	s_nop 1
	v_cndmask_b32_e32 v100, v236, v100, vcc
	v_cmp_lt_f32_e64 vcc, |v99|, s27
	s_nop 1
	v_cndmask_b32_e32 v99, v100, v99, vcc
	v_sub_f32_e32 v98, v98, v99

.LBB0_976:
	s_andn2_saveexec_b64 s[44:45], s[44:45]
	s_cbranch_execz .LBB0_978
	s_mov_b32 s27, 0x33800000
	s_waitcnt vmcnt(0)
	v_mov_b32_e32 v98, v249
	v_add_f32_e32 v99, v111, v98
	v_min_f32_e32 v98, 0, v99
	v_mul_f32_e64 v99, |v99|, s29
	v_exp_f32_e32 v99, v99
	s_nop 0
	v_add_f32_e32 v138, 1.0, v99
	v_add_f32_e32 v100, -1.0, v138
	v_sub_f32_e32 v101, v100, v138
	v_add_f32_e32 v101, 1.0, v101
	v_sub_f32_e32 v100, v99, v100
	v_add_f32_e32 v139, v100, v101
	v_frexp_mant_f32_e32 v100, v138
	v_cmp_gt_f32_e32 vcc, s50, v100
	v_cvt_f64_f32_e32 v[100:101], v138
	v_frexp_exp_i32_f64_e32 v100, v[100:101]
	v_subbrev_co_u32_e32 v144, vcc, 0, v100, vcc
	v_sub_u32_e32 v100, 0, v144
	v_ldexp_f32 v101, v138, v100
	v_add_f32_e32 v138, -1.0, v101
	v_add_f32_e32 v140, 1.0, v101
	v_ldexp_f32 v100, v139, v100
	v_add_f32_e32 v139, 1.0, v138
	v_add_f32_e32 v141, -1.0, v140
	v_sub_f32_e32 v139, v101, v139
	v_sub_f32_e32 v101, v101, v141
	v_add_f32_e32 v139, v100, v139
	v_add_f32_e32 v100, v100, v101
	v_add_f32_e32 v145, v140, v100
	v_rcp_f32_e32 v147, v145
	v_sub_f32_e32 v101, v145, v140
	v_sub_f32_e32 v146, v100, v101
	v_add_f32_e32 v101, v138, v139
	v_mul_f32_e32 v149, v101, v147
	v_sub_f32_e32 v100, v101, v138
	v_mul_f32_e32 v138, v145, v149
	v_fma_f32 v140, v149, v145, -v138
	v_fmac_f32_e32 v140, v149, v146
	v_sub_f32_e32 v148, v139, v100
	v_add_f32_e32 v100, v138, v140
	v_sub_f32_e32 v139, v101, v100
	v_pk_add_f32 v[142:143], v[100:101], v[138:139] neg_lo:[0,1] neg_hi:[0,1]
	v_mov_b32_e32 v141, v100
	v_pk_add_f32 v[100:101], v[142:143], v[140:141] neg_lo:[0,1] neg_hi:[0,1]
	v_cmp_neq_f32_e32 vcc, s52, v99
	v_add_f32_e32 v101, v148, v101
	v_add_f32_e32 v100, v100, v101
	v_add_f32_e32 v101, v139, v100
	v_mul_f32_e32 v148, v147, v101
	v_mul_f32_e32 v138, v145, v148
	v_fma_f32 v140, v148, v145, -v138
	v_fmac_f32_e32 v140, v148, v146
	v_sub_f32_e32 v139, v139, v101
	v_add_f32_e32 v145, v100, v139
	v_add_f32_e32 v100, v138, v140
	v_sub_f32_e32 v139, v101, v100
	v_pk_add_f32 v[142:143], v[100:101], v[138:139] neg_lo:[0,1] neg_hi:[0,1]
	v_mov_b32_e32 v141, v100
	v_pk_add_f32 v[100:101], v[142:143], v[140:141] neg_lo:[0,1] neg_hi:[0,1]
	s_nop 0
	v_add_f32_e32 v101, v145, v101
	v_add_f32_e32 v100, v100, v101
	v_add_f32_e32 v101, v149, v148
	v_add_f32_e32 v100, v139, v100
	v_sub_f32_e32 v138, v101, v149
	v_mul_f32_e32 v100, v147, v100
	v_sub_f32_e32 v138, v148, v138
	v_add_f32_e32 v138, v138, v100
	v_add_f32_e32 v140, v101, v138
	v_mul_f32_e32 v141, v140, v140
	v_fmamk_f32 v100, v141, 0x3e9b6dac, v233
	v_fmaak_f32 v185, v141, v100, 0x3f2aaada
	v_cvt_f32_i32_e32 v100, v144
	v_sub_f32_e32 v101, v140, v101
	v_sub_f32_e32 v101, v138, v101
	v_ldexp_f32 v142, v101, 1
	v_mul_f32_e32 v101, v140, v141
	v_ldexp_f32 v139, v140, 1
	v_pk_mul_f32 v[140:141], v[100:101], v[184:185]
	s_nop 0
	v_fma_f32 v138, v100, s51, -v140
	v_fmac_f32_e32 v138, 0xb102e308, v100
	v_pk_add_f32 v[100:101], v[140:141], v[138:139]
	s_nop 0
	v_sub_f32_e32 v139, v101, v139
	v_sub_f32_e32 v139, v141, v139
	v_add_f32_e32 v143, v142, v139
	v_mov_b32_e32 v142, v140
	v_pk_add_f32 v[140:141], v[100:101], v[140:141] neg_lo:[0,1] neg_hi:[0,1]
	v_pk_add_f32 v[144:145], v[100:101], v[142:143]
	v_mov_b32_e32 v139, v100
	v_mov_b32_e32 v141, v145
	v_pk_add_f32 v[146:147], v[138:139], v[140:141] neg_lo:[0,1] neg_hi:[0,1]
	v_pk_add_f32 v[138:139], v[138:139], v[140:141]
	v_mov_b32_e32 v142, v143
	v_pk_add_f32 v[140:141], v[138:139], v[100:101] op_sel:[1,0] op_sel_hi:[0,1] neg_lo:[0,1] neg_hi:[0,1]
	v_pk_add_f32 v[148:149], v[144:145], v[140:141] op_sel_hi:[1,0] neg_lo:[0,1] neg_hi:[0,1]
	v_mov_b32_e32 v144, v145
	v_mov_b32_e32 v145, v139
	v_pk_mov_b32 v[140:141], v[100:101], v[140:141] op_sel:[1,0]
	v_mov_b32_e32 v143, v100
	v_pk_add_f32 v[140:141], v[144:145], v[140:141] neg_lo:[0,1] neg_hi:[0,1]
	v_mov_b32_e32 v148, v146
	v_pk_add_f32 v[100:101], v[142:143], v[140:141] neg_lo:[0,1] neg_hi:[0,1]
	v_mov_b32_e32 v147, v139
	v_pk_add_f32 v[140:141], v[148:149], v[100:101]
	s_nop 0
	v_pk_add_f32 v[142:143], v[140:141], v[140:141] op_sel:[0,1] op_sel_hi:[1,0]
	s_nop 0
	v_pk_add_f32 v[138:139], v[138:139], v[142:143] op_sel:[1,0] op_sel_hi:[0,1]
	v_mov_b32_e32 v141, v138
	v_pk_add_f32 v[144:145], v[140:141], v[146:147] neg_lo:[0,1] neg_hi:[0,1]
	v_mov_b32_e32 v101, v142
	v_sub_f32_e32 v139, v140, v144
	v_pk_add_f32 v[100:101], v[100:101], v[144:145] neg_lo:[0,1] neg_hi:[0,1]
	v_sub_f32_e32 v139, v146, v139
	v_add_f32_e32 v100, v100, v139
	v_add_f32_e32 v100, v100, v101
	v_add_f32_e32 v100, v138, v100
	v_cndmask_b32_e32 v100, v226, v100, vcc
	v_cmp_ngt_f32_e32 vcc, -1.0, v99
	s_nop 1
	v_cndmask_b32_e32 v100, v227, v100, vcc
	v_cmp_neq_f32_e32 vcc, -1.0, v99
	s_nop 1
	v_cndmask_b32_e32 v100, v236, v100, vcc
	v_cmp_lt_f32_e64 vcc, |v99|, s27
	s_nop 1
	v_cndmask_b32_e32 v99, v100, v99, vcc
	v_sub_f32_e32 v98, v98, v99

.LBB0_980:
	s_andn2_saveexec_b64 s[44:45], s[44:45]
	s_cbranch_execz .LBB0_982
	s_mov_b32 s27, 0x33800000
	s_waitcnt vmcnt(0)
	v_mov_b32_e32 v98, v250
	v_add_f32_e32 v99, v116, v98
	v_min_f32_e32 v98, 0, v99
	v_mul_f32_e64 v99, |v99|, s29
	v_exp_f32_e32 v99, v99
	s_nop 0
	v_add_f32_e32 v138, 1.0, v99
	v_add_f32_e32 v100, -1.0, v138
	v_sub_f32_e32 v101, v100, v138
	v_add_f32_e32 v101, 1.0, v101
	v_sub_f32_e32 v100, v99, v100
	v_add_f32_e32 v139, v100, v101
	v_frexp_mant_f32_e32 v100, v138
	v_cmp_gt_f32_e32 vcc, s50, v100
	v_cvt_f64_f32_e32 v[100:101], v138
	v_frexp_exp_i32_f64_e32 v100, v[100:101]
	v_subbrev_co_u32_e32 v144, vcc, 0, v100, vcc
	v_sub_u32_e32 v100, 0, v144
	v_ldexp_f32 v101, v138, v100
	v_add_f32_e32 v138, -1.0, v101
	v_add_f32_e32 v140, 1.0, v101
	v_ldexp_f32 v100, v139, v100
	v_add_f32_e32 v139, 1.0, v138
	v_add_f32_e32 v141, -1.0, v140
	v_sub_f32_e32 v139, v101, v139
	v_sub_f32_e32 v101, v101, v141
	v_add_f32_e32 v139, v100, v139
	v_add_f32_e32 v100, v100, v101
	v_add_f32_e32 v145, v140, v100
	v_rcp_f32_e32 v147, v145
	v_sub_f32_e32 v101, v145, v140
	v_sub_f32_e32 v146, v100, v101
	v_add_f32_e32 v101, v138, v139
	v_mul_f32_e32 v149, v101, v147
	v_sub_f32_e32 v100, v101, v138
	v_mul_f32_e32 v138, v145, v149
	v_fma_f32 v140, v149, v145, -v138
	v_fmac_f32_e32 v140, v149, v146
	v_sub_f32_e32 v148, v139, v100
	v_add_f32_e32 v100, v138, v140
	v_sub_f32_e32 v139, v101, v100
	v_pk_add_f32 v[142:143], v[100:101], v[138:139] neg_lo:[0,1] neg_hi:[0,1]
	v_mov_b32_e32 v141, v100
	v_pk_add_f32 v[100:101], v[142:143], v[140:141] neg_lo:[0,1] neg_hi:[0,1]
	v_cmp_neq_f32_e32 vcc, s52, v99
	v_add_f32_e32 v101, v148, v101
	v_add_f32_e32 v100, v100, v101
	v_add_f32_e32 v101, v139, v100
	v_mul_f32_e32 v148, v147, v101
	v_mul_f32_e32 v138, v145, v148
	v_fma_f32 v140, v148, v145, -v138
	v_fmac_f32_e32 v140, v148, v146
	v_sub_f32_e32 v139, v139, v101
	v_add_f32_e32 v145, v100, v139
	v_add_f32_e32 v100, v138, v140
	v_sub_f32_e32 v139, v101, v100
	v_pk_add_f32 v[142:143], v[100:101], v[138:139] neg_lo:[0,1] neg_hi:[0,1]
	v_mov_b32_e32 v141, v100
	v_pk_add_f32 v[100:101], v[142:143], v[140:141] neg_lo:[0,1] neg_hi:[0,1]
	s_nop 0
	v_add_f32_e32 v101, v145, v101
	v_add_f32_e32 v100, v100, v101
	v_add_f32_e32 v101, v149, v148
	v_add_f32_e32 v100, v139, v100
	v_sub_f32_e32 v138, v101, v149
	v_mul_f32_e32 v100, v147, v100
	v_sub_f32_e32 v138, v148, v138
	v_add_f32_e32 v138, v138, v100
	v_add_f32_e32 v140, v101, v138
	v_mul_f32_e32 v141, v140, v140
	v_fmamk_f32 v100, v141, 0x3e9b6dac, v233
	v_fmaak_f32 v185, v141, v100, 0x3f2aaada
	v_cvt_f32_i32_e32 v100, v144
	v_sub_f32_e32 v101, v140, v101
	v_sub_f32_e32 v101, v138, v101
	v_ldexp_f32 v142, v101, 1
	v_mul_f32_e32 v101, v140, v141
	v_ldexp_f32 v139, v140, 1
	v_pk_mul_f32 v[140:141], v[100:101], v[184:185]
	s_nop 0
	v_fma_f32 v138, v100, s51, -v140
	v_fmac_f32_e32 v138, 0xb102e308, v100
	v_pk_add_f32 v[100:101], v[140:141], v[138:139]
	s_nop 0
	v_sub_f32_e32 v139, v101, v139
	v_sub_f32_e32 v139, v141, v139
	v_add_f32_e32 v143, v142, v139
	v_mov_b32_e32 v142, v140
	v_pk_add_f32 v[140:141], v[100:101], v[140:141] neg_lo:[0,1] neg_hi:[0,1]
	v_pk_add_f32 v[144:145], v[100:101], v[142:143]
	v_mov_b32_e32 v139, v100
	v_mov_b32_e32 v141, v145
	v_pk_add_f32 v[146:147], v[138:139], v[140:141] neg_lo:[0,1] neg_hi:[0,1]
	v_pk_add_f32 v[138:139], v[138:139], v[140:141]
	v_mov_b32_e32 v142, v143
	v_pk_add_f32 v[140:141], v[138:139], v[100:101] op_sel:[1,0] op_sel_hi:[0,1] neg_lo:[0,1] neg_hi:[0,1]
	v_pk_add_f32 v[148:149], v[144:145], v[140:141] op_sel_hi:[1,0] neg_lo:[0,1] neg_hi:[0,1]
	v_mov_b32_e32 v144, v145
	v_mov_b32_e32 v145, v139
	v_pk_mov_b32 v[140:141], v[100:101], v[140:141] op_sel:[1,0]
	v_mov_b32_e32 v143, v100
	v_pk_add_f32 v[140:141], v[144:145], v[140:141] neg_lo:[0,1] neg_hi:[0,1]
	v_mov_b32_e32 v148, v146
	v_pk_add_f32 v[100:101], v[142:143], v[140:141] neg_lo:[0,1] neg_hi:[0,1]
	v_mov_b32_e32 v147, v139
	v_pk_add_f32 v[140:141], v[148:149], v[100:101]
	s_nop 0
	v_pk_add_f32 v[142:143], v[140:141], v[140:141] op_sel:[0,1] op_sel_hi:[1,0]
	s_nop 0
	v_pk_add_f32 v[138:139], v[138:139], v[142:143] op_sel:[1,0] op_sel_hi:[0,1]
	v_mov_b32_e32 v141, v138
	v_pk_add_f32 v[144:145], v[140:141], v[146:147] neg_lo:[0,1] neg_hi:[0,1]
	v_mov_b32_e32 v101, v142
	v_sub_f32_e32 v139, v140, v144
	v_pk_add_f32 v[100:101], v[100:101], v[144:145] neg_lo:[0,1] neg_hi:[0,1]
	v_sub_f32_e32 v139, v146, v139
	v_add_f32_e32 v100, v100, v139
	v_add_f32_e32 v100, v100, v101
	v_add_f32_e32 v100, v138, v100
	v_cndmask_b32_e32 v100, v226, v100, vcc
	v_cmp_ngt_f32_e32 vcc, -1.0, v99
	s_nop 1
	v_cndmask_b32_e32 v100, v227, v100, vcc
	v_cmp_neq_f32_e32 vcc, -1.0, v99
	s_nop 1
	v_cndmask_b32_e32 v100, v236, v100, vcc
	v_cmp_lt_f32_e64 vcc, |v99|, s27
	s_nop 1
	v_cndmask_b32_e32 v99, v100, v99, vcc
	v_sub_f32_e32 v98, v98, v99

.LBB0_984:
	s_andn2_saveexec_b64 s[44:45], s[44:45]
	s_cbranch_execz .LBB0_986
	s_mov_b32 s27, 0x33800000
	s_waitcnt vmcnt(0)
	v_mov_b32_e32 v98, v251
	v_add_f32_e32 v99, v117, v98
	v_min_f32_e32 v98, 0, v99
	v_mul_f32_e64 v99, |v99|, s29
	v_exp_f32_e32 v99, v99
	s_nop 0
	v_add_f32_e32 v138, 1.0, v99
	v_add_f32_e32 v100, -1.0, v138
	v_sub_f32_e32 v101, v100, v138
	v_add_f32_e32 v101, 1.0, v101
	v_sub_f32_e32 v100, v99, v100
	v_add_f32_e32 v139, v100, v101
	v_frexp_mant_f32_e32 v100, v138
	v_cmp_gt_f32_e32 vcc, s50, v100
	v_cvt_f64_f32_e32 v[100:101], v138
	v_frexp_exp_i32_f64_e32 v100, v[100:101]
	v_subbrev_co_u32_e32 v144, vcc, 0, v100, vcc
	v_sub_u32_e32 v100, 0, v144
	v_ldexp_f32 v101, v138, v100
	v_add_f32_e32 v138, -1.0, v101
	v_add_f32_e32 v140, 1.0, v101
	v_ldexp_f32 v100, v139, v100
	v_add_f32_e32 v139, 1.0, v138
	v_add_f32_e32 v141, -1.0, v140
	v_sub_f32_e32 v139, v101, v139
	v_sub_f32_e32 v101, v101, v141
	v_add_f32_e32 v139, v100, v139
	v_add_f32_e32 v100, v100, v101
	v_add_f32_e32 v145, v140, v100
	v_rcp_f32_e32 v147, v145
	v_sub_f32_e32 v101, v145, v140
	v_sub_f32_e32 v146, v100, v101
	v_add_f32_e32 v101, v138, v139
	v_mul_f32_e32 v149, v101, v147
	v_sub_f32_e32 v100, v101, v138
	v_mul_f32_e32 v138, v145, v149
	v_fma_f32 v140, v149, v145, -v138
	v_fmac_f32_e32 v140, v149, v146
	v_sub_f32_e32 v148, v139, v100
	v_add_f32_e32 v100, v138, v140
	v_sub_f32_e32 v139, v101, v100
	v_pk_add_f32 v[142:143], v[100:101], v[138:139] neg_lo:[0,1] neg_hi:[0,1]
	v_mov_b32_e32 v141, v100
	v_pk_add_f32 v[100:101], v[142:143], v[140:141] neg_lo:[0,1] neg_hi:[0,1]
	v_cmp_neq_f32_e32 vcc, s52, v99
	v_add_f32_e32 v101, v148, v101
	v_add_f32_e32 v100, v100, v101
	v_add_f32_e32 v101, v139, v100
	v_mul_f32_e32 v148, v147, v101
	v_mul_f32_e32 v138, v145, v148
	v_fma_f32 v140, v148, v145, -v138
	v_fmac_f32_e32 v140, v148, v146
	v_sub_f32_e32 v139, v139, v101
	v_add_f32_e32 v145, v100, v139
	v_add_f32_e32 v100, v138, v140
	v_sub_f32_e32 v139, v101, v100
	v_pk_add_f32 v[142:143], v[100:101], v[138:139] neg_lo:[0,1] neg_hi:[0,1]
	v_mov_b32_e32 v141, v100
	v_pk_add_f32 v[100:101], v[142:143], v[140:141] neg_lo:[0,1] neg_hi:[0,1]
	s_nop 0
	v_add_f32_e32 v101, v145, v101
	v_add_f32_e32 v100, v100, v101
	v_add_f32_e32 v101, v149, v148
	v_add_f32_e32 v100, v139, v100
	v_sub_f32_e32 v138, v101, v149
	v_mul_f32_e32 v100, v147, v100
	v_sub_f32_e32 v138, v148, v138
	v_add_f32_e32 v138, v138, v100
	v_add_f32_e32 v140, v101, v138
	v_mul_f32_e32 v141, v140, v140
	v_fmamk_f32 v100, v141, 0x3e9b6dac, v233
	v_fmaak_f32 v185, v141, v100, 0x3f2aaada
	v_cvt_f32_i32_e32 v100, v144
	v_sub_f32_e32 v101, v140, v101
	v_sub_f32_e32 v101, v138, v101
	v_ldexp_f32 v142, v101, 1
	v_mul_f32_e32 v101, v140, v141
	v_ldexp_f32 v139, v140, 1
	v_pk_mul_f32 v[140:141], v[100:101], v[184:185]
	s_nop 0
	v_fma_f32 v138, v100, s51, -v140
	v_fmac_f32_e32 v138, 0xb102e308, v100
	v_pk_add_f32 v[100:101], v[140:141], v[138:139]
	s_nop 0
	v_sub_f32_e32 v139, v101, v139
	v_sub_f32_e32 v139, v141, v139
	v_add_f32_e32 v143, v142, v139
	v_mov_b32_e32 v142, v140
	v_pk_add_f32 v[140:141], v[100:101], v[140:141] neg_lo:[0,1] neg_hi:[0,1]
	v_pk_add_f32 v[144:145], v[100:101], v[142:143]
	v_mov_b32_e32 v139, v100
	v_mov_b32_e32 v141, v145
	v_pk_add_f32 v[146:147], v[138:139], v[140:141] neg_lo:[0,1] neg_hi:[0,1]
	v_pk_add_f32 v[138:139], v[138:139], v[140:141]
	v_mov_b32_e32 v142, v143
	v_pk_add_f32 v[140:141], v[138:139], v[100:101] op_sel:[1,0] op_sel_hi:[0,1] neg_lo:[0,1] neg_hi:[0,1]
	v_pk_add_f32 v[148:149], v[144:145], v[140:141] op_sel_hi:[1,0] neg_lo:[0,1] neg_hi:[0,1]
	v_mov_b32_e32 v144, v145
	v_mov_b32_e32 v145, v139
	v_pk_mov_b32 v[140:141], v[100:101], v[140:141] op_sel:[1,0]
	v_mov_b32_e32 v143, v100
	v_pk_add_f32 v[140:141], v[144:145], v[140:141] neg_lo:[0,1] neg_hi:[0,1]
	v_mov_b32_e32 v148, v146
	v_pk_add_f32 v[100:101], v[142:143], v[140:141] neg_lo:[0,1] neg_hi:[0,1]
	v_mov_b32_e32 v147, v139
	v_pk_add_f32 v[140:141], v[148:149], v[100:101]
	s_nop 0
	v_pk_add_f32 v[142:143], v[140:141], v[140:141] op_sel:[0,1] op_sel_hi:[1,0]
	s_nop 0
	v_pk_add_f32 v[138:139], v[138:139], v[142:143] op_sel:[1,0] op_sel_hi:[0,1]
	v_mov_b32_e32 v141, v138
	v_pk_add_f32 v[144:145], v[140:141], v[146:147] neg_lo:[0,1] neg_hi:[0,1]
	v_mov_b32_e32 v101, v142
	v_sub_f32_e32 v139, v140, v144
	v_pk_add_f32 v[100:101], v[100:101], v[144:145] neg_lo:[0,1] neg_hi:[0,1]
	v_sub_f32_e32 v139, v146, v139
	v_add_f32_e32 v100, v100, v139
	v_add_f32_e32 v100, v100, v101
	v_add_f32_e32 v100, v138, v100
	v_cndmask_b32_e32 v100, v226, v100, vcc
	v_cmp_ngt_f32_e32 vcc, -1.0, v99
	s_nop 1
	v_cndmask_b32_e32 v100, v227, v100, vcc
	v_cmp_neq_f32_e32 vcc, -1.0, v99
	s_nop 1
	v_cndmask_b32_e32 v100, v236, v100, vcc
	v_cmp_lt_f32_e64 vcc, |v99|, s27
	s_nop 1
	v_cndmask_b32_e32 v99, v100, v99, vcc
	v_sub_f32_e32 v98, v98, v99

.LBB0_998:
	s_andn2_saveexec_b64 s[44:45], s[44:45]
	s_cbranch_execz .LBB0_1000
	s_mov_b32 s27, 0x33800000
	s_waitcnt vmcnt(0)
	v_mov_b32_e32 v82, v248
	v_add_f32_e32 v83, v94, v82
	v_min_f32_e32 v82, 0, v83
	v_mul_f32_e64 v83, |v83|, s29
	v_exp_f32_e32 v83, v83
	s_nop 0
	v_add_f32_e32 v104, 1.0, v83
	v_add_f32_e32 v84, -1.0, v104
	v_sub_f32_e32 v85, v84, v104
	v_add_f32_e32 v85, 1.0, v85
	v_sub_f32_e32 v84, v83, v84
	v_add_f32_e32 v105, v84, v85
	v_frexp_mant_f32_e32 v84, v104
	v_cmp_gt_f32_e32 vcc, s50, v84
	v_cvt_f64_f32_e32 v[84:85], v104
	v_frexp_exp_i32_f64_e32 v84, v[84:85]
	v_subbrev_co_u32_e32 v110, vcc, 0, v84, vcc
	v_sub_u32_e32 v84, 0, v110
	v_ldexp_f32 v85, v104, v84
	v_add_f32_e32 v104, -1.0, v85
	v_add_f32_e32 v106, 1.0, v85
	v_ldexp_f32 v84, v105, v84
	v_add_f32_e32 v105, 1.0, v104
	v_add_f32_e32 v107, -1.0, v106
	v_sub_f32_e32 v105, v85, v105
	v_sub_f32_e32 v85, v85, v107
	v_add_f32_e32 v105, v84, v105
	v_add_f32_e32 v84, v84, v85
	v_add_f32_e32 v111, v106, v84
	v_rcp_f32_e32 v113, v111
	v_sub_f32_e32 v85, v111, v106
	v_sub_f32_e32 v112, v84, v85
	v_add_f32_e32 v85, v104, v105
	v_mul_f32_e32 v115, v85, v113
	v_sub_f32_e32 v84, v85, v104
	v_mul_f32_e32 v104, v111, v115
	v_fma_f32 v106, v115, v111, -v104
	v_fmac_f32_e32 v106, v115, v112
	v_sub_f32_e32 v114, v105, v84
	v_add_f32_e32 v84, v104, v106
	v_sub_f32_e32 v105, v85, v84
	v_pk_add_f32 v[108:109], v[84:85], v[104:105] neg_lo:[0,1] neg_hi:[0,1]
	v_mov_b32_e32 v107, v84
	v_pk_add_f32 v[84:85], v[108:109], v[106:107] neg_lo:[0,1] neg_hi:[0,1]
	v_cmp_neq_f32_e32 vcc, s52, v83
	v_add_f32_e32 v85, v114, v85
	v_add_f32_e32 v84, v84, v85
	v_add_f32_e32 v85, v105, v84
	v_mul_f32_e32 v114, v113, v85
	v_mul_f32_e32 v104, v111, v114
	v_fma_f32 v106, v114, v111, -v104
	v_fmac_f32_e32 v106, v114, v112
	v_sub_f32_e32 v105, v105, v85
	v_add_f32_e32 v111, v84, v105
	v_add_f32_e32 v84, v104, v106
	v_sub_f32_e32 v105, v85, v84
	v_pk_add_f32 v[108:109], v[84:85], v[104:105] neg_lo:[0,1] neg_hi:[0,1]
	v_mov_b32_e32 v107, v84
	v_pk_add_f32 v[84:85], v[108:109], v[106:107] neg_lo:[0,1] neg_hi:[0,1]
	s_nop 0
	v_add_f32_e32 v85, v111, v85
	v_add_f32_e32 v84, v84, v85
	v_add_f32_e32 v85, v115, v114
	v_add_f32_e32 v84, v105, v84
	v_sub_f32_e32 v104, v85, v115
	v_mul_f32_e32 v84, v113, v84
	v_sub_f32_e32 v104, v114, v104
	v_add_f32_e32 v104, v104, v84
	v_add_f32_e32 v106, v85, v104
	v_mul_f32_e32 v107, v106, v106
	v_fmamk_f32 v84, v107, 0x3e9b6dac, v233
	v_fmaak_f32 v185, v107, v84, 0x3f2aaada
	v_cvt_f32_i32_e32 v84, v110
	v_sub_f32_e32 v85, v106, v85
	v_sub_f32_e32 v85, v104, v85
	v_ldexp_f32 v108, v85, 1
	v_mul_f32_e32 v85, v106, v107
	v_ldexp_f32 v105, v106, 1
	v_pk_mul_f32 v[106:107], v[84:85], v[184:185]
	s_nop 0
	v_fma_f32 v104, v84, s51, -v106
	v_fmac_f32_e32 v104, 0xb102e308, v84
	v_pk_add_f32 v[84:85], v[106:107], v[104:105]
	s_nop 0
	v_sub_f32_e32 v105, v85, v105
	v_sub_f32_e32 v105, v107, v105
	v_add_f32_e32 v109, v108, v105
	v_mov_b32_e32 v108, v106
	v_pk_add_f32 v[106:107], v[84:85], v[106:107] neg_lo:[0,1] neg_hi:[0,1]
	v_pk_add_f32 v[110:111], v[84:85], v[108:109]
	v_mov_b32_e32 v105, v84
	v_mov_b32_e32 v107, v111
	v_pk_add_f32 v[112:113], v[104:105], v[106:107] neg_lo:[0,1] neg_hi:[0,1]
	v_pk_add_f32 v[104:105], v[104:105], v[106:107]
	v_mov_b32_e32 v108, v109
	v_pk_add_f32 v[106:107], v[104:105], v[84:85] op_sel:[1,0] op_sel_hi:[0,1] neg_lo:[0,1] neg_hi:[0,1]
	v_pk_add_f32 v[114:115], v[110:111], v[106:107] op_sel_hi:[1,0] neg_lo:[0,1] neg_hi:[0,1]
	v_mov_b32_e32 v110, v111
	v_mov_b32_e32 v111, v105
	v_pk_mov_b32 v[106:107], v[84:85], v[106:107] op_sel:[1,0]
	v_mov_b32_e32 v109, v84
	v_pk_add_f32 v[106:107], v[110:111], v[106:107] neg_lo:[0,1] neg_hi:[0,1]
	v_mov_b32_e32 v114, v112
	v_pk_add_f32 v[84:85], v[108:109], v[106:107] neg_lo:[0,1] neg_hi:[0,1]
	v_mov_b32_e32 v113, v105
	v_pk_add_f32 v[106:107], v[114:115], v[84:85]
	s_nop 0
	v_pk_add_f32 v[108:109], v[106:107], v[106:107] op_sel:[0,1] op_sel_hi:[1,0]
	s_nop 0
	v_pk_add_f32 v[104:105], v[104:105], v[108:109] op_sel:[1,0] op_sel_hi:[0,1]
	v_mov_b32_e32 v107, v104
	v_pk_add_f32 v[110:111], v[106:107], v[112:113] neg_lo:[0,1] neg_hi:[0,1]
	v_mov_b32_e32 v85, v108
	v_sub_f32_e32 v105, v106, v110
	v_pk_add_f32 v[84:85], v[84:85], v[110:111] neg_lo:[0,1] neg_hi:[0,1]
	v_sub_f32_e32 v105, v112, v105
	v_add_f32_e32 v84, v84, v105
	v_add_f32_e32 v84, v84, v85
	v_add_f32_e32 v84, v104, v84
	v_cndmask_b32_e32 v84, v226, v84, vcc
	v_cmp_ngt_f32_e32 vcc, -1.0, v83
	s_nop 1
	v_cndmask_b32_e32 v84, v227, v84, vcc
	v_cmp_neq_f32_e32 vcc, -1.0, v83
	s_nop 1
	v_cndmask_b32_e32 v84, v236, v84, vcc
	v_cmp_lt_f32_e64 vcc, |v83|, s27
	s_nop 1
	v_cndmask_b32_e32 v83, v84, v83, vcc
	v_sub_f32_e32 v82, v82, v83

.LBB0_1002:
	s_andn2_saveexec_b64 s[44:45], s[44:45]
	s_cbranch_execz .LBB0_1004
	s_mov_b32 s27, 0x33800000
	s_waitcnt vmcnt(0)
	v_mov_b32_e32 v82, v249
	v_add_f32_e32 v83, v95, v82
	v_min_f32_e32 v82, 0, v83
	v_mul_f32_e64 v83, |v83|, s29
	v_exp_f32_e32 v83, v83
	s_nop 0
	v_add_f32_e32 v106, 1.0, v83
	v_add_f32_e32 v84, -1.0, v106
	v_sub_f32_e32 v85, v84, v106
	v_add_f32_e32 v85, 1.0, v85
	v_sub_f32_e32 v84, v83, v84
	v_add_f32_e32 v107, v84, v85
	v_frexp_mant_f32_e32 v84, v106
	v_cmp_gt_f32_e32 vcc, s50, v84
	v_cvt_f64_f32_e32 v[84:85], v106
	v_frexp_exp_i32_f64_e32 v84, v[84:85]
	v_subbrev_co_u32_e32 v112, vcc, 0, v84, vcc
	v_sub_u32_e32 v84, 0, v112
	v_ldexp_f32 v85, v106, v84
	v_add_f32_e32 v106, -1.0, v85
	v_add_f32_e32 v108, 1.0, v85
	v_ldexp_f32 v84, v107, v84
	v_add_f32_e32 v107, 1.0, v106
	v_add_f32_e32 v109, -1.0, v108
	v_sub_f32_e32 v107, v85, v107
	v_sub_f32_e32 v85, v85, v109
	v_add_f32_e32 v107, v84, v107
	v_add_f32_e32 v84, v84, v85
	v_add_f32_e32 v113, v108, v84
	v_rcp_f32_e32 v115, v113
	v_sub_f32_e32 v85, v113, v108
	v_sub_f32_e32 v114, v84, v85
	v_add_f32_e32 v85, v106, v107
	v_mul_f32_e32 v117, v85, v115
	v_sub_f32_e32 v84, v85, v106
	v_mul_f32_e32 v106, v113, v117
	v_fma_f32 v108, v117, v113, -v106
	v_fmac_f32_e32 v108, v117, v114
	v_sub_f32_e32 v116, v107, v84
	v_add_f32_e32 v84, v106, v108
	v_sub_f32_e32 v107, v85, v84
	v_pk_add_f32 v[110:111], v[84:85], v[106:107] neg_lo:[0,1] neg_hi:[0,1]
	v_mov_b32_e32 v109, v84
	v_pk_add_f32 v[84:85], v[110:111], v[108:109] neg_lo:[0,1] neg_hi:[0,1]
	v_cmp_neq_f32_e32 vcc, s52, v83
	v_add_f32_e32 v85, v116, v85
	v_add_f32_e32 v84, v84, v85
	v_add_f32_e32 v85, v107, v84
	v_mul_f32_e32 v116, v115, v85
	v_mul_f32_e32 v106, v113, v116
	v_fma_f32 v108, v116, v113, -v106
	v_fmac_f32_e32 v108, v116, v114
	v_sub_f32_e32 v107, v107, v85
	v_add_f32_e32 v113, v84, v107
	v_add_f32_e32 v84, v106, v108
	v_sub_f32_e32 v107, v85, v84
	v_pk_add_f32 v[110:111], v[84:85], v[106:107] neg_lo:[0,1] neg_hi:[0,1]
	v_mov_b32_e32 v109, v84
	v_pk_add_f32 v[84:85], v[110:111], v[108:109] neg_lo:[0,1] neg_hi:[0,1]
	s_nop 0
	v_add_f32_e32 v85, v113, v85
	v_add_f32_e32 v84, v84, v85
	v_add_f32_e32 v85, v117, v116
	v_add_f32_e32 v84, v107, v84
	v_sub_f32_e32 v106, v85, v117
	v_mul_f32_e32 v84, v115, v84
	v_sub_f32_e32 v106, v116, v106
	v_add_f32_e32 v106, v106, v84
	v_add_f32_e32 v108, v85, v106
	v_mul_f32_e32 v109, v108, v108
	v_fmamk_f32 v84, v109, 0x3e9b6dac, v233
	v_fmaak_f32 v185, v109, v84, 0x3f2aaada
	v_cvt_f32_i32_e32 v84, v112
	v_sub_f32_e32 v85, v108, v85
	v_sub_f32_e32 v85, v106, v85
	v_ldexp_f32 v110, v85, 1
	v_mul_f32_e32 v85, v108, v109
	v_ldexp_f32 v107, v108, 1
	v_pk_mul_f32 v[108:109], v[84:85], v[184:185]
	s_nop 0
	v_fma_f32 v106, v84, s51, -v108
	v_fmac_f32_e32 v106, 0xb102e308, v84
	v_pk_add_f32 v[84:85], v[108:109], v[106:107]
	s_nop 0
	v_sub_f32_e32 v107, v85, v107
	v_sub_f32_e32 v107, v109, v107
	v_add_f32_e32 v111, v110, v107
	v_mov_b32_e32 v110, v108
	v_pk_add_f32 v[108:109], v[84:85], v[108:109] neg_lo:[0,1] neg_hi:[0,1]
	v_pk_add_f32 v[112:113], v[84:85], v[110:111]
	v_mov_b32_e32 v107, v84
	v_mov_b32_e32 v109, v113
	v_pk_add_f32 v[114:115], v[106:107], v[108:109] neg_lo:[0,1] neg_hi:[0,1]
	v_pk_add_f32 v[106:107], v[106:107], v[108:109]
	v_mov_b32_e32 v110, v111
	v_pk_add_f32 v[108:109], v[106:107], v[84:85] op_sel:[1,0] op_sel_hi:[0,1] neg_lo:[0,1] neg_hi:[0,1]
	v_pk_add_f32 v[116:117], v[112:113], v[108:109] op_sel_hi:[1,0] neg_lo:[0,1] neg_hi:[0,1]
	v_mov_b32_e32 v112, v113
	v_mov_b32_e32 v113, v107
	v_pk_mov_b32 v[108:109], v[84:85], v[108:109] op_sel:[1,0]
	v_mov_b32_e32 v111, v84
	v_pk_add_f32 v[108:109], v[112:113], v[108:109] neg_lo:[0,1] neg_hi:[0,1]
	v_mov_b32_e32 v116, v114
	v_pk_add_f32 v[84:85], v[110:111], v[108:109] neg_lo:[0,1] neg_hi:[0,1]
	v_mov_b32_e32 v115, v107
	v_pk_add_f32 v[108:109], v[116:117], v[84:85]
	s_nop 0
	v_pk_add_f32 v[110:111], v[108:109], v[108:109] op_sel:[0,1] op_sel_hi:[1,0]
	s_nop 0
	v_pk_add_f32 v[106:107], v[106:107], v[110:111] op_sel:[1,0] op_sel_hi:[0,1]
	v_mov_b32_e32 v109, v106
	v_pk_add_f32 v[112:113], v[108:109], v[114:115] neg_lo:[0,1] neg_hi:[0,1]
	v_mov_b32_e32 v85, v110
	v_sub_f32_e32 v107, v108, v112
	v_pk_add_f32 v[84:85], v[84:85], v[112:113] neg_lo:[0,1] neg_hi:[0,1]
	v_sub_f32_e32 v107, v114, v107
	v_add_f32_e32 v84, v84, v107
	v_add_f32_e32 v84, v84, v85
	v_add_f32_e32 v84, v106, v84
	v_cndmask_b32_e32 v84, v226, v84, vcc
	v_cmp_ngt_f32_e32 vcc, -1.0, v83
	s_nop 1
	v_cndmask_b32_e32 v84, v227, v84, vcc
	v_cmp_neq_f32_e32 vcc, -1.0, v83
	s_nop 1
	v_cndmask_b32_e32 v84, v236, v84, vcc
	v_cmp_lt_f32_e64 vcc, |v83|, s27
	s_nop 1
	v_cndmask_b32_e32 v83, v84, v83, vcc
	v_sub_f32_e32 v82, v82, v83

.LBB0_1006:
	s_andn2_saveexec_b64 s[44:45], s[44:45]
	s_cbranch_execz .LBB0_1008
	s_mov_b32 s27, 0x33800000
	s_waitcnt vmcnt(0)
	v_mov_b32_e32 v82, v250
	v_add_f32_e32 v83, v100, v82
	v_min_f32_e32 v82, 0, v83
	v_mul_f32_e64 v83, |v83|, s29
	v_exp_f32_e32 v83, v83
	s_nop 0
	v_add_f32_e32 v106, 1.0, v83
	v_add_f32_e32 v84, -1.0, v106
	v_sub_f32_e32 v85, v84, v106
	v_add_f32_e32 v85, 1.0, v85
	v_sub_f32_e32 v84, v83, v84
	v_add_f32_e32 v107, v84, v85
	v_frexp_mant_f32_e32 v84, v106
	v_cmp_gt_f32_e32 vcc, s50, v84
	v_cvt_f64_f32_e32 v[84:85], v106
	v_frexp_exp_i32_f64_e32 v84, v[84:85]
	v_subbrev_co_u32_e32 v112, vcc, 0, v84, vcc
	v_sub_u32_e32 v84, 0, v112
	v_ldexp_f32 v85, v106, v84
	v_add_f32_e32 v106, -1.0, v85
	v_add_f32_e32 v108, 1.0, v85
	v_ldexp_f32 v84, v107, v84
	v_add_f32_e32 v107, 1.0, v106
	v_add_f32_e32 v109, -1.0, v108
	v_sub_f32_e32 v107, v85, v107
	v_sub_f32_e32 v85, v85, v109
	v_add_f32_e32 v107, v84, v107
	v_add_f32_e32 v84, v84, v85
	v_add_f32_e32 v113, v108, v84
	v_rcp_f32_e32 v115, v113
	v_sub_f32_e32 v85, v113, v108
	v_sub_f32_e32 v114, v84, v85
	v_add_f32_e32 v85, v106, v107
	v_mul_f32_e32 v117, v85, v115
	v_sub_f32_e32 v84, v85, v106
	v_mul_f32_e32 v106, v113, v117
	v_fma_f32 v108, v117, v113, -v106
	v_fmac_f32_e32 v108, v117, v114
	v_sub_f32_e32 v116, v107, v84
	v_add_f32_e32 v84, v106, v108
	v_sub_f32_e32 v107, v85, v84
	v_pk_add_f32 v[110:111], v[84:85], v[106:107] neg_lo:[0,1] neg_hi:[0,1]
	v_mov_b32_e32 v109, v84
	v_pk_add_f32 v[84:85], v[110:111], v[108:109] neg_lo:[0,1] neg_hi:[0,1]
	v_cmp_neq_f32_e32 vcc, s52, v83
	v_add_f32_e32 v85, v116, v85
	v_add_f32_e32 v84, v84, v85
	v_add_f32_e32 v85, v107, v84
	v_mul_f32_e32 v116, v115, v85
	v_mul_f32_e32 v106, v113, v116
	v_fma_f32 v108, v116, v113, -v106
	v_fmac_f32_e32 v108, v116, v114
	v_sub_f32_e32 v107, v107, v85
	v_add_f32_e32 v113, v84, v107
	v_add_f32_e32 v84, v106, v108
	v_sub_f32_e32 v107, v85, v84
	v_pk_add_f32 v[110:111], v[84:85], v[106:107] neg_lo:[0,1] neg_hi:[0,1]
	v_mov_b32_e32 v109, v84
	v_pk_add_f32 v[84:85], v[110:111], v[108:109] neg_lo:[0,1] neg_hi:[0,1]
	s_nop 0
	v_add_f32_e32 v85, v113, v85
	v_add_f32_e32 v84, v84, v85
	v_add_f32_e32 v85, v117, v116
	v_add_f32_e32 v84, v107, v84
	v_sub_f32_e32 v106, v85, v117
	v_mul_f32_e32 v84, v115, v84
	v_sub_f32_e32 v106, v116, v106
	v_add_f32_e32 v106, v106, v84
	v_add_f32_e32 v108, v85, v106
	v_mul_f32_e32 v109, v108, v108
	v_fmamk_f32 v84, v109, 0x3e9b6dac, v233
	v_fmaak_f32 v185, v109, v84, 0x3f2aaada
	v_cvt_f32_i32_e32 v84, v112
	v_sub_f32_e32 v85, v108, v85
	v_sub_f32_e32 v85, v106, v85
	v_ldexp_f32 v110, v85, 1
	v_mul_f32_e32 v85, v108, v109
	v_ldexp_f32 v107, v108, 1
	v_pk_mul_f32 v[108:109], v[84:85], v[184:185]
	s_nop 0
	v_fma_f32 v106, v84, s51, -v108
	v_fmac_f32_e32 v106, 0xb102e308, v84
	v_pk_add_f32 v[84:85], v[108:109], v[106:107]
	s_nop 0
	v_sub_f32_e32 v107, v85, v107
	v_sub_f32_e32 v107, v109, v107
	v_add_f32_e32 v111, v110, v107
	v_mov_b32_e32 v110, v108
	v_pk_add_f32 v[108:109], v[84:85], v[108:109] neg_lo:[0,1] neg_hi:[0,1]
	v_pk_add_f32 v[112:113], v[84:85], v[110:111]
	v_mov_b32_e32 v107, v84
	v_mov_b32_e32 v109, v113
	v_pk_add_f32 v[114:115], v[106:107], v[108:109] neg_lo:[0,1] neg_hi:[0,1]
	v_pk_add_f32 v[106:107], v[106:107], v[108:109]
	v_mov_b32_e32 v110, v111
	v_pk_add_f32 v[108:109], v[106:107], v[84:85] op_sel:[1,0] op_sel_hi:[0,1] neg_lo:[0,1] neg_hi:[0,1]
	v_pk_add_f32 v[116:117], v[112:113], v[108:109] op_sel_hi:[1,0] neg_lo:[0,1] neg_hi:[0,1]
	v_mov_b32_e32 v112, v113
	v_mov_b32_e32 v113, v107
	v_pk_mov_b32 v[108:109], v[84:85], v[108:109] op_sel:[1,0]
	v_mov_b32_e32 v111, v84
	v_pk_add_f32 v[108:109], v[112:113], v[108:109] neg_lo:[0,1] neg_hi:[0,1]
	v_mov_b32_e32 v116, v114
	v_pk_add_f32 v[84:85], v[110:111], v[108:109] neg_lo:[0,1] neg_hi:[0,1]
	v_mov_b32_e32 v115, v107
	v_pk_add_f32 v[108:109], v[116:117], v[84:85]
	s_nop 0
	v_pk_add_f32 v[110:111], v[108:109], v[108:109] op_sel:[0,1] op_sel_hi:[1,0]
	s_nop 0
	v_pk_add_f32 v[106:107], v[106:107], v[110:111] op_sel:[1,0] op_sel_hi:[0,1]
	v_mov_b32_e32 v109, v106
	v_pk_add_f32 v[112:113], v[108:109], v[114:115] neg_lo:[0,1] neg_hi:[0,1]
	v_mov_b32_e32 v85, v110
	v_sub_f32_e32 v107, v108, v112
	v_pk_add_f32 v[84:85], v[84:85], v[112:113] neg_lo:[0,1] neg_hi:[0,1]
	v_sub_f32_e32 v107, v114, v107
	v_add_f32_e32 v84, v84, v107
	v_add_f32_e32 v84, v84, v85
	v_add_f32_e32 v84, v106, v84
	v_cndmask_b32_e32 v84, v226, v84, vcc
	v_cmp_ngt_f32_e32 vcc, -1.0, v83
	s_nop 1
	v_cndmask_b32_e32 v84, v227, v84, vcc
	v_cmp_neq_f32_e32 vcc, -1.0, v83
	s_nop 1
	v_cndmask_b32_e32 v84, v236, v84, vcc
	v_cmp_lt_f32_e64 vcc, |v83|, s27
	s_nop 1
	v_cndmask_b32_e32 v83, v84, v83, vcc
	v_sub_f32_e32 v82, v82, v83

.LBB0_1010:
	s_andn2_saveexec_b64 s[44:45], s[44:45]
	s_cbranch_execz .LBB0_1012
	s_mov_b32 s27, 0x33800000
	s_waitcnt vmcnt(0)
	v_mov_b32_e32 v82, v251
	v_add_f32_e32 v83, v101, v82
	v_min_f32_e32 v82, 0, v83
	v_mul_f32_e64 v83, |v83|, s29
	v_exp_f32_e32 v83, v83
	s_nop 0
	v_add_f32_e32 v106, 1.0, v83
	v_add_f32_e32 v84, -1.0, v106
	v_sub_f32_e32 v85, v84, v106
	v_add_f32_e32 v85, 1.0, v85
	v_sub_f32_e32 v84, v83, v84
	v_add_f32_e32 v107, v84, v85
	v_frexp_mant_f32_e32 v84, v106
	v_cmp_gt_f32_e32 vcc, s50, v84
	v_cvt_f64_f32_e32 v[84:85], v106
	v_frexp_exp_i32_f64_e32 v84, v[84:85]
	v_subbrev_co_u32_e32 v112, vcc, 0, v84, vcc
	v_sub_u32_e32 v84, 0, v112
	v_ldexp_f32 v85, v106, v84
	v_add_f32_e32 v106, -1.0, v85
	v_add_f32_e32 v108, 1.0, v85
	v_ldexp_f32 v84, v107, v84
	v_add_f32_e32 v107, 1.0, v106
	v_add_f32_e32 v109, -1.0, v108
	v_sub_f32_e32 v107, v85, v107
	v_sub_f32_e32 v85, v85, v109
	v_add_f32_e32 v107, v84, v107
	v_add_f32_e32 v84, v84, v85
	v_add_f32_e32 v113, v108, v84
	v_rcp_f32_e32 v115, v113
	v_sub_f32_e32 v85, v113, v108
	v_sub_f32_e32 v114, v84, v85
	v_add_f32_e32 v85, v106, v107
	v_mul_f32_e32 v117, v85, v115
	v_sub_f32_e32 v84, v85, v106
	v_mul_f32_e32 v106, v113, v117
	v_fma_f32 v108, v117, v113, -v106
	v_fmac_f32_e32 v108, v117, v114
	v_sub_f32_e32 v116, v107, v84
	v_add_f32_e32 v84, v106, v108
	v_sub_f32_e32 v107, v85, v84
	v_pk_add_f32 v[110:111], v[84:85], v[106:107] neg_lo:[0,1] neg_hi:[0,1]
	v_mov_b32_e32 v109, v84
	v_pk_add_f32 v[84:85], v[110:111], v[108:109] neg_lo:[0,1] neg_hi:[0,1]
	v_cmp_neq_f32_e32 vcc, s52, v83
	v_add_f32_e32 v85, v116, v85
	v_add_f32_e32 v84, v84, v85
	v_add_f32_e32 v85, v107, v84
	v_mul_f32_e32 v116, v115, v85
	v_mul_f32_e32 v106, v113, v116
	v_fma_f32 v108, v116, v113, -v106
	v_fmac_f32_e32 v108, v116, v114
	v_sub_f32_e32 v107, v107, v85
	v_add_f32_e32 v113, v84, v107
	v_add_f32_e32 v84, v106, v108
	v_sub_f32_e32 v107, v85, v84
	v_pk_add_f32 v[110:111], v[84:85], v[106:107] neg_lo:[0,1] neg_hi:[0,1]
	v_mov_b32_e32 v109, v84
	v_pk_add_f32 v[84:85], v[110:111], v[108:109] neg_lo:[0,1] neg_hi:[0,1]
	s_nop 0
	v_add_f32_e32 v85, v113, v85
	v_add_f32_e32 v84, v84, v85
	v_add_f32_e32 v85, v117, v116
	v_add_f32_e32 v84, v107, v84
	v_sub_f32_e32 v106, v85, v117
	v_mul_f32_e32 v84, v115, v84
	v_sub_f32_e32 v106, v116, v106
	v_add_f32_e32 v106, v106, v84
	v_add_f32_e32 v108, v85, v106
	v_mul_f32_e32 v109, v108, v108
	v_fmamk_f32 v84, v109, 0x3e9b6dac, v233
	v_fmaak_f32 v185, v109, v84, 0x3f2aaada
	v_cvt_f32_i32_e32 v84, v112
	v_sub_f32_e32 v85, v108, v85
	v_sub_f32_e32 v85, v106, v85
	v_ldexp_f32 v110, v85, 1
	v_mul_f32_e32 v85, v108, v109
	v_ldexp_f32 v107, v108, 1
	v_pk_mul_f32 v[108:109], v[84:85], v[184:185]
	s_nop 0
	v_fma_f32 v106, v84, s51, -v108
	v_fmac_f32_e32 v106, 0xb102e308, v84
	v_pk_add_f32 v[84:85], v[108:109], v[106:107]
	s_nop 0
	v_sub_f32_e32 v107, v85, v107
	v_sub_f32_e32 v107, v109, v107
	v_add_f32_e32 v111, v110, v107
	v_mov_b32_e32 v110, v108
	v_pk_add_f32 v[108:109], v[84:85], v[108:109] neg_lo:[0,1] neg_hi:[0,1]
	v_pk_add_f32 v[112:113], v[84:85], v[110:111]
	v_mov_b32_e32 v107, v84
	v_mov_b32_e32 v109, v113
	v_pk_add_f32 v[114:115], v[106:107], v[108:109] neg_lo:[0,1] neg_hi:[0,1]
	v_pk_add_f32 v[106:107], v[106:107], v[108:109]
	v_mov_b32_e32 v110, v111
	v_pk_add_f32 v[108:109], v[106:107], v[84:85] op_sel:[1,0] op_sel_hi:[0,1] neg_lo:[0,1] neg_hi:[0,1]
	v_pk_add_f32 v[116:117], v[112:113], v[108:109] op_sel_hi:[1,0] neg_lo:[0,1] neg_hi:[0,1]
	v_mov_b32_e32 v112, v113
	v_mov_b32_e32 v113, v107
	v_pk_mov_b32 v[108:109], v[84:85], v[108:109] op_sel:[1,0]
	v_mov_b32_e32 v111, v84
	v_pk_add_f32 v[108:109], v[112:113], v[108:109] neg_lo:[0,1] neg_hi:[0,1]
	v_mov_b32_e32 v116, v114
	v_pk_add_f32 v[84:85], v[110:111], v[108:109] neg_lo:[0,1] neg_hi:[0,1]
	v_mov_b32_e32 v115, v107
	v_pk_add_f32 v[108:109], v[116:117], v[84:85]
	s_nop 0
	v_pk_add_f32 v[110:111], v[108:109], v[108:109] op_sel:[0,1] op_sel_hi:[1,0]
	s_nop 0
	v_pk_add_f32 v[106:107], v[106:107], v[110:111] op_sel:[1,0] op_sel_hi:[0,1]
	v_mov_b32_e32 v109, v106
	v_pk_add_f32 v[112:113], v[108:109], v[114:115] neg_lo:[0,1] neg_hi:[0,1]
	v_mov_b32_e32 v85, v110
	v_sub_f32_e32 v107, v108, v112
	v_pk_add_f32 v[84:85], v[84:85], v[112:113] neg_lo:[0,1] neg_hi:[0,1]
	v_sub_f32_e32 v107, v114, v107
	v_add_f32_e32 v84, v84, v107
	v_add_f32_e32 v84, v84, v85
	v_add_f32_e32 v84, v106, v84
	v_cndmask_b32_e32 v84, v226, v84, vcc
	v_cmp_ngt_f32_e32 vcc, -1.0, v83
	s_nop 1
	v_cndmask_b32_e32 v84, v227, v84, vcc
	v_cmp_neq_f32_e32 vcc, -1.0, v83
	s_nop 1
	v_cndmask_b32_e32 v84, v236, v84, vcc
	v_cmp_lt_f32_e64 vcc, |v83|, s27
	s_nop 1
	v_cndmask_b32_e32 v83, v84, v83, vcc
	v_sub_f32_e32 v82, v82, v83

.LBB0_1024:
	s_andn2_saveexec_b64 s[44:45], s[44:45]
	s_cbranch_execz .LBB0_1026
	s_mov_b32 s27, 0x33800000
	s_waitcnt vmcnt(0)
	v_mov_b32_e32 v66, v248
	v_add_f32_e32 v67, v78, v66
	v_min_f32_e32 v66, 0, v67
	v_mul_f32_e64 v67, |v67|, s29
	v_exp_f32_e32 v67, v67
	s_nop 0
	v_add_f32_e32 v88, 1.0, v67
	v_add_f32_e32 v68, -1.0, v88
	v_sub_f32_e32 v69, v68, v88
	v_add_f32_e32 v69, 1.0, v69
	v_sub_f32_e32 v68, v67, v68
	v_add_f32_e32 v89, v68, v69
	v_frexp_mant_f32_e32 v68, v88
	v_cmp_gt_f32_e32 vcc, s50, v68
	v_cvt_f64_f32_e32 v[68:69], v88
	v_frexp_exp_i32_f64_e32 v68, v[68:69]
	v_subbrev_co_u32_e32 v94, vcc, 0, v68, vcc
	v_sub_u32_e32 v68, 0, v94
	v_ldexp_f32 v69, v88, v68
	v_add_f32_e32 v88, -1.0, v69
	v_add_f32_e32 v90, 1.0, v69
	v_ldexp_f32 v68, v89, v68
	v_add_f32_e32 v89, 1.0, v88
	v_add_f32_e32 v91, -1.0, v90
	v_sub_f32_e32 v89, v69, v89
	v_sub_f32_e32 v69, v69, v91
	v_add_f32_e32 v89, v68, v89
	v_add_f32_e32 v68, v68, v69
	v_add_f32_e32 v95, v90, v68
	v_rcp_f32_e32 v97, v95
	v_sub_f32_e32 v69, v95, v90
	v_sub_f32_e32 v96, v68, v69
	v_add_f32_e32 v69, v88, v89
	v_mul_f32_e32 v99, v69, v97
	v_sub_f32_e32 v68, v69, v88
	v_mul_f32_e32 v88, v95, v99
	v_fma_f32 v90, v99, v95, -v88
	v_fmac_f32_e32 v90, v99, v96
	v_sub_f32_e32 v98, v89, v68
	v_add_f32_e32 v68, v88, v90
	v_sub_f32_e32 v89, v69, v68
	v_pk_add_f32 v[92:93], v[68:69], v[88:89] neg_lo:[0,1] neg_hi:[0,1]
	v_mov_b32_e32 v91, v68
	v_pk_add_f32 v[68:69], v[92:93], v[90:91] neg_lo:[0,1] neg_hi:[0,1]
	v_cmp_neq_f32_e32 vcc, s52, v67
	v_add_f32_e32 v69, v98, v69
	v_add_f32_e32 v68, v68, v69
	v_add_f32_e32 v69, v89, v68
	v_mul_f32_e32 v98, v97, v69
	v_mul_f32_e32 v88, v95, v98
	v_fma_f32 v90, v98, v95, -v88
	v_fmac_f32_e32 v90, v98, v96
	v_sub_f32_e32 v89, v89, v69
	v_add_f32_e32 v95, v68, v89
	v_add_f32_e32 v68, v88, v90
	v_sub_f32_e32 v89, v69, v68
	v_pk_add_f32 v[92:93], v[68:69], v[88:89] neg_lo:[0,1] neg_hi:[0,1]
	v_mov_b32_e32 v91, v68
	v_pk_add_f32 v[68:69], v[92:93], v[90:91] neg_lo:[0,1] neg_hi:[0,1]
	s_nop 0
	v_add_f32_e32 v69, v95, v69
	v_add_f32_e32 v68, v68, v69
	v_add_f32_e32 v69, v99, v98
	v_add_f32_e32 v68, v89, v68
	v_sub_f32_e32 v88, v69, v99
	v_mul_f32_e32 v68, v97, v68
	v_sub_f32_e32 v88, v98, v88
	v_add_f32_e32 v88, v88, v68
	v_add_f32_e32 v90, v69, v88
	v_mul_f32_e32 v91, v90, v90
	v_fmamk_f32 v68, v91, 0x3e9b6dac, v233
	v_fmaak_f32 v185, v91, v68, 0x3f2aaada
	v_cvt_f32_i32_e32 v68, v94
	v_sub_f32_e32 v69, v90, v69
	v_sub_f32_e32 v69, v88, v69
	v_ldexp_f32 v92, v69, 1
	v_mul_f32_e32 v69, v90, v91
	v_ldexp_f32 v89, v90, 1
	v_pk_mul_f32 v[90:91], v[68:69], v[184:185]
	s_nop 0
	v_fma_f32 v88, v68, s51, -v90
	v_fmac_f32_e32 v88, 0xb102e308, v68
	v_pk_add_f32 v[68:69], v[90:91], v[88:89]
	s_nop 0
	v_sub_f32_e32 v89, v69, v89
	v_sub_f32_e32 v89, v91, v89
	v_add_f32_e32 v93, v92, v89
	v_mov_b32_e32 v92, v90
	v_pk_add_f32 v[90:91], v[68:69], v[90:91] neg_lo:[0,1] neg_hi:[0,1]
	v_pk_add_f32 v[94:95], v[68:69], v[92:93]
	v_mov_b32_e32 v89, v68
	v_mov_b32_e32 v91, v95
	v_pk_add_f32 v[96:97], v[88:89], v[90:91] neg_lo:[0,1] neg_hi:[0,1]
	v_pk_add_f32 v[88:89], v[88:89], v[90:91]
	v_mov_b32_e32 v92, v93
	v_pk_add_f32 v[90:91], v[88:89], v[68:69] op_sel:[1,0] op_sel_hi:[0,1] neg_lo:[0,1] neg_hi:[0,1]
	v_pk_add_f32 v[98:99], v[94:95], v[90:91] op_sel_hi:[1,0] neg_lo:[0,1] neg_hi:[0,1]
	v_mov_b32_e32 v94, v95
	v_mov_b32_e32 v95, v89
	v_pk_mov_b32 v[90:91], v[68:69], v[90:91] op_sel:[1,0]
	v_mov_b32_e32 v93, v68
	v_pk_add_f32 v[90:91], v[94:95], v[90:91] neg_lo:[0,1] neg_hi:[0,1]
	v_mov_b32_e32 v98, v96
	v_pk_add_f32 v[68:69], v[92:93], v[90:91] neg_lo:[0,1] neg_hi:[0,1]
	v_mov_b32_e32 v97, v89
	v_pk_add_f32 v[90:91], v[98:99], v[68:69]
	s_nop 0
	v_pk_add_f32 v[92:93], v[90:91], v[90:91] op_sel:[0,1] op_sel_hi:[1,0]
	s_nop 0
	v_pk_add_f32 v[88:89], v[88:89], v[92:93] op_sel:[1,0] op_sel_hi:[0,1]
	v_mov_b32_e32 v91, v88
	v_pk_add_f32 v[94:95], v[90:91], v[96:97] neg_lo:[0,1] neg_hi:[0,1]
	v_mov_b32_e32 v69, v92
	v_sub_f32_e32 v89, v90, v94
	v_pk_add_f32 v[68:69], v[68:69], v[94:95] neg_lo:[0,1] neg_hi:[0,1]
	v_sub_f32_e32 v89, v96, v89
	v_add_f32_e32 v68, v68, v89
	v_add_f32_e32 v68, v68, v69
	v_add_f32_e32 v68, v88, v68
	v_cndmask_b32_e32 v68, v226, v68, vcc
	v_cmp_ngt_f32_e32 vcc, -1.0, v67
	s_nop 1
	v_cndmask_b32_e32 v68, v227, v68, vcc
	v_cmp_neq_f32_e32 vcc, -1.0, v67
	s_nop 1
	v_cndmask_b32_e32 v68, v236, v68, vcc
	v_cmp_lt_f32_e64 vcc, |v67|, s27
	s_nop 1
	v_cndmask_b32_e32 v67, v68, v67, vcc
	v_sub_f32_e32 v66, v66, v67

.LBB0_1028:
	s_andn2_saveexec_b64 s[44:45], s[44:45]
	s_cbranch_execz .LBB0_1030
	s_mov_b32 s27, 0x33800000
	s_waitcnt vmcnt(0)
	v_mov_b32_e32 v66, v249
	v_add_f32_e32 v67, v79, v66
	v_min_f32_e32 v66, 0, v67
	v_mul_f32_e64 v67, |v67|, s29
	v_exp_f32_e32 v67, v67
	s_nop 0
	v_add_f32_e32 v90, 1.0, v67
	v_add_f32_e32 v68, -1.0, v90
	v_sub_f32_e32 v69, v68, v90
	v_add_f32_e32 v69, 1.0, v69
	v_sub_f32_e32 v68, v67, v68
	v_add_f32_e32 v91, v68, v69
	v_frexp_mant_f32_e32 v68, v90
	v_cmp_gt_f32_e32 vcc, s50, v68
	v_cvt_f64_f32_e32 v[68:69], v90
	v_frexp_exp_i32_f64_e32 v68, v[68:69]
	v_subbrev_co_u32_e32 v96, vcc, 0, v68, vcc
	v_sub_u32_e32 v68, 0, v96
	v_ldexp_f32 v69, v90, v68
	v_add_f32_e32 v90, -1.0, v69
	v_add_f32_e32 v92, 1.0, v69
	v_ldexp_f32 v68, v91, v68
	v_add_f32_e32 v91, 1.0, v90
	v_add_f32_e32 v93, -1.0, v92
	v_sub_f32_e32 v91, v69, v91
	v_sub_f32_e32 v69, v69, v93
	v_add_f32_e32 v91, v68, v91
	v_add_f32_e32 v68, v68, v69
	v_add_f32_e32 v97, v92, v68
	v_rcp_f32_e32 v99, v97
	v_sub_f32_e32 v69, v97, v92
	v_sub_f32_e32 v98, v68, v69
	v_add_f32_e32 v69, v90, v91
	v_mul_f32_e32 v101, v69, v99
	v_sub_f32_e32 v68, v69, v90
	v_mul_f32_e32 v90, v97, v101
	v_fma_f32 v92, v101, v97, -v90
	v_fmac_f32_e32 v92, v101, v98
	v_sub_f32_e32 v100, v91, v68
	v_add_f32_e32 v68, v90, v92
	v_sub_f32_e32 v91, v69, v68
	v_pk_add_f32 v[94:95], v[68:69], v[90:91] neg_lo:[0,1] neg_hi:[0,1]
	v_mov_b32_e32 v93, v68
	v_pk_add_f32 v[68:69], v[94:95], v[92:93] neg_lo:[0,1] neg_hi:[0,1]
	v_cmp_neq_f32_e32 vcc, s52, v67
	v_add_f32_e32 v69, v100, v69
	v_add_f32_e32 v68, v68, v69
	v_add_f32_e32 v69, v91, v68
	v_mul_f32_e32 v100, v99, v69
	v_mul_f32_e32 v90, v97, v100
	v_fma_f32 v92, v100, v97, -v90
	v_fmac_f32_e32 v92, v100, v98
	v_sub_f32_e32 v91, v91, v69
	v_add_f32_e32 v97, v68, v91
	v_add_f32_e32 v68, v90, v92
	v_sub_f32_e32 v91, v69, v68
	v_pk_add_f32 v[94:95], v[68:69], v[90:91] neg_lo:[0,1] neg_hi:[0,1]
	v_mov_b32_e32 v93, v68
	v_pk_add_f32 v[68:69], v[94:95], v[92:93] neg_lo:[0,1] neg_hi:[0,1]
	s_nop 0
	v_add_f32_e32 v69, v97, v69
	v_add_f32_e32 v68, v68, v69
	v_add_f32_e32 v69, v101, v100
	v_add_f32_e32 v68, v91, v68
	v_sub_f32_e32 v90, v69, v101
	v_mul_f32_e32 v68, v99, v68
	v_sub_f32_e32 v90, v100, v90
	v_add_f32_e32 v90, v90, v68
	v_add_f32_e32 v92, v69, v90
	v_mul_f32_e32 v93, v92, v92
	v_fmamk_f32 v68, v93, 0x3e9b6dac, v233
	v_fmaak_f32 v185, v93, v68, 0x3f2aaada
	v_cvt_f32_i32_e32 v68, v96
	v_sub_f32_e32 v69, v92, v69
	v_sub_f32_e32 v69, v90, v69
	v_ldexp_f32 v94, v69, 1
	v_mul_f32_e32 v69, v92, v93
	v_ldexp_f32 v91, v92, 1
	v_pk_mul_f32 v[92:93], v[68:69], v[184:185]
	s_nop 0
	v_fma_f32 v90, v68, s51, -v92
	v_fmac_f32_e32 v90, 0xb102e308, v68
	v_pk_add_f32 v[68:69], v[92:93], v[90:91]
	s_nop 0
	v_sub_f32_e32 v91, v69, v91
	v_sub_f32_e32 v91, v93, v91
	v_add_f32_e32 v95, v94, v91
	v_mov_b32_e32 v94, v92
	v_pk_add_f32 v[92:93], v[68:69], v[92:93] neg_lo:[0,1] neg_hi:[0,1]
	v_pk_add_f32 v[96:97], v[68:69], v[94:95]
	v_mov_b32_e32 v91, v68
	v_mov_b32_e32 v93, v97
	v_pk_add_f32 v[98:99], v[90:91], v[92:93] neg_lo:[0,1] neg_hi:[0,1]
	v_pk_add_f32 v[90:91], v[90:91], v[92:93]
	v_mov_b32_e32 v94, v95
	v_pk_add_f32 v[92:93], v[90:91], v[68:69] op_sel:[1,0] op_sel_hi:[0,1] neg_lo:[0,1] neg_hi:[0,1]
	v_pk_add_f32 v[100:101], v[96:97], v[92:93] op_sel_hi:[1,0] neg_lo:[0,1] neg_hi:[0,1]
	v_mov_b32_e32 v96, v97
	v_mov_b32_e32 v97, v91
	v_pk_mov_b32 v[92:93], v[68:69], v[92:93] op_sel:[1,0]
	v_mov_b32_e32 v95, v68
	v_pk_add_f32 v[92:93], v[96:97], v[92:93] neg_lo:[0,1] neg_hi:[0,1]
	v_mov_b32_e32 v100, v98
	v_pk_add_f32 v[68:69], v[94:95], v[92:93] neg_lo:[0,1] neg_hi:[0,1]
	v_mov_b32_e32 v99, v91
	v_pk_add_f32 v[92:93], v[100:101], v[68:69]
	s_nop 0
	v_pk_add_f32 v[94:95], v[92:93], v[92:93] op_sel:[0,1] op_sel_hi:[1,0]
	s_nop 0
	v_pk_add_f32 v[90:91], v[90:91], v[94:95] op_sel:[1,0] op_sel_hi:[0,1]
	v_mov_b32_e32 v93, v90
	v_pk_add_f32 v[96:97], v[92:93], v[98:99] neg_lo:[0,1] neg_hi:[0,1]
	v_mov_b32_e32 v69, v94
	v_sub_f32_e32 v91, v92, v96
	v_pk_add_f32 v[68:69], v[68:69], v[96:97] neg_lo:[0,1] neg_hi:[0,1]
	v_sub_f32_e32 v91, v98, v91
	v_add_f32_e32 v68, v68, v91
	v_add_f32_e32 v68, v68, v69
	v_add_f32_e32 v68, v90, v68
	v_cndmask_b32_e32 v68, v226, v68, vcc
	v_cmp_ngt_f32_e32 vcc, -1.0, v67
	s_nop 1
	v_cndmask_b32_e32 v68, v227, v68, vcc
	v_cmp_neq_f32_e32 vcc, -1.0, v67
	s_nop 1
	v_cndmask_b32_e32 v68, v236, v68, vcc
	v_cmp_lt_f32_e64 vcc, |v67|, s27
	s_nop 1
	v_cndmask_b32_e32 v67, v68, v67, vcc
	v_sub_f32_e32 v66, v66, v67

.LBB0_1032:
	s_andn2_saveexec_b64 s[44:45], s[44:45]
	s_cbranch_execz .LBB0_1034
	s_mov_b32 s27, 0x33800000
	s_waitcnt vmcnt(0)
	v_mov_b32_e32 v66, v250
	v_add_f32_e32 v67, v84, v66
	v_min_f32_e32 v66, 0, v67
	v_mul_f32_e64 v67, |v67|, s29
	v_exp_f32_e32 v67, v67
	s_nop 0
	v_add_f32_e32 v90, 1.0, v67
	v_add_f32_e32 v68, -1.0, v90
	v_sub_f32_e32 v69, v68, v90
	v_add_f32_e32 v69, 1.0, v69
	v_sub_f32_e32 v68, v67, v68
	v_add_f32_e32 v91, v68, v69
	v_frexp_mant_f32_e32 v68, v90
	v_cmp_gt_f32_e32 vcc, s50, v68
	v_cvt_f64_f32_e32 v[68:69], v90
	v_frexp_exp_i32_f64_e32 v68, v[68:69]
	v_subbrev_co_u32_e32 v96, vcc, 0, v68, vcc
	v_sub_u32_e32 v68, 0, v96
	v_ldexp_f32 v69, v90, v68
	v_add_f32_e32 v90, -1.0, v69
	v_add_f32_e32 v92, 1.0, v69
	v_ldexp_f32 v68, v91, v68
	v_add_f32_e32 v91, 1.0, v90
	v_add_f32_e32 v93, -1.0, v92
	v_sub_f32_e32 v91, v69, v91
	v_sub_f32_e32 v69, v69, v93
	v_add_f32_e32 v91, v68, v91
	v_add_f32_e32 v68, v68, v69
	v_add_f32_e32 v97, v92, v68
	v_rcp_f32_e32 v99, v97
	v_sub_f32_e32 v69, v97, v92
	v_sub_f32_e32 v98, v68, v69
	v_add_f32_e32 v69, v90, v91
	v_mul_f32_e32 v101, v69, v99
	v_sub_f32_e32 v68, v69, v90
	v_mul_f32_e32 v90, v97, v101
	v_fma_f32 v92, v101, v97, -v90
	v_fmac_f32_e32 v92, v101, v98
	v_sub_f32_e32 v100, v91, v68
	v_add_f32_e32 v68, v90, v92
	v_sub_f32_e32 v91, v69, v68
	v_pk_add_f32 v[94:95], v[68:69], v[90:91] neg_lo:[0,1] neg_hi:[0,1]
	v_mov_b32_e32 v93, v68
	v_pk_add_f32 v[68:69], v[94:95], v[92:93] neg_lo:[0,1] neg_hi:[0,1]
	v_cmp_neq_f32_e32 vcc, s52, v67
	v_add_f32_e32 v69, v100, v69
	v_add_f32_e32 v68, v68, v69
	v_add_f32_e32 v69, v91, v68
	v_mul_f32_e32 v100, v99, v69
	v_mul_f32_e32 v90, v97, v100
	v_fma_f32 v92, v100, v97, -v90
	v_fmac_f32_e32 v92, v100, v98
	v_sub_f32_e32 v91, v91, v69
	v_add_f32_e32 v97, v68, v91
	v_add_f32_e32 v68, v90, v92
	v_sub_f32_e32 v91, v69, v68
	v_pk_add_f32 v[94:95], v[68:69], v[90:91] neg_lo:[0,1] neg_hi:[0,1]
	v_mov_b32_e32 v93, v68
	v_pk_add_f32 v[68:69], v[94:95], v[92:93] neg_lo:[0,1] neg_hi:[0,1]
	s_nop 0
	v_add_f32_e32 v69, v97, v69
	v_add_f32_e32 v68, v68, v69
	v_add_f32_e32 v69, v101, v100
	v_add_f32_e32 v68, v91, v68
	v_sub_f32_e32 v90, v69, v101
	v_mul_f32_e32 v68, v99, v68
	v_sub_f32_e32 v90, v100, v90
	v_add_f32_e32 v90, v90, v68
	v_add_f32_e32 v92, v69, v90
	v_mul_f32_e32 v93, v92, v92
	v_fmamk_f32 v68, v93, 0x3e9b6dac, v233
	v_fmaak_f32 v185, v93, v68, 0x3f2aaada
	v_cvt_f32_i32_e32 v68, v96
	v_sub_f32_e32 v69, v92, v69
	v_sub_f32_e32 v69, v90, v69
	v_ldexp_f32 v94, v69, 1
	v_mul_f32_e32 v69, v92, v93
	v_ldexp_f32 v91, v92, 1
	v_pk_mul_f32 v[92:93], v[68:69], v[184:185]
	s_nop 0
	v_fma_f32 v90, v68, s51, -v92
	v_fmac_f32_e32 v90, 0xb102e308, v68
	v_pk_add_f32 v[68:69], v[92:93], v[90:91]
	s_nop 0
	v_sub_f32_e32 v91, v69, v91
	v_sub_f32_e32 v91, v93, v91
	v_add_f32_e32 v95, v94, v91
	v_mov_b32_e32 v94, v92
	v_pk_add_f32 v[92:93], v[68:69], v[92:93] neg_lo:[0,1] neg_hi:[0,1]
	v_pk_add_f32 v[96:97], v[68:69], v[94:95]
	v_mov_b32_e32 v91, v68
	v_mov_b32_e32 v93, v97
	v_pk_add_f32 v[98:99], v[90:91], v[92:93] neg_lo:[0,1] neg_hi:[0,1]
	v_pk_add_f32 v[90:91], v[90:91], v[92:93]
	v_mov_b32_e32 v94, v95
	v_pk_add_f32 v[92:93], v[90:91], v[68:69] op_sel:[1,0] op_sel_hi:[0,1] neg_lo:[0,1] neg_hi:[0,1]
	v_pk_add_f32 v[100:101], v[96:97], v[92:93] op_sel_hi:[1,0] neg_lo:[0,1] neg_hi:[0,1]
	v_mov_b32_e32 v96, v97
	v_mov_b32_e32 v97, v91
	v_pk_mov_b32 v[92:93], v[68:69], v[92:93] op_sel:[1,0]
	v_mov_b32_e32 v95, v68
	v_pk_add_f32 v[92:93], v[96:97], v[92:93] neg_lo:[0,1] neg_hi:[0,1]
	v_mov_b32_e32 v100, v98
	v_pk_add_f32 v[68:69], v[94:95], v[92:93] neg_lo:[0,1] neg_hi:[0,1]
	v_mov_b32_e32 v99, v91
	v_pk_add_f32 v[92:93], v[100:101], v[68:69]
	s_nop 0
	v_pk_add_f32 v[94:95], v[92:93], v[92:93] op_sel:[0,1] op_sel_hi:[1,0]
	s_nop 0
	v_pk_add_f32 v[90:91], v[90:91], v[94:95] op_sel:[1,0] op_sel_hi:[0,1]
	v_mov_b32_e32 v93, v90
	v_pk_add_f32 v[96:97], v[92:93], v[98:99] neg_lo:[0,1] neg_hi:[0,1]
	v_mov_b32_e32 v69, v94
	v_sub_f32_e32 v91, v92, v96
	v_pk_add_f32 v[68:69], v[68:69], v[96:97] neg_lo:[0,1] neg_hi:[0,1]
	v_sub_f32_e32 v91, v98, v91
	v_add_f32_e32 v68, v68, v91
	v_add_f32_e32 v68, v68, v69
	v_add_f32_e32 v68, v90, v68
	v_cndmask_b32_e32 v68, v226, v68, vcc
	v_cmp_ngt_f32_e32 vcc, -1.0, v67
	s_nop 1
	v_cndmask_b32_e32 v68, v227, v68, vcc
	v_cmp_neq_f32_e32 vcc, -1.0, v67
	s_nop 1
	v_cndmask_b32_e32 v68, v236, v68, vcc
	v_cmp_lt_f32_e64 vcc, |v67|, s27
	s_nop 1
	v_cndmask_b32_e32 v67, v68, v67, vcc
	v_sub_f32_e32 v66, v66, v67

.LBB0_1036:
	s_andn2_saveexec_b64 s[44:45], s[44:45]
	s_cbranch_execz .LBB0_1038
	s_mov_b32 s27, 0x33800000
	s_waitcnt vmcnt(0)
	v_mov_b32_e32 v66, v251
	v_add_f32_e32 v67, v85, v66
	v_min_f32_e32 v66, 0, v67
	v_mul_f32_e64 v67, |v67|, s29
	v_exp_f32_e32 v67, v67
	s_nop 0
	v_add_f32_e32 v90, 1.0, v67
	v_add_f32_e32 v68, -1.0, v90
	v_sub_f32_e32 v69, v68, v90
	v_add_f32_e32 v69, 1.0, v69
	v_sub_f32_e32 v68, v67, v68
	v_add_f32_e32 v91, v68, v69
	v_frexp_mant_f32_e32 v68, v90
	v_cmp_gt_f32_e32 vcc, s50, v68
	v_cvt_f64_f32_e32 v[68:69], v90
	v_frexp_exp_i32_f64_e32 v68, v[68:69]
	v_subbrev_co_u32_e32 v96, vcc, 0, v68, vcc
	v_sub_u32_e32 v68, 0, v96
	v_ldexp_f32 v69, v90, v68
	v_add_f32_e32 v90, -1.0, v69
	v_add_f32_e32 v92, 1.0, v69
	v_ldexp_f32 v68, v91, v68
	v_add_f32_e32 v91, 1.0, v90
	v_add_f32_e32 v93, -1.0, v92
	v_sub_f32_e32 v91, v69, v91
	v_sub_f32_e32 v69, v69, v93
	v_add_f32_e32 v91, v68, v91
	v_add_f32_e32 v68, v68, v69
	v_add_f32_e32 v97, v92, v68
	v_rcp_f32_e32 v99, v97
	v_sub_f32_e32 v69, v97, v92
	v_sub_f32_e32 v98, v68, v69
	v_add_f32_e32 v69, v90, v91
	v_mul_f32_e32 v101, v69, v99
	v_sub_f32_e32 v68, v69, v90
	v_mul_f32_e32 v90, v97, v101
	v_fma_f32 v92, v101, v97, -v90
	v_fmac_f32_e32 v92, v101, v98
	v_sub_f32_e32 v100, v91, v68
	v_add_f32_e32 v68, v90, v92
	v_sub_f32_e32 v91, v69, v68
	v_pk_add_f32 v[94:95], v[68:69], v[90:91] neg_lo:[0,1] neg_hi:[0,1]
	v_mov_b32_e32 v93, v68
	v_pk_add_f32 v[68:69], v[94:95], v[92:93] neg_lo:[0,1] neg_hi:[0,1]
	v_cmp_neq_f32_e32 vcc, s52, v67
	v_add_f32_e32 v69, v100, v69
	v_add_f32_e32 v68, v68, v69
	v_add_f32_e32 v69, v91, v68
	v_mul_f32_e32 v100, v99, v69
	v_mul_f32_e32 v90, v97, v100
	v_fma_f32 v92, v100, v97, -v90
	v_fmac_f32_e32 v92, v100, v98
	v_sub_f32_e32 v91, v91, v69
	v_add_f32_e32 v97, v68, v91
	v_add_f32_e32 v68, v90, v92
	v_sub_f32_e32 v91, v69, v68
	v_pk_add_f32 v[94:95], v[68:69], v[90:91] neg_lo:[0,1] neg_hi:[0,1]
	v_mov_b32_e32 v93, v68
	v_pk_add_f32 v[68:69], v[94:95], v[92:93] neg_lo:[0,1] neg_hi:[0,1]
	s_nop 0
	v_add_f32_e32 v69, v97, v69
	v_add_f32_e32 v68, v68, v69
	v_add_f32_e32 v69, v101, v100
	v_add_f32_e32 v68, v91, v68
	v_sub_f32_e32 v90, v69, v101
	v_mul_f32_e32 v68, v99, v68
	v_sub_f32_e32 v90, v100, v90
	v_add_f32_e32 v90, v90, v68
	v_add_f32_e32 v92, v69, v90
	v_mul_f32_e32 v93, v92, v92
	v_fmamk_f32 v68, v93, 0x3e9b6dac, v233
	v_fmaak_f32 v185, v93, v68, 0x3f2aaada
	v_cvt_f32_i32_e32 v68, v96
	v_sub_f32_e32 v69, v92, v69
	v_sub_f32_e32 v69, v90, v69
	v_ldexp_f32 v94, v69, 1
	v_mul_f32_e32 v69, v92, v93
	v_ldexp_f32 v91, v92, 1
	v_pk_mul_f32 v[92:93], v[68:69], v[184:185]
	s_nop 0
	v_fma_f32 v90, v68, s51, -v92
	v_fmac_f32_e32 v90, 0xb102e308, v68
	v_pk_add_f32 v[68:69], v[92:93], v[90:91]
	s_nop 0
	v_sub_f32_e32 v91, v69, v91
	v_sub_f32_e32 v91, v93, v91
	v_add_f32_e32 v95, v94, v91
	v_mov_b32_e32 v94, v92
	v_pk_add_f32 v[92:93], v[68:69], v[92:93] neg_lo:[0,1] neg_hi:[0,1]
	v_pk_add_f32 v[96:97], v[68:69], v[94:95]
	v_mov_b32_e32 v91, v68
	v_mov_b32_e32 v93, v97
	v_pk_add_f32 v[98:99], v[90:91], v[92:93] neg_lo:[0,1] neg_hi:[0,1]
	v_pk_add_f32 v[90:91], v[90:91], v[92:93]
	v_mov_b32_e32 v94, v95
	v_pk_add_f32 v[92:93], v[90:91], v[68:69] op_sel:[1,0] op_sel_hi:[0,1] neg_lo:[0,1] neg_hi:[0,1]
	v_pk_add_f32 v[100:101], v[96:97], v[92:93] op_sel_hi:[1,0] neg_lo:[0,1] neg_hi:[0,1]
	v_mov_b32_e32 v96, v97
	v_mov_b32_e32 v97, v91
	v_pk_mov_b32 v[92:93], v[68:69], v[92:93] op_sel:[1,0]
	v_mov_b32_e32 v95, v68
	v_pk_add_f32 v[92:93], v[96:97], v[92:93] neg_lo:[0,1] neg_hi:[0,1]
	v_mov_b32_e32 v100, v98
	v_pk_add_f32 v[68:69], v[94:95], v[92:93] neg_lo:[0,1] neg_hi:[0,1]
	v_mov_b32_e32 v99, v91
	v_pk_add_f32 v[92:93], v[100:101], v[68:69]
	s_nop 0
	v_pk_add_f32 v[94:95], v[92:93], v[92:93] op_sel:[0,1] op_sel_hi:[1,0]
	s_nop 0
	v_pk_add_f32 v[90:91], v[90:91], v[94:95] op_sel:[1,0] op_sel_hi:[0,1]
	v_mov_b32_e32 v93, v90
	v_pk_add_f32 v[96:97], v[92:93], v[98:99] neg_lo:[0,1] neg_hi:[0,1]
	v_mov_b32_e32 v69, v94
	v_sub_f32_e32 v91, v92, v96
	v_pk_add_f32 v[68:69], v[68:69], v[96:97] neg_lo:[0,1] neg_hi:[0,1]
	v_sub_f32_e32 v91, v98, v91
	v_add_f32_e32 v68, v68, v91
	v_add_f32_e32 v68, v68, v69
	v_add_f32_e32 v68, v90, v68
	v_cndmask_b32_e32 v68, v226, v68, vcc
	v_cmp_ngt_f32_e32 vcc, -1.0, v67
	s_nop 1
	v_cndmask_b32_e32 v68, v227, v68, vcc
	v_cmp_neq_f32_e32 vcc, -1.0, v67
	s_nop 1
	v_cndmask_b32_e32 v68, v236, v68, vcc
	v_cmp_lt_f32_e64 vcc, |v67|, s27
	s_nop 1
	v_cndmask_b32_e32 v67, v68, v67, vcc
	v_sub_f32_e32 v66, v66, v67

.LBB0_1050:
	s_andn2_saveexec_b64 s[44:45], s[44:45]
	s_cbranch_execz .LBB0_1052
	s_mov_b32 s27, 0x33800000
	s_waitcnt vmcnt(0)
	v_mov_b32_e32 v50, v248
	v_add_f32_e32 v51, v62, v50
	v_min_f32_e32 v50, 0, v51
	v_mul_f32_e64 v51, |v51|, s29
	v_exp_f32_e32 v51, v51
	s_nop 0
	v_add_f32_e32 v72, 1.0, v51
	v_add_f32_e32 v52, -1.0, v72
	v_sub_f32_e32 v53, v52, v72
	v_add_f32_e32 v53, 1.0, v53
	v_sub_f32_e32 v52, v51, v52
	v_add_f32_e32 v73, v52, v53
	v_frexp_mant_f32_e32 v52, v72
	v_cmp_gt_f32_e32 vcc, s50, v52
	v_cvt_f64_f32_e32 v[52:53], v72
	v_frexp_exp_i32_f64_e32 v52, v[52:53]
	v_subbrev_co_u32_e32 v78, vcc, 0, v52, vcc
	v_sub_u32_e32 v52, 0, v78
	v_ldexp_f32 v53, v72, v52
	v_add_f32_e32 v72, -1.0, v53
	v_add_f32_e32 v74, 1.0, v53
	v_ldexp_f32 v52, v73, v52
	v_add_f32_e32 v73, 1.0, v72
	v_add_f32_e32 v75, -1.0, v74
	v_sub_f32_e32 v73, v53, v73
	v_sub_f32_e32 v53, v53, v75
	v_add_f32_e32 v73, v52, v73
	v_add_f32_e32 v52, v52, v53
	v_add_f32_e32 v79, v74, v52
	v_rcp_f32_e32 v81, v79
	v_sub_f32_e32 v53, v79, v74
	v_sub_f32_e32 v80, v52, v53
	v_add_f32_e32 v53, v72, v73
	v_mul_f32_e32 v83, v53, v81
	v_sub_f32_e32 v52, v53, v72
	v_mul_f32_e32 v72, v79, v83
	v_fma_f32 v74, v83, v79, -v72
	v_fmac_f32_e32 v74, v83, v80
	v_sub_f32_e32 v82, v73, v52
	v_add_f32_e32 v52, v72, v74
	v_sub_f32_e32 v73, v53, v52
	v_pk_add_f32 v[76:77], v[52:53], v[72:73] neg_lo:[0,1] neg_hi:[0,1]
	v_mov_b32_e32 v75, v52
	v_pk_add_f32 v[52:53], v[76:77], v[74:75] neg_lo:[0,1] neg_hi:[0,1]
	v_cmp_neq_f32_e32 vcc, s52, v51
	v_add_f32_e32 v53, v82, v53
	v_add_f32_e32 v52, v52, v53
	v_add_f32_e32 v53, v73, v52
	v_mul_f32_e32 v82, v81, v53
	v_mul_f32_e32 v72, v79, v82
	v_fma_f32 v74, v82, v79, -v72
	v_fmac_f32_e32 v74, v82, v80
	v_sub_f32_e32 v73, v73, v53
	v_add_f32_e32 v79, v52, v73
	v_add_f32_e32 v52, v72, v74
	v_sub_f32_e32 v73, v53, v52
	v_pk_add_f32 v[76:77], v[52:53], v[72:73] neg_lo:[0,1] neg_hi:[0,1]
	v_mov_b32_e32 v75, v52
	v_pk_add_f32 v[52:53], v[76:77], v[74:75] neg_lo:[0,1] neg_hi:[0,1]
	s_nop 0
	v_add_f32_e32 v53, v79, v53
	v_add_f32_e32 v52, v52, v53
	v_add_f32_e32 v53, v83, v82
	v_add_f32_e32 v52, v73, v52
	v_sub_f32_e32 v72, v53, v83
	v_mul_f32_e32 v52, v81, v52
	v_sub_f32_e32 v72, v82, v72
	v_add_f32_e32 v72, v72, v52
	v_add_f32_e32 v74, v53, v72
	v_mul_f32_e32 v75, v74, v74
	v_fmamk_f32 v52, v75, 0x3e9b6dac, v233
	v_fmaak_f32 v185, v75, v52, 0x3f2aaada
	v_cvt_f32_i32_e32 v52, v78
	v_sub_f32_e32 v53, v74, v53
	v_sub_f32_e32 v53, v72, v53
	v_ldexp_f32 v76, v53, 1
	v_mul_f32_e32 v53, v74, v75
	v_ldexp_f32 v73, v74, 1
	v_pk_mul_f32 v[74:75], v[52:53], v[184:185]
	s_nop 0
	v_fma_f32 v72, v52, s51, -v74
	v_fmac_f32_e32 v72, 0xb102e308, v52
	v_pk_add_f32 v[52:53], v[74:75], v[72:73]
	s_nop 0
	v_sub_f32_e32 v73, v53, v73
	v_sub_f32_e32 v73, v75, v73
	v_add_f32_e32 v77, v76, v73
	v_mov_b32_e32 v76, v74
	v_pk_add_f32 v[74:75], v[52:53], v[74:75] neg_lo:[0,1] neg_hi:[0,1]
	v_pk_add_f32 v[78:79], v[52:53], v[76:77]
	v_mov_b32_e32 v73, v52
	v_mov_b32_e32 v75, v79
	v_pk_add_f32 v[80:81], v[72:73], v[74:75] neg_lo:[0,1] neg_hi:[0,1]
	v_pk_add_f32 v[72:73], v[72:73], v[74:75]
	v_mov_b32_e32 v76, v77
	v_pk_add_f32 v[74:75], v[72:73], v[52:53] op_sel:[1,0] op_sel_hi:[0,1] neg_lo:[0,1] neg_hi:[0,1]
	v_pk_add_f32 v[82:83], v[78:79], v[74:75] op_sel_hi:[1,0] neg_lo:[0,1] neg_hi:[0,1]
	v_mov_b32_e32 v78, v79
	v_mov_b32_e32 v79, v73
	v_pk_mov_b32 v[74:75], v[52:53], v[74:75] op_sel:[1,0]
	v_mov_b32_e32 v77, v52
	v_pk_add_f32 v[74:75], v[78:79], v[74:75] neg_lo:[0,1] neg_hi:[0,1]
	v_mov_b32_e32 v82, v80
	v_pk_add_f32 v[52:53], v[76:77], v[74:75] neg_lo:[0,1] neg_hi:[0,1]
	v_mov_b32_e32 v81, v73
	v_pk_add_f32 v[74:75], v[82:83], v[52:53]
	s_nop 0
	v_pk_add_f32 v[76:77], v[74:75], v[74:75] op_sel:[0,1] op_sel_hi:[1,0]
	s_nop 0
	v_pk_add_f32 v[72:73], v[72:73], v[76:77] op_sel:[1,0] op_sel_hi:[0,1]
	v_mov_b32_e32 v75, v72
	v_pk_add_f32 v[78:79], v[74:75], v[80:81] neg_lo:[0,1] neg_hi:[0,1]
	v_mov_b32_e32 v53, v76
	v_sub_f32_e32 v73, v74, v78
	v_pk_add_f32 v[52:53], v[52:53], v[78:79] neg_lo:[0,1] neg_hi:[0,1]
	v_sub_f32_e32 v73, v80, v73
	v_add_f32_e32 v52, v52, v73
	v_add_f32_e32 v52, v52, v53
	v_add_f32_e32 v52, v72, v52
	v_cndmask_b32_e32 v52, v226, v52, vcc
	v_cmp_ngt_f32_e32 vcc, -1.0, v51
	s_nop 1
	v_cndmask_b32_e32 v52, v227, v52, vcc
	v_cmp_neq_f32_e32 vcc, -1.0, v51
	s_nop 1
	v_cndmask_b32_e32 v52, v236, v52, vcc
	v_cmp_lt_f32_e64 vcc, |v51|, s27
	s_nop 1
	v_cndmask_b32_e32 v51, v52, v51, vcc
	v_sub_f32_e32 v52, v50, v51

.LBB0_1054:
	s_andn2_saveexec_b64 s[44:45], s[44:45]
	s_cbranch_execz .LBB0_1056
	s_mov_b32 s27, 0x33800000
	s_waitcnt vmcnt(0)
	v_mov_b32_e32 v52, v249
	v_add_f32_e32 v53, v63, v52
	v_min_f32_e32 v52, 0, v53
	v_mul_f32_e64 v53, |v53|, s29
	v_exp_f32_e32 v53, v53
	s_nop 0
	v_add_f32_e32 v74, 1.0, v53
	v_add_f32_e32 v72, -1.0, v74
	v_sub_f32_e32 v73, v72, v74
	v_add_f32_e32 v73, 1.0, v73
	v_sub_f32_e32 v72, v53, v72
	v_add_f32_e32 v75, v72, v73
	v_frexp_mant_f32_e32 v72, v74
	v_cmp_gt_f32_e32 vcc, s50, v72
	v_cvt_f64_f32_e32 v[72:73], v74
	v_frexp_exp_i32_f64_e32 v72, v[72:73]
	v_subbrev_co_u32_e32 v80, vcc, 0, v72, vcc
	v_sub_u32_e32 v72, 0, v80
	v_ldexp_f32 v73, v74, v72
	v_add_f32_e32 v74, -1.0, v73
	v_add_f32_e32 v76, 1.0, v73
	v_ldexp_f32 v72, v75, v72
	v_add_f32_e32 v75, 1.0, v74
	v_add_f32_e32 v77, -1.0, v76
	v_sub_f32_e32 v75, v73, v75
	v_sub_f32_e32 v73, v73, v77
	v_add_f32_e32 v75, v72, v75
	v_add_f32_e32 v72, v72, v73
	v_add_f32_e32 v81, v76, v72
	v_rcp_f32_e32 v83, v81
	v_sub_f32_e32 v73, v81, v76
	v_sub_f32_e32 v82, v72, v73
	v_add_f32_e32 v73, v74, v75
	v_mul_f32_e32 v85, v73, v83
	v_sub_f32_e32 v72, v73, v74
	v_mul_f32_e32 v74, v81, v85
	v_fma_f32 v76, v85, v81, -v74
	v_fmac_f32_e32 v76, v85, v82
	v_sub_f32_e32 v84, v75, v72
	v_add_f32_e32 v72, v74, v76
	v_sub_f32_e32 v75, v73, v72
	v_pk_add_f32 v[78:79], v[72:73], v[74:75] neg_lo:[0,1] neg_hi:[0,1]
	v_mov_b32_e32 v77, v72
	v_pk_add_f32 v[72:73], v[78:79], v[76:77] neg_lo:[0,1] neg_hi:[0,1]
	v_cmp_neq_f32_e32 vcc, s52, v53
	v_add_f32_e32 v73, v84, v73
	v_add_f32_e32 v72, v72, v73
	v_add_f32_e32 v73, v75, v72
	v_mul_f32_e32 v84, v83, v73
	v_mul_f32_e32 v74, v81, v84
	v_fma_f32 v76, v84, v81, -v74
	v_fmac_f32_e32 v76, v84, v82
	v_sub_f32_e32 v75, v75, v73
	v_add_f32_e32 v81, v72, v75
	v_add_f32_e32 v72, v74, v76
	v_sub_f32_e32 v75, v73, v72
	v_pk_add_f32 v[78:79], v[72:73], v[74:75] neg_lo:[0,1] neg_hi:[0,1]
	v_mov_b32_e32 v77, v72
	v_pk_add_f32 v[72:73], v[78:79], v[76:77] neg_lo:[0,1] neg_hi:[0,1]
	s_nop 0
	v_add_f32_e32 v73, v81, v73
	v_add_f32_e32 v72, v72, v73
	v_add_f32_e32 v73, v85, v84
	v_add_f32_e32 v72, v75, v72
	v_sub_f32_e32 v74, v73, v85
	v_mul_f32_e32 v72, v83, v72
	v_sub_f32_e32 v74, v84, v74
	v_add_f32_e32 v74, v74, v72
	v_add_f32_e32 v76, v73, v74
	v_mul_f32_e32 v77, v76, v76
	v_fmamk_f32 v72, v77, 0x3e9b6dac, v233
	v_fmaak_f32 v185, v77, v72, 0x3f2aaada
	v_cvt_f32_i32_e32 v72, v80
	v_sub_f32_e32 v73, v76, v73
	v_sub_f32_e32 v73, v74, v73
	v_ldexp_f32 v78, v73, 1
	v_mul_f32_e32 v73, v76, v77
	v_ldexp_f32 v75, v76, 1
	v_pk_mul_f32 v[76:77], v[72:73], v[184:185]
	s_nop 0
	v_fma_f32 v74, v72, s51, -v76
	v_fmac_f32_e32 v74, 0xb102e308, v72
	v_pk_add_f32 v[72:73], v[76:77], v[74:75]
	s_nop 0
	v_sub_f32_e32 v75, v73, v75
	v_sub_f32_e32 v75, v77, v75
	v_add_f32_e32 v79, v78, v75
	v_mov_b32_e32 v78, v76
	v_pk_add_f32 v[76:77], v[72:73], v[76:77] neg_lo:[0,1] neg_hi:[0,1]
	v_pk_add_f32 v[80:81], v[72:73], v[78:79]
	v_mov_b32_e32 v75, v72
	v_mov_b32_e32 v77, v81
	v_pk_add_f32 v[82:83], v[74:75], v[76:77] neg_lo:[0,1] neg_hi:[0,1]
	v_pk_add_f32 v[74:75], v[74:75], v[76:77]
	v_mov_b32_e32 v78, v79
	v_pk_add_f32 v[76:77], v[74:75], v[72:73] op_sel:[1,0] op_sel_hi:[0,1] neg_lo:[0,1] neg_hi:[0,1]
	v_pk_add_f32 v[84:85], v[80:81], v[76:77] op_sel_hi:[1,0] neg_lo:[0,1] neg_hi:[0,1]
	v_mov_b32_e32 v80, v81
	v_mov_b32_e32 v81, v75
	v_pk_mov_b32 v[76:77], v[72:73], v[76:77] op_sel:[1,0]
	v_mov_b32_e32 v79, v72
	v_pk_add_f32 v[76:77], v[80:81], v[76:77] neg_lo:[0,1] neg_hi:[0,1]
	v_mov_b32_e32 v84, v82
	v_pk_add_f32 v[72:73], v[78:79], v[76:77] neg_lo:[0,1] neg_hi:[0,1]
	v_mov_b32_e32 v83, v75
	v_pk_add_f32 v[76:77], v[84:85], v[72:73]
	s_nop 0
	v_pk_add_f32 v[78:79], v[76:77], v[76:77] op_sel:[0,1] op_sel_hi:[1,0]
	s_nop 0
	v_pk_add_f32 v[74:75], v[74:75], v[78:79] op_sel:[1,0] op_sel_hi:[0,1]
	v_mov_b32_e32 v77, v74
	v_pk_add_f32 v[80:81], v[76:77], v[82:83] neg_lo:[0,1] neg_hi:[0,1]
	v_mov_b32_e32 v73, v78
	v_sub_f32_e32 v75, v76, v80
	v_pk_add_f32 v[72:73], v[72:73], v[80:81] neg_lo:[0,1] neg_hi:[0,1]
	v_sub_f32_e32 v75, v82, v75
	v_add_f32_e32 v72, v72, v75
	v_add_f32_e32 v72, v72, v73
	v_add_f32_e32 v72, v74, v72
	v_cndmask_b32_e32 v72, v226, v72, vcc
	v_cmp_ngt_f32_e32 vcc, -1.0, v53
	s_nop 1
	v_cndmask_b32_e32 v72, v227, v72, vcc
	v_cmp_neq_f32_e32 vcc, -1.0, v53
	s_nop 1
	v_cndmask_b32_e32 v72, v236, v72, vcc
	v_cmp_lt_f32_e64 vcc, |v53|, s27
	s_nop 1
	v_cndmask_b32_e32 v53, v72, v53, vcc
	v_sub_f32_e32 v52, v52, v53

.LBB0_1058:
	s_andn2_saveexec_b64 s[44:45], s[44:45]
	s_cbranch_execz .LBB0_1060
	s_mov_b32 s27, 0x33800000
	s_waitcnt vmcnt(0)
	v_mov_b32_e32 v50, v250
	v_add_f32_e32 v51, v68, v50
	v_min_f32_e32 v50, 0, v51
	v_mul_f32_e64 v51, |v51|, s29
	v_exp_f32_e32 v51, v51
	s_nop 0
	v_add_f32_e32 v74, 1.0, v51
	v_add_f32_e32 v52, -1.0, v74
	v_sub_f32_e32 v53, v52, v74
	v_add_f32_e32 v53, 1.0, v53
	v_sub_f32_e32 v52, v51, v52
	v_add_f32_e32 v75, v52, v53
	v_frexp_mant_f32_e32 v52, v74
	v_cmp_gt_f32_e32 vcc, s50, v52
	v_cvt_f64_f32_e32 v[52:53], v74
	v_frexp_exp_i32_f64_e32 v52, v[52:53]
	v_subbrev_co_u32_e32 v80, vcc, 0, v52, vcc
	v_sub_u32_e32 v52, 0, v80
	v_ldexp_f32 v53, v74, v52
	v_add_f32_e32 v74, -1.0, v53
	v_add_f32_e32 v76, 1.0, v53
	v_ldexp_f32 v52, v75, v52
	v_add_f32_e32 v75, 1.0, v74
	v_add_f32_e32 v77, -1.0, v76
	v_sub_f32_e32 v75, v53, v75
	v_sub_f32_e32 v53, v53, v77
	v_add_f32_e32 v75, v52, v75
	v_add_f32_e32 v52, v52, v53
	v_add_f32_e32 v81, v76, v52
	v_rcp_f32_e32 v83, v81
	v_sub_f32_e32 v53, v81, v76
	v_sub_f32_e32 v82, v52, v53
	v_add_f32_e32 v53, v74, v75
	v_mul_f32_e32 v85, v53, v83
	v_sub_f32_e32 v52, v53, v74
	v_mul_f32_e32 v74, v81, v85
	v_fma_f32 v76, v85, v81, -v74
	v_fmac_f32_e32 v76, v85, v82
	v_sub_f32_e32 v84, v75, v52
	v_add_f32_e32 v52, v74, v76
	v_sub_f32_e32 v75, v53, v52
	v_pk_add_f32 v[78:79], v[52:53], v[74:75] neg_lo:[0,1] neg_hi:[0,1]
	v_mov_b32_e32 v77, v52
	v_pk_add_f32 v[52:53], v[78:79], v[76:77] neg_lo:[0,1] neg_hi:[0,1]
	v_cmp_neq_f32_e32 vcc, s52, v51
	v_add_f32_e32 v53, v84, v53
	v_add_f32_e32 v52, v52, v53
	v_add_f32_e32 v53, v75, v52
	v_mul_f32_e32 v84, v83, v53
	v_mul_f32_e32 v74, v81, v84
	v_fma_f32 v76, v84, v81, -v74
	v_fmac_f32_e32 v76, v84, v82
	v_sub_f32_e32 v75, v75, v53
	v_add_f32_e32 v81, v52, v75
	v_add_f32_e32 v52, v74, v76
	v_sub_f32_e32 v75, v53, v52
	v_pk_add_f32 v[78:79], v[52:53], v[74:75] neg_lo:[0,1] neg_hi:[0,1]
	v_mov_b32_e32 v77, v52
	v_pk_add_f32 v[52:53], v[78:79], v[76:77] neg_lo:[0,1] neg_hi:[0,1]
	s_nop 0
	v_add_f32_e32 v53, v81, v53
	v_add_f32_e32 v52, v52, v53
	v_add_f32_e32 v53, v85, v84
	v_add_f32_e32 v52, v75, v52
	v_sub_f32_e32 v74, v53, v85
	v_mul_f32_e32 v52, v83, v52
	v_sub_f32_e32 v74, v84, v74
	v_add_f32_e32 v74, v74, v52
	v_add_f32_e32 v76, v53, v74
	v_mul_f32_e32 v77, v76, v76
	v_fmamk_f32 v52, v77, 0x3e9b6dac, v233
	v_fmaak_f32 v185, v77, v52, 0x3f2aaada
	v_cvt_f32_i32_e32 v52, v80
	v_sub_f32_e32 v53, v76, v53
	v_sub_f32_e32 v53, v74, v53
	v_ldexp_f32 v78, v53, 1
	v_mul_f32_e32 v53, v76, v77
	v_ldexp_f32 v75, v76, 1
	v_pk_mul_f32 v[76:77], v[52:53], v[184:185]
	s_nop 0
	v_fma_f32 v74, v52, s51, -v76
	v_fmac_f32_e32 v74, 0xb102e308, v52
	v_pk_add_f32 v[52:53], v[76:77], v[74:75]
	s_nop 0
	v_sub_f32_e32 v75, v53, v75
	v_sub_f32_e32 v75, v77, v75
	v_add_f32_e32 v79, v78, v75
	v_mov_b32_e32 v78, v76
	v_pk_add_f32 v[76:77], v[52:53], v[76:77] neg_lo:[0,1] neg_hi:[0,1]
	v_pk_add_f32 v[80:81], v[52:53], v[78:79]
	v_mov_b32_e32 v75, v52
	v_mov_b32_e32 v77, v81
	v_pk_add_f32 v[82:83], v[74:75], v[76:77] neg_lo:[0,1] neg_hi:[0,1]
	v_pk_add_f32 v[74:75], v[74:75], v[76:77]
	v_mov_b32_e32 v78, v79
	v_pk_add_f32 v[76:77], v[74:75], v[52:53] op_sel:[1,0] op_sel_hi:[0,1] neg_lo:[0,1] neg_hi:[0,1]
	v_pk_add_f32 v[84:85], v[80:81], v[76:77] op_sel_hi:[1,0] neg_lo:[0,1] neg_hi:[0,1]
	v_mov_b32_e32 v80, v81
	v_mov_b32_e32 v81, v75
	v_pk_mov_b32 v[76:77], v[52:53], v[76:77] op_sel:[1,0]
	v_mov_b32_e32 v79, v52
	v_pk_add_f32 v[76:77], v[80:81], v[76:77] neg_lo:[0,1] neg_hi:[0,1]
	v_mov_b32_e32 v84, v82
	v_pk_add_f32 v[52:53], v[78:79], v[76:77] neg_lo:[0,1] neg_hi:[0,1]
	v_mov_b32_e32 v83, v75
	v_pk_add_f32 v[76:77], v[84:85], v[52:53]
	s_nop 0
	v_pk_add_f32 v[78:79], v[76:77], v[76:77] op_sel:[0,1] op_sel_hi:[1,0]
	s_nop 0
	v_pk_add_f32 v[74:75], v[74:75], v[78:79] op_sel:[1,0] op_sel_hi:[0,1]
	v_mov_b32_e32 v77, v74
	v_pk_add_f32 v[80:81], v[76:77], v[82:83] neg_lo:[0,1] neg_hi:[0,1]
	v_mov_b32_e32 v53, v78
	v_sub_f32_e32 v75, v76, v80
	v_pk_add_f32 v[52:53], v[52:53], v[80:81] neg_lo:[0,1] neg_hi:[0,1]
	v_sub_f32_e32 v75, v82, v75
	v_add_f32_e32 v52, v52, v75
	v_add_f32_e32 v52, v52, v53
	v_add_f32_e32 v52, v74, v52
	v_cndmask_b32_e32 v52, v226, v52, vcc
	v_cmp_ngt_f32_e32 vcc, -1.0, v51
	s_nop 1
	v_cndmask_b32_e32 v52, v227, v52, vcc
	v_cmp_neq_f32_e32 vcc, -1.0, v51
	s_nop 1
	v_cndmask_b32_e32 v52, v236, v52, vcc
	v_cmp_lt_f32_e64 vcc, |v51|, s27
	s_nop 1
	v_cndmask_b32_e32 v51, v52, v51, vcc
	v_sub_f32_e32 v50, v50, v51

.LBB0_1062:
	s_andn2_saveexec_b64 s[44:45], s[44:45]
	s_cbranch_execz .LBB0_1064
	s_mov_b32 s27, 0x33800000
	s_waitcnt vmcnt(0)
	v_mov_b32_e32 v50, v251
	v_add_f32_e32 v51, v69, v50
	v_min_f32_e32 v50, 0, v51
	v_mul_f32_e64 v51, |v51|, s29
	v_exp_f32_e32 v51, v51
	s_nop 0
	v_add_f32_e32 v74, 1.0, v51
	v_add_f32_e32 v52, -1.0, v74
	v_sub_f32_e32 v53, v52, v74
	v_add_f32_e32 v53, 1.0, v53
	v_sub_f32_e32 v52, v51, v52
	v_add_f32_e32 v75, v52, v53
	v_frexp_mant_f32_e32 v52, v74
	v_cmp_gt_f32_e32 vcc, s50, v52
	v_cvt_f64_f32_e32 v[52:53], v74
	v_frexp_exp_i32_f64_e32 v52, v[52:53]
	v_subbrev_co_u32_e32 v80, vcc, 0, v52, vcc
	v_sub_u32_e32 v52, 0, v80
	v_ldexp_f32 v53, v74, v52
	v_add_f32_e32 v74, -1.0, v53
	v_add_f32_e32 v76, 1.0, v53
	v_ldexp_f32 v52, v75, v52
	v_add_f32_e32 v75, 1.0, v74
	v_add_f32_e32 v77, -1.0, v76
	v_sub_f32_e32 v75, v53, v75
	v_sub_f32_e32 v53, v53, v77
	v_add_f32_e32 v75, v52, v75
	v_add_f32_e32 v52, v52, v53
	v_add_f32_e32 v81, v76, v52
	v_rcp_f32_e32 v83, v81
	v_sub_f32_e32 v53, v81, v76
	v_sub_f32_e32 v82, v52, v53
	v_add_f32_e32 v53, v74, v75
	v_mul_f32_e32 v85, v53, v83
	v_sub_f32_e32 v52, v53, v74
	v_mul_f32_e32 v74, v81, v85
	v_fma_f32 v76, v85, v81, -v74
	v_fmac_f32_e32 v76, v85, v82
	v_sub_f32_e32 v84, v75, v52
	v_add_f32_e32 v52, v74, v76
	v_sub_f32_e32 v75, v53, v52
	v_pk_add_f32 v[78:79], v[52:53], v[74:75] neg_lo:[0,1] neg_hi:[0,1]
	v_mov_b32_e32 v77, v52
	v_pk_add_f32 v[52:53], v[78:79], v[76:77] neg_lo:[0,1] neg_hi:[0,1]
	v_cmp_neq_f32_e32 vcc, s52, v51
	v_add_f32_e32 v53, v84, v53
	v_add_f32_e32 v52, v52, v53
	v_add_f32_e32 v53, v75, v52
	v_mul_f32_e32 v84, v83, v53
	v_mul_f32_e32 v74, v81, v84
	v_fma_f32 v76, v84, v81, -v74
	v_fmac_f32_e32 v76, v84, v82
	v_sub_f32_e32 v75, v75, v53
	v_add_f32_e32 v81, v52, v75
	v_add_f32_e32 v52, v74, v76
	v_sub_f32_e32 v75, v53, v52
	v_pk_add_f32 v[78:79], v[52:53], v[74:75] neg_lo:[0,1] neg_hi:[0,1]
	v_mov_b32_e32 v77, v52
	v_pk_add_f32 v[52:53], v[78:79], v[76:77] neg_lo:[0,1] neg_hi:[0,1]
	s_nop 0
	v_add_f32_e32 v53, v81, v53
	v_add_f32_e32 v52, v52, v53
	v_add_f32_e32 v53, v85, v84
	v_add_f32_e32 v52, v75, v52
	v_sub_f32_e32 v74, v53, v85
	v_mul_f32_e32 v52, v83, v52
	v_sub_f32_e32 v74, v84, v74
	v_add_f32_e32 v74, v74, v52
	v_add_f32_e32 v76, v53, v74
	v_mul_f32_e32 v77, v76, v76
	v_fmamk_f32 v52, v77, 0x3e9b6dac, v233
	v_fmaak_f32 v185, v77, v52, 0x3f2aaada
	v_cvt_f32_i32_e32 v52, v80
	v_sub_f32_e32 v53, v76, v53
	v_sub_f32_e32 v53, v74, v53
	v_ldexp_f32 v78, v53, 1
	v_mul_f32_e32 v53, v76, v77
	v_ldexp_f32 v75, v76, 1
	v_pk_mul_f32 v[76:77], v[52:53], v[184:185]
	s_nop 0
	v_fma_f32 v74, v52, s51, -v76
	v_fmac_f32_e32 v74, 0xb102e308, v52
	v_pk_add_f32 v[52:53], v[76:77], v[74:75]
	s_nop 0
	v_sub_f32_e32 v75, v53, v75
	v_sub_f32_e32 v75, v77, v75
	v_add_f32_e32 v79, v78, v75
	v_mov_b32_e32 v78, v76
	v_pk_add_f32 v[76:77], v[52:53], v[76:77] neg_lo:[0,1] neg_hi:[0,1]
	v_pk_add_f32 v[80:81], v[52:53], v[78:79]
	v_mov_b32_e32 v75, v52
	v_mov_b32_e32 v77, v81
	v_pk_add_f32 v[82:83], v[74:75], v[76:77] neg_lo:[0,1] neg_hi:[0,1]
	v_pk_add_f32 v[74:75], v[74:75], v[76:77]
	v_mov_b32_e32 v78, v79
	v_pk_add_f32 v[76:77], v[74:75], v[52:53] op_sel:[1,0] op_sel_hi:[0,1] neg_lo:[0,1] neg_hi:[0,1]
	v_pk_add_f32 v[84:85], v[80:81], v[76:77] op_sel_hi:[1,0] neg_lo:[0,1] neg_hi:[0,1]
	v_mov_b32_e32 v80, v81
	v_mov_b32_e32 v81, v75
	v_pk_mov_b32 v[76:77], v[52:53], v[76:77] op_sel:[1,0]
	v_mov_b32_e32 v79, v52
	v_pk_add_f32 v[76:77], v[80:81], v[76:77] neg_lo:[0,1] neg_hi:[0,1]
	v_mov_b32_e32 v84, v82
	v_pk_add_f32 v[52:53], v[78:79], v[76:77] neg_lo:[0,1] neg_hi:[0,1]
	v_mov_b32_e32 v83, v75
	v_pk_add_f32 v[76:77], v[84:85], v[52:53]
	s_nop 0
	v_pk_add_f32 v[78:79], v[76:77], v[76:77] op_sel:[0,1] op_sel_hi:[1,0]
	s_nop 0
	v_pk_add_f32 v[74:75], v[74:75], v[78:79] op_sel:[1,0] op_sel_hi:[0,1]
	v_mov_b32_e32 v77, v74
	v_pk_add_f32 v[80:81], v[76:77], v[82:83] neg_lo:[0,1] neg_hi:[0,1]
	v_mov_b32_e32 v53, v78
	v_sub_f32_e32 v75, v76, v80
	v_pk_add_f32 v[52:53], v[52:53], v[80:81] neg_lo:[0,1] neg_hi:[0,1]
	v_sub_f32_e32 v75, v82, v75
	v_add_f32_e32 v52, v52, v75
	v_add_f32_e32 v52, v52, v53
	v_add_f32_e32 v52, v74, v52
	v_cndmask_b32_e32 v52, v226, v52, vcc
	v_cmp_ngt_f32_e32 vcc, -1.0, v51
	s_nop 1
	v_cndmask_b32_e32 v52, v227, v52, vcc
	v_cmp_neq_f32_e32 vcc, -1.0, v51
	s_nop 1
	v_cndmask_b32_e32 v52, v236, v52, vcc
	v_cmp_lt_f32_e64 vcc, |v51|, s27
	s_nop 1
	v_cndmask_b32_e32 v51, v52, v51, vcc
	v_sub_f32_e32 v50, v50, v51

.LBB0_1076:
	s_andn2_saveexec_b64 s[44:45], s[44:45]
	s_cbranch_execz .LBB0_1078
	s_mov_b32 s27, 0x33800000
	s_waitcnt vmcnt(0)
	v_mov_b32_e32 v34, v248
	v_add_f32_e32 v35, v46, v34
	v_min_f32_e32 v34, 0, v35
	v_mul_f32_e64 v35, |v35|, s29
	v_exp_f32_e32 v35, v35
	s_nop 0
	v_add_f32_e32 v56, 1.0, v35
	v_add_f32_e32 v36, -1.0, v56
	v_sub_f32_e32 v37, v36, v56
	v_add_f32_e32 v37, 1.0, v37
	v_sub_f32_e32 v36, v35, v36
	v_add_f32_e32 v57, v36, v37
	v_frexp_mant_f32_e32 v36, v56
	v_cmp_gt_f32_e32 vcc, s50, v36
	v_cvt_f64_f32_e32 v[36:37], v56
	v_frexp_exp_i32_f64_e32 v36, v[36:37]
	v_subbrev_co_u32_e32 v62, vcc, 0, v36, vcc
	v_sub_u32_e32 v36, 0, v62
	v_ldexp_f32 v37, v56, v36
	v_add_f32_e32 v56, -1.0, v37
	v_add_f32_e32 v58, 1.0, v37
	v_ldexp_f32 v36, v57, v36
	v_add_f32_e32 v57, 1.0, v56
	v_add_f32_e32 v59, -1.0, v58
	v_sub_f32_e32 v57, v37, v57
	v_sub_f32_e32 v37, v37, v59
	v_add_f32_e32 v57, v36, v57
	v_add_f32_e32 v36, v36, v37
	v_add_f32_e32 v63, v58, v36
	v_rcp_f32_e32 v65, v63
	v_sub_f32_e32 v37, v63, v58
	v_sub_f32_e32 v64, v36, v37
	v_add_f32_e32 v37, v56, v57
	v_mul_f32_e32 v67, v37, v65
	v_sub_f32_e32 v36, v37, v56
	v_mul_f32_e32 v56, v63, v67
	v_fma_f32 v58, v67, v63, -v56
	v_fmac_f32_e32 v58, v67, v64
	v_sub_f32_e32 v66, v57, v36
	v_add_f32_e32 v36, v56, v58
	v_sub_f32_e32 v57, v37, v36
	v_pk_add_f32 v[60:61], v[36:37], v[56:57] neg_lo:[0,1] neg_hi:[0,1]
	v_mov_b32_e32 v59, v36
	v_pk_add_f32 v[36:37], v[60:61], v[58:59] neg_lo:[0,1] neg_hi:[0,1]
	v_cmp_neq_f32_e32 vcc, s52, v35
	v_add_f32_e32 v37, v66, v37
	v_add_f32_e32 v36, v36, v37
	v_add_f32_e32 v37, v57, v36
	v_mul_f32_e32 v66, v65, v37
	v_mul_f32_e32 v56, v63, v66
	v_fma_f32 v58, v66, v63, -v56
	v_fmac_f32_e32 v58, v66, v64
	v_sub_f32_e32 v57, v57, v37
	v_add_f32_e32 v63, v36, v57
	v_add_f32_e32 v36, v56, v58
	v_sub_f32_e32 v57, v37, v36
	v_pk_add_f32 v[60:61], v[36:37], v[56:57] neg_lo:[0,1] neg_hi:[0,1]
	v_mov_b32_e32 v59, v36
	v_pk_add_f32 v[36:37], v[60:61], v[58:59] neg_lo:[0,1] neg_hi:[0,1]
	s_nop 0
	v_add_f32_e32 v37, v63, v37
	v_add_f32_e32 v36, v36, v37
	v_add_f32_e32 v37, v67, v66
	v_add_f32_e32 v36, v57, v36
	v_sub_f32_e32 v56, v37, v67
	v_mul_f32_e32 v36, v65, v36
	v_sub_f32_e32 v56, v66, v56
	v_add_f32_e32 v56, v56, v36
	v_add_f32_e32 v58, v37, v56
	v_mul_f32_e32 v59, v58, v58
	v_fmamk_f32 v36, v59, 0x3e9b6dac, v233
	v_fmaak_f32 v185, v59, v36, 0x3f2aaada
	v_cvt_f32_i32_e32 v36, v62
	v_sub_f32_e32 v37, v58, v37
	v_sub_f32_e32 v37, v56, v37
	v_ldexp_f32 v60, v37, 1
	v_mul_f32_e32 v37, v58, v59
	v_ldexp_f32 v57, v58, 1
	v_pk_mul_f32 v[58:59], v[36:37], v[184:185]
	s_nop 0
	v_fma_f32 v56, v36, s51, -v58
	v_fmac_f32_e32 v56, 0xb102e308, v36
	v_pk_add_f32 v[36:37], v[58:59], v[56:57]
	s_nop 0
	v_sub_f32_e32 v57, v37, v57
	v_sub_f32_e32 v57, v59, v57
	v_add_f32_e32 v61, v60, v57
	v_mov_b32_e32 v60, v58
	v_pk_add_f32 v[58:59], v[36:37], v[58:59] neg_lo:[0,1] neg_hi:[0,1]
	v_pk_add_f32 v[62:63], v[36:37], v[60:61]
	v_mov_b32_e32 v57, v36
	v_mov_b32_e32 v59, v63
	v_pk_add_f32 v[64:65], v[56:57], v[58:59] neg_lo:[0,1] neg_hi:[0,1]
	v_pk_add_f32 v[56:57], v[56:57], v[58:59]
	v_mov_b32_e32 v60, v61
	v_pk_add_f32 v[58:59], v[56:57], v[36:37] op_sel:[1,0] op_sel_hi:[0,1] neg_lo:[0,1] neg_hi:[0,1]
	v_pk_add_f32 v[66:67], v[62:63], v[58:59] op_sel_hi:[1,0] neg_lo:[0,1] neg_hi:[0,1]
	v_mov_b32_e32 v62, v63
	v_mov_b32_e32 v63, v57
	v_pk_mov_b32 v[58:59], v[36:37], v[58:59] op_sel:[1,0]
	v_mov_b32_e32 v61, v36
	v_pk_add_f32 v[58:59], v[62:63], v[58:59] neg_lo:[0,1] neg_hi:[0,1]
	v_mov_b32_e32 v66, v64
	v_pk_add_f32 v[36:37], v[60:61], v[58:59] neg_lo:[0,1] neg_hi:[0,1]
	v_mov_b32_e32 v65, v57
	v_pk_add_f32 v[58:59], v[66:67], v[36:37]
	s_nop 0
	v_pk_add_f32 v[60:61], v[58:59], v[58:59] op_sel:[0,1] op_sel_hi:[1,0]
	s_nop 0
	v_pk_add_f32 v[56:57], v[56:57], v[60:61] op_sel:[1,0] op_sel_hi:[0,1]
	v_mov_b32_e32 v59, v56
	v_pk_add_f32 v[62:63], v[58:59], v[64:65] neg_lo:[0,1] neg_hi:[0,1]
	v_mov_b32_e32 v37, v60
	v_sub_f32_e32 v57, v58, v62
	v_pk_add_f32 v[36:37], v[36:37], v[62:63] neg_lo:[0,1] neg_hi:[0,1]
	v_sub_f32_e32 v57, v64, v57
	v_add_f32_e32 v36, v36, v57
	v_add_f32_e32 v36, v36, v37
	v_add_f32_e32 v36, v56, v36
	v_cndmask_b32_e32 v36, v226, v36, vcc
	v_cmp_ngt_f32_e32 vcc, -1.0, v35
	s_nop 1
	v_cndmask_b32_e32 v36, v227, v36, vcc
	v_cmp_neq_f32_e32 vcc, -1.0, v35
	s_nop 1
	v_cndmask_b32_e32 v36, v236, v36, vcc
	v_cmp_lt_f32_e64 vcc, |v35|, s27
	s_nop 1
	v_cndmask_b32_e32 v35, v36, v35, vcc
	v_sub_f32_e32 v36, v34, v35

.LBB0_1080:
	s_andn2_saveexec_b64 s[44:45], s[44:45]
	s_cbranch_execz .LBB0_1082
	s_mov_b32 s27, 0x33800000
	s_waitcnt vmcnt(0)
	v_mov_b32_e32 v36, v249
	v_add_f32_e32 v37, v47, v36
	v_min_f32_e32 v36, 0, v37
	v_mul_f32_e64 v37, |v37|, s29
	v_exp_f32_e32 v37, v37
	s_nop 0
	v_add_f32_e32 v58, 1.0, v37
	v_add_f32_e32 v56, -1.0, v58
	v_sub_f32_e32 v57, v56, v58
	v_add_f32_e32 v57, 1.0, v57
	v_sub_f32_e32 v56, v37, v56
	v_add_f32_e32 v59, v56, v57
	v_frexp_mant_f32_e32 v56, v58
	v_cmp_gt_f32_e32 vcc, s50, v56
	v_cvt_f64_f32_e32 v[56:57], v58
	v_frexp_exp_i32_f64_e32 v56, v[56:57]
	v_subbrev_co_u32_e32 v64, vcc, 0, v56, vcc
	v_sub_u32_e32 v56, 0, v64
	v_ldexp_f32 v57, v58, v56
	v_add_f32_e32 v58, -1.0, v57
	v_add_f32_e32 v60, 1.0, v57
	v_ldexp_f32 v56, v59, v56
	v_add_f32_e32 v59, 1.0, v58
	v_add_f32_e32 v61, -1.0, v60
	v_sub_f32_e32 v59, v57, v59
	v_sub_f32_e32 v57, v57, v61
	v_add_f32_e32 v59, v56, v59
	v_add_f32_e32 v56, v56, v57
	v_add_f32_e32 v65, v60, v56
	v_rcp_f32_e32 v67, v65
	v_sub_f32_e32 v57, v65, v60
	v_sub_f32_e32 v66, v56, v57
	v_add_f32_e32 v57, v58, v59
	v_mul_f32_e32 v69, v57, v67
	v_sub_f32_e32 v56, v57, v58
	v_mul_f32_e32 v58, v65, v69
	v_fma_f32 v60, v69, v65, -v58
	v_fmac_f32_e32 v60, v69, v66
	v_sub_f32_e32 v68, v59, v56
	v_add_f32_e32 v56, v58, v60
	v_sub_f32_e32 v59, v57, v56
	v_pk_add_f32 v[62:63], v[56:57], v[58:59] neg_lo:[0,1] neg_hi:[0,1]
	v_mov_b32_e32 v61, v56
	v_pk_add_f32 v[56:57], v[62:63], v[60:61] neg_lo:[0,1] neg_hi:[0,1]
	v_cmp_neq_f32_e32 vcc, s52, v37
	v_add_f32_e32 v57, v68, v57
	v_add_f32_e32 v56, v56, v57
	v_add_f32_e32 v57, v59, v56
	v_mul_f32_e32 v68, v67, v57
	v_mul_f32_e32 v58, v65, v68
	v_fma_f32 v60, v68, v65, -v58
	v_fmac_f32_e32 v60, v68, v66
	v_sub_f32_e32 v59, v59, v57
	v_add_f32_e32 v65, v56, v59
	v_add_f32_e32 v56, v58, v60
	v_sub_f32_e32 v59, v57, v56
	v_pk_add_f32 v[62:63], v[56:57], v[58:59] neg_lo:[0,1] neg_hi:[0,1]
	v_mov_b32_e32 v61, v56
	v_pk_add_f32 v[56:57], v[62:63], v[60:61] neg_lo:[0,1] neg_hi:[0,1]
	s_nop 0
	v_add_f32_e32 v57, v65, v57
	v_add_f32_e32 v56, v56, v57
	v_add_f32_e32 v57, v69, v68
	v_add_f32_e32 v56, v59, v56
	v_sub_f32_e32 v58, v57, v69
	v_mul_f32_e32 v56, v67, v56
	v_sub_f32_e32 v58, v68, v58
	v_add_f32_e32 v58, v58, v56
	v_add_f32_e32 v60, v57, v58
	v_mul_f32_e32 v61, v60, v60
	v_fmamk_f32 v56, v61, 0x3e9b6dac, v233
	v_fmaak_f32 v185, v61, v56, 0x3f2aaada
	v_cvt_f32_i32_e32 v56, v64
	v_sub_f32_e32 v57, v60, v57
	v_sub_f32_e32 v57, v58, v57
	v_ldexp_f32 v62, v57, 1
	v_mul_f32_e32 v57, v60, v61
	v_ldexp_f32 v59, v60, 1
	v_pk_mul_f32 v[60:61], v[56:57], v[184:185]
	s_nop 0
	v_fma_f32 v58, v56, s51, -v60
	v_fmac_f32_e32 v58, 0xb102e308, v56
	v_pk_add_f32 v[56:57], v[60:61], v[58:59]
	s_nop 0
	v_sub_f32_e32 v59, v57, v59
	v_sub_f32_e32 v59, v61, v59
	v_add_f32_e32 v63, v62, v59
	v_mov_b32_e32 v62, v60
	v_pk_add_f32 v[60:61], v[56:57], v[60:61] neg_lo:[0,1] neg_hi:[0,1]
	v_pk_add_f32 v[64:65], v[56:57], v[62:63]
	v_mov_b32_e32 v59, v56
	v_mov_b32_e32 v61, v65
	v_pk_add_f32 v[66:67], v[58:59], v[60:61] neg_lo:[0,1] neg_hi:[0,1]
	v_pk_add_f32 v[58:59], v[58:59], v[60:61]
	v_mov_b32_e32 v62, v63
	v_pk_add_f32 v[60:61], v[58:59], v[56:57] op_sel:[1,0] op_sel_hi:[0,1] neg_lo:[0,1] neg_hi:[0,1]
	v_pk_add_f32 v[68:69], v[64:65], v[60:61] op_sel_hi:[1,0] neg_lo:[0,1] neg_hi:[0,1]
	v_mov_b32_e32 v64, v65
	v_mov_b32_e32 v65, v59
	v_pk_mov_b32 v[60:61], v[56:57], v[60:61] op_sel:[1,0]
	v_mov_b32_e32 v63, v56
	v_pk_add_f32 v[60:61], v[64:65], v[60:61] neg_lo:[0,1] neg_hi:[0,1]
	v_mov_b32_e32 v68, v66
	v_pk_add_f32 v[56:57], v[62:63], v[60:61] neg_lo:[0,1] neg_hi:[0,1]
	v_mov_b32_e32 v67, v59
	v_pk_add_f32 v[60:61], v[68:69], v[56:57]
	s_nop 0
	v_pk_add_f32 v[62:63], v[60:61], v[60:61] op_sel:[0,1] op_sel_hi:[1,0]
	s_nop 0
	v_pk_add_f32 v[58:59], v[58:59], v[62:63] op_sel:[1,0] op_sel_hi:[0,1]
	v_mov_b32_e32 v61, v58
	v_pk_add_f32 v[64:65], v[60:61], v[66:67] neg_lo:[0,1] neg_hi:[0,1]
	v_mov_b32_e32 v57, v62
	v_sub_f32_e32 v59, v60, v64
	v_pk_add_f32 v[56:57], v[56:57], v[64:65] neg_lo:[0,1] neg_hi:[0,1]
	v_sub_f32_e32 v59, v66, v59
	v_add_f32_e32 v56, v56, v59
	v_add_f32_e32 v56, v56, v57
	v_add_f32_e32 v56, v58, v56
	v_cndmask_b32_e32 v56, v226, v56, vcc
	v_cmp_ngt_f32_e32 vcc, -1.0, v37
	s_nop 1
	v_cndmask_b32_e32 v56, v227, v56, vcc
	v_cmp_neq_f32_e32 vcc, -1.0, v37
	s_nop 1
	v_cndmask_b32_e32 v56, v236, v56, vcc
	v_cmp_lt_f32_e64 vcc, |v37|, s27
	s_nop 1
	v_cndmask_b32_e32 v37, v56, v37, vcc
	v_sub_f32_e32 v36, v36, v37

.LBB0_1084:
	s_andn2_saveexec_b64 s[44:45], s[44:45]
	s_cbranch_execz .LBB0_1086
	s_mov_b32 s27, 0x33800000
	s_waitcnt vmcnt(0)
	v_mov_b32_e32 v34, v250
	v_add_f32_e32 v35, v52, v34
	v_min_f32_e32 v34, 0, v35
	v_mul_f32_e64 v35, |v35|, s29
	v_exp_f32_e32 v35, v35
	s_nop 0
	v_add_f32_e32 v58, 1.0, v35
	v_add_f32_e32 v36, -1.0, v58
	v_sub_f32_e32 v37, v36, v58
	v_add_f32_e32 v37, 1.0, v37
	v_sub_f32_e32 v36, v35, v36
	v_add_f32_e32 v59, v36, v37
	v_frexp_mant_f32_e32 v36, v58
	v_cmp_gt_f32_e32 vcc, s50, v36
	v_cvt_f64_f32_e32 v[36:37], v58
	v_frexp_exp_i32_f64_e32 v36, v[36:37]
	v_subbrev_co_u32_e32 v64, vcc, 0, v36, vcc
	v_sub_u32_e32 v36, 0, v64
	v_ldexp_f32 v37, v58, v36
	v_add_f32_e32 v58, -1.0, v37
	v_add_f32_e32 v60, 1.0, v37
	v_ldexp_f32 v36, v59, v36
	v_add_f32_e32 v59, 1.0, v58
	v_add_f32_e32 v61, -1.0, v60
	v_sub_f32_e32 v59, v37, v59
	v_sub_f32_e32 v37, v37, v61
	v_add_f32_e32 v59, v36, v59
	v_add_f32_e32 v36, v36, v37
	v_add_f32_e32 v65, v60, v36
	v_rcp_f32_e32 v67, v65
	v_sub_f32_e32 v37, v65, v60
	v_sub_f32_e32 v66, v36, v37
	v_add_f32_e32 v37, v58, v59
	v_mul_f32_e32 v69, v37, v67
	v_sub_f32_e32 v36, v37, v58
	v_mul_f32_e32 v58, v65, v69
	v_fma_f32 v60, v69, v65, -v58
	v_fmac_f32_e32 v60, v69, v66
	v_sub_f32_e32 v68, v59, v36
	v_add_f32_e32 v36, v58, v60
	v_sub_f32_e32 v59, v37, v36
	v_pk_add_f32 v[62:63], v[36:37], v[58:59] neg_lo:[0,1] neg_hi:[0,1]
	v_mov_b32_e32 v61, v36
	v_pk_add_f32 v[36:37], v[62:63], v[60:61] neg_lo:[0,1] neg_hi:[0,1]
	v_cmp_neq_f32_e32 vcc, s52, v35
	v_add_f32_e32 v37, v68, v37
	v_add_f32_e32 v36, v36, v37
	v_add_f32_e32 v37, v59, v36
	v_mul_f32_e32 v68, v67, v37
	v_mul_f32_e32 v58, v65, v68
	v_fma_f32 v60, v68, v65, -v58
	v_fmac_f32_e32 v60, v68, v66
	v_sub_f32_e32 v59, v59, v37
	v_add_f32_e32 v65, v36, v59
	v_add_f32_e32 v36, v58, v60
	v_sub_f32_e32 v59, v37, v36
	v_pk_add_f32 v[62:63], v[36:37], v[58:59] neg_lo:[0,1] neg_hi:[0,1]
	v_mov_b32_e32 v61, v36
	v_pk_add_f32 v[36:37], v[62:63], v[60:61] neg_lo:[0,1] neg_hi:[0,1]
	s_nop 0
	v_add_f32_e32 v37, v65, v37
	v_add_f32_e32 v36, v36, v37
	v_add_f32_e32 v37, v69, v68
	v_add_f32_e32 v36, v59, v36
	v_sub_f32_e32 v58, v37, v69
	v_mul_f32_e32 v36, v67, v36
	v_sub_f32_e32 v58, v68, v58
	v_add_f32_e32 v58, v58, v36
	v_add_f32_e32 v60, v37, v58
	v_mul_f32_e32 v61, v60, v60
	v_fmamk_f32 v36, v61, 0x3e9b6dac, v233
	v_fmaak_f32 v185, v61, v36, 0x3f2aaada
	v_cvt_f32_i32_e32 v36, v64
	v_sub_f32_e32 v37, v60, v37
	v_sub_f32_e32 v37, v58, v37
	v_ldexp_f32 v62, v37, 1
	v_mul_f32_e32 v37, v60, v61
	v_ldexp_f32 v59, v60, 1
	v_pk_mul_f32 v[60:61], v[36:37], v[184:185]
	s_nop 0
	v_fma_f32 v58, v36, s51, -v60
	v_fmac_f32_e32 v58, 0xb102e308, v36
	v_pk_add_f32 v[36:37], v[60:61], v[58:59]
	s_nop 0
	v_sub_f32_e32 v59, v37, v59
	v_sub_f32_e32 v59, v61, v59
	v_add_f32_e32 v63, v62, v59
	v_mov_b32_e32 v62, v60
	v_pk_add_f32 v[60:61], v[36:37], v[60:61] neg_lo:[0,1] neg_hi:[0,1]
	v_pk_add_f32 v[64:65], v[36:37], v[62:63]
	v_mov_b32_e32 v59, v36
	v_mov_b32_e32 v61, v65
	v_pk_add_f32 v[66:67], v[58:59], v[60:61] neg_lo:[0,1] neg_hi:[0,1]
	v_pk_add_f32 v[58:59], v[58:59], v[60:61]
	v_mov_b32_e32 v62, v63
	v_pk_add_f32 v[60:61], v[58:59], v[36:37] op_sel:[1,0] op_sel_hi:[0,1] neg_lo:[0,1] neg_hi:[0,1]
	v_pk_add_f32 v[68:69], v[64:65], v[60:61] op_sel_hi:[1,0] neg_lo:[0,1] neg_hi:[0,1]
	v_mov_b32_e32 v64, v65
	v_mov_b32_e32 v65, v59
	v_pk_mov_b32 v[60:61], v[36:37], v[60:61] op_sel:[1,0]
	v_mov_b32_e32 v63, v36
	v_pk_add_f32 v[60:61], v[64:65], v[60:61] neg_lo:[0,1] neg_hi:[0,1]
	v_mov_b32_e32 v68, v66
	v_pk_add_f32 v[36:37], v[62:63], v[60:61] neg_lo:[0,1] neg_hi:[0,1]
	v_mov_b32_e32 v67, v59
	v_pk_add_f32 v[60:61], v[68:69], v[36:37]
	s_nop 0
	v_pk_add_f32 v[62:63], v[60:61], v[60:61] op_sel:[0,1] op_sel_hi:[1,0]
	s_nop 0
	v_pk_add_f32 v[58:59], v[58:59], v[62:63] op_sel:[1,0] op_sel_hi:[0,1]
	v_mov_b32_e32 v61, v58
	v_pk_add_f32 v[64:65], v[60:61], v[66:67] neg_lo:[0,1] neg_hi:[0,1]
	v_mov_b32_e32 v37, v62
	v_sub_f32_e32 v59, v60, v64
	v_pk_add_f32 v[36:37], v[36:37], v[64:65] neg_lo:[0,1] neg_hi:[0,1]
	v_sub_f32_e32 v59, v66, v59
	v_add_f32_e32 v36, v36, v59
	v_add_f32_e32 v36, v36, v37
	v_add_f32_e32 v36, v58, v36
	v_cndmask_b32_e32 v36, v226, v36, vcc
	v_cmp_ngt_f32_e32 vcc, -1.0, v35
	s_nop 1
	v_cndmask_b32_e32 v36, v227, v36, vcc
	v_cmp_neq_f32_e32 vcc, -1.0, v35
	s_nop 1
	v_cndmask_b32_e32 v36, v236, v36, vcc
	v_cmp_lt_f32_e64 vcc, |v35|, s27
	s_nop 1
	v_cndmask_b32_e32 v35, v36, v35, vcc
	v_sub_f32_e32 v34, v34, v35

.LBB0_1088:
	s_andn2_saveexec_b64 s[44:45], s[44:45]
	s_cbranch_execz .LBB0_1090
	s_mov_b32 s27, 0x33800000
	s_waitcnt vmcnt(0)
	v_mov_b32_e32 v34, v251
	v_add_f32_e32 v35, v53, v34
	v_min_f32_e32 v34, 0, v35
	v_mul_f32_e64 v35, |v35|, s29
	v_exp_f32_e32 v35, v35
	s_nop 0
	v_add_f32_e32 v58, 1.0, v35
	v_add_f32_e32 v36, -1.0, v58
	v_sub_f32_e32 v37, v36, v58
	v_add_f32_e32 v37, 1.0, v37
	v_sub_f32_e32 v36, v35, v36
	v_add_f32_e32 v59, v36, v37
	v_frexp_mant_f32_e32 v36, v58
	v_cmp_gt_f32_e32 vcc, s50, v36
	v_cvt_f64_f32_e32 v[36:37], v58
	v_frexp_exp_i32_f64_e32 v36, v[36:37]
	v_subbrev_co_u32_e32 v64, vcc, 0, v36, vcc
	v_sub_u32_e32 v36, 0, v64
	v_ldexp_f32 v37, v58, v36
	v_add_f32_e32 v58, -1.0, v37
	v_add_f32_e32 v60, 1.0, v37
	v_ldexp_f32 v36, v59, v36
	v_add_f32_e32 v59, 1.0, v58
	v_add_f32_e32 v61, -1.0, v60
	v_sub_f32_e32 v59, v37, v59
	v_sub_f32_e32 v37, v37, v61
	v_add_f32_e32 v59, v36, v59
	v_add_f32_e32 v36, v36, v37
	v_add_f32_e32 v65, v60, v36
	v_rcp_f32_e32 v67, v65
	v_sub_f32_e32 v37, v65, v60
	v_sub_f32_e32 v66, v36, v37
	v_add_f32_e32 v37, v58, v59
	v_mul_f32_e32 v69, v37, v67
	v_sub_f32_e32 v36, v37, v58
	v_mul_f32_e32 v58, v65, v69
	v_fma_f32 v60, v69, v65, -v58
	v_fmac_f32_e32 v60, v69, v66
	v_sub_f32_e32 v68, v59, v36
	v_add_f32_e32 v36, v58, v60
	v_sub_f32_e32 v59, v37, v36
	v_pk_add_f32 v[62:63], v[36:37], v[58:59] neg_lo:[0,1] neg_hi:[0,1]
	v_mov_b32_e32 v61, v36
	v_pk_add_f32 v[36:37], v[62:63], v[60:61] neg_lo:[0,1] neg_hi:[0,1]
	v_cmp_neq_f32_e32 vcc, s52, v35
	v_add_f32_e32 v37, v68, v37
	v_add_f32_e32 v36, v36, v37
	v_add_f32_e32 v37, v59, v36
	v_mul_f32_e32 v68, v67, v37
	v_mul_f32_e32 v58, v65, v68
	v_fma_f32 v60, v68, v65, -v58
	v_fmac_f32_e32 v60, v68, v66
	v_sub_f32_e32 v59, v59, v37
	v_add_f32_e32 v65, v36, v59
	v_add_f32_e32 v36, v58, v60
	v_sub_f32_e32 v59, v37, v36
	v_pk_add_f32 v[62:63], v[36:37], v[58:59] neg_lo:[0,1] neg_hi:[0,1]
	v_mov_b32_e32 v61, v36
	v_pk_add_f32 v[36:37], v[62:63], v[60:61] neg_lo:[0,1] neg_hi:[0,1]
	s_nop 0
	v_add_f32_e32 v37, v65, v37
	v_add_f32_e32 v36, v36, v37
	v_add_f32_e32 v37, v69, v68
	v_add_f32_e32 v36, v59, v36
	v_sub_f32_e32 v58, v37, v69
	v_mul_f32_e32 v36, v67, v36
	v_sub_f32_e32 v58, v68, v58
	v_add_f32_e32 v58, v58, v36
	v_add_f32_e32 v60, v37, v58
	v_mul_f32_e32 v61, v60, v60
	v_fmamk_f32 v36, v61, 0x3e9b6dac, v233
	v_fmaak_f32 v185, v61, v36, 0x3f2aaada
	v_cvt_f32_i32_e32 v36, v64
	v_sub_f32_e32 v37, v60, v37
	v_sub_f32_e32 v37, v58, v37
	v_ldexp_f32 v62, v37, 1
	v_mul_f32_e32 v37, v60, v61
	v_ldexp_f32 v59, v60, 1
	v_pk_mul_f32 v[60:61], v[36:37], v[184:185]
	s_nop 0
	v_fma_f32 v58, v36, s51, -v60
	v_fmac_f32_e32 v58, 0xb102e308, v36
	v_pk_add_f32 v[36:37], v[60:61], v[58:59]
	s_nop 0
	v_sub_f32_e32 v59, v37, v59
	v_sub_f32_e32 v59, v61, v59
	v_add_f32_e32 v63, v62, v59
	v_mov_b32_e32 v62, v60
	v_pk_add_f32 v[60:61], v[36:37], v[60:61] neg_lo:[0,1] neg_hi:[0,1]
	v_pk_add_f32 v[64:65], v[36:37], v[62:63]
	v_mov_b32_e32 v59, v36
	v_mov_b32_e32 v61, v65
	v_pk_add_f32 v[66:67], v[58:59], v[60:61] neg_lo:[0,1] neg_hi:[0,1]
	v_pk_add_f32 v[58:59], v[58:59], v[60:61]
	v_mov_b32_e32 v62, v63
	v_pk_add_f32 v[60:61], v[58:59], v[36:37] op_sel:[1,0] op_sel_hi:[0,1] neg_lo:[0,1] neg_hi:[0,1]
	v_pk_add_f32 v[68:69], v[64:65], v[60:61] op_sel_hi:[1,0] neg_lo:[0,1] neg_hi:[0,1]
	v_mov_b32_e32 v64, v65
	v_mov_b32_e32 v65, v59
	v_pk_mov_b32 v[60:61], v[36:37], v[60:61] op_sel:[1,0]
	v_mov_b32_e32 v63, v36
	v_pk_add_f32 v[60:61], v[64:65], v[60:61] neg_lo:[0,1] neg_hi:[0,1]
	v_mov_b32_e32 v68, v66
	v_pk_add_f32 v[36:37], v[62:63], v[60:61] neg_lo:[0,1] neg_hi:[0,1]
	v_mov_b32_e32 v67, v59
	v_pk_add_f32 v[60:61], v[68:69], v[36:37]
	s_nop 0
	v_pk_add_f32 v[62:63], v[60:61], v[60:61] op_sel:[0,1] op_sel_hi:[1,0]
	s_nop 0
	v_pk_add_f32 v[58:59], v[58:59], v[62:63] op_sel:[1,0] op_sel_hi:[0,1]
	v_mov_b32_e32 v61, v58
	v_pk_add_f32 v[64:65], v[60:61], v[66:67] neg_lo:[0,1] neg_hi:[0,1]
	v_mov_b32_e32 v37, v62
	v_sub_f32_e32 v59, v60, v64
	v_pk_add_f32 v[36:37], v[36:37], v[64:65] neg_lo:[0,1] neg_hi:[0,1]
	v_sub_f32_e32 v59, v66, v59
	v_add_f32_e32 v36, v36, v59
	v_add_f32_e32 v36, v36, v37
	v_add_f32_e32 v36, v58, v36
	v_cndmask_b32_e32 v36, v226, v36, vcc
	v_cmp_ngt_f32_e32 vcc, -1.0, v35
	s_nop 1
	v_cndmask_b32_e32 v36, v227, v36, vcc
	v_cmp_neq_f32_e32 vcc, -1.0, v35
	s_nop 1
	v_cndmask_b32_e32 v36, v236, v36, vcc
	v_cmp_lt_f32_e64 vcc, |v35|, s27
	s_nop 1
	v_cndmask_b32_e32 v35, v36, v35, vcc
	v_sub_f32_e32 v34, v34, v35

.LBB0_1102:
	s_andn2_saveexec_b64 s[44:45], s[44:45]
	s_cbranch_execz .LBB0_1104
	s_mov_b32 s27, 0x33800000
	s_waitcnt vmcnt(0)
	v_mov_b32_e32 v18, v248
	v_add_f32_e32 v19, v30, v18
	v_min_f32_e32 v18, 0, v19
	v_mul_f32_e64 v19, |v19|, s29
	v_exp_f32_e32 v19, v19
	s_nop 0
	v_add_f32_e32 v40, 1.0, v19
	v_add_f32_e32 v20, -1.0, v40
	v_sub_f32_e32 v21, v20, v40
	v_add_f32_e32 v21, 1.0, v21
	v_sub_f32_e32 v20, v19, v20
	v_add_f32_e32 v41, v20, v21
	v_frexp_mant_f32_e32 v20, v40
	v_cmp_gt_f32_e32 vcc, s50, v20
	v_cvt_f64_f32_e32 v[20:21], v40
	v_frexp_exp_i32_f64_e32 v20, v[20:21]
	v_subbrev_co_u32_e32 v46, vcc, 0, v20, vcc
	v_sub_u32_e32 v20, 0, v46
	v_ldexp_f32 v21, v40, v20
	v_add_f32_e32 v40, -1.0, v21
	v_add_f32_e32 v42, 1.0, v21
	v_ldexp_f32 v20, v41, v20
	v_add_f32_e32 v41, 1.0, v40
	v_add_f32_e32 v43, -1.0, v42
	v_sub_f32_e32 v41, v21, v41
	v_sub_f32_e32 v21, v21, v43
	v_add_f32_e32 v41, v20, v41
	v_add_f32_e32 v20, v20, v21
	v_add_f32_e32 v47, v42, v20
	v_rcp_f32_e32 v49, v47
	v_sub_f32_e32 v21, v47, v42
	v_sub_f32_e32 v48, v20, v21
	v_add_f32_e32 v21, v40, v41
	v_mul_f32_e32 v51, v21, v49
	v_sub_f32_e32 v20, v21, v40
	v_mul_f32_e32 v40, v47, v51
	v_fma_f32 v42, v51, v47, -v40
	v_fmac_f32_e32 v42, v51, v48
	v_sub_f32_e32 v50, v41, v20
	v_add_f32_e32 v20, v40, v42
	v_sub_f32_e32 v41, v21, v20
	v_pk_add_f32 v[44:45], v[20:21], v[40:41] neg_lo:[0,1] neg_hi:[0,1]
	v_mov_b32_e32 v43, v20
	v_pk_add_f32 v[20:21], v[44:45], v[42:43] neg_lo:[0,1] neg_hi:[0,1]
	v_cmp_neq_f32_e32 vcc, s52, v19
	v_add_f32_e32 v21, v50, v21
	v_add_f32_e32 v20, v20, v21
	v_add_f32_e32 v21, v41, v20
	v_mul_f32_e32 v50, v49, v21
	v_mul_f32_e32 v40, v47, v50
	v_fma_f32 v42, v50, v47, -v40
	v_fmac_f32_e32 v42, v50, v48
	v_sub_f32_e32 v41, v41, v21
	v_add_f32_e32 v47, v20, v41
	v_add_f32_e32 v20, v40, v42
	v_sub_f32_e32 v41, v21, v20
	v_pk_add_f32 v[44:45], v[20:21], v[40:41] neg_lo:[0,1] neg_hi:[0,1]
	v_mov_b32_e32 v43, v20
	v_pk_add_f32 v[20:21], v[44:45], v[42:43] neg_lo:[0,1] neg_hi:[0,1]
	s_nop 0
	v_add_f32_e32 v21, v47, v21
	v_add_f32_e32 v20, v20, v21
	v_add_f32_e32 v21, v51, v50
	v_add_f32_e32 v20, v41, v20
	v_sub_f32_e32 v40, v21, v51
	v_mul_f32_e32 v20, v49, v20
	v_sub_f32_e32 v40, v50, v40
	v_add_f32_e32 v40, v40, v20
	v_add_f32_e32 v42, v21, v40
	v_mul_f32_e32 v43, v42, v42
	v_fmamk_f32 v20, v43, 0x3e9b6dac, v233
	v_fmaak_f32 v185, v43, v20, 0x3f2aaada
	v_cvt_f32_i32_e32 v20, v46
	v_sub_f32_e32 v21, v42, v21
	v_sub_f32_e32 v21, v40, v21
	v_ldexp_f32 v44, v21, 1
	v_mul_f32_e32 v21, v42, v43
	v_ldexp_f32 v41, v42, 1
	v_pk_mul_f32 v[42:43], v[20:21], v[184:185]
	s_nop 0
	v_fma_f32 v40, v20, s51, -v42
	v_fmac_f32_e32 v40, 0xb102e308, v20
	v_pk_add_f32 v[20:21], v[42:43], v[40:41]
	s_nop 0
	v_sub_f32_e32 v41, v21, v41
	v_sub_f32_e32 v41, v43, v41
	v_add_f32_e32 v45, v44, v41
	v_mov_b32_e32 v44, v42
	v_pk_add_f32 v[42:43], v[20:21], v[42:43] neg_lo:[0,1] neg_hi:[0,1]
	v_pk_add_f32 v[46:47], v[20:21], v[44:45]
	v_mov_b32_e32 v41, v20
	v_mov_b32_e32 v43, v47
	v_pk_add_f32 v[48:49], v[40:41], v[42:43] neg_lo:[0,1] neg_hi:[0,1]
	v_pk_add_f32 v[40:41], v[40:41], v[42:43]
	v_mov_b32_e32 v44, v45
	v_pk_add_f32 v[42:43], v[40:41], v[20:21] op_sel:[1,0] op_sel_hi:[0,1] neg_lo:[0,1] neg_hi:[0,1]
	v_pk_add_f32 v[50:51], v[46:47], v[42:43] op_sel_hi:[1,0] neg_lo:[0,1] neg_hi:[0,1]
	v_mov_b32_e32 v46, v47
	v_mov_b32_e32 v47, v41
	v_pk_mov_b32 v[42:43], v[20:21], v[42:43] op_sel:[1,0]
	v_mov_b32_e32 v45, v20
	v_pk_add_f32 v[42:43], v[46:47], v[42:43] neg_lo:[0,1] neg_hi:[0,1]
	v_mov_b32_e32 v50, v48
	v_pk_add_f32 v[20:21], v[44:45], v[42:43] neg_lo:[0,1] neg_hi:[0,1]
	v_mov_b32_e32 v49, v41
	v_pk_add_f32 v[42:43], v[50:51], v[20:21]
	s_nop 0
	v_pk_add_f32 v[44:45], v[42:43], v[42:43] op_sel:[0,1] op_sel_hi:[1,0]
	s_nop 0
	v_pk_add_f32 v[40:41], v[40:41], v[44:45] op_sel:[1,0] op_sel_hi:[0,1]
	v_mov_b32_e32 v43, v40
	v_pk_add_f32 v[46:47], v[42:43], v[48:49] neg_lo:[0,1] neg_hi:[0,1]
	v_mov_b32_e32 v21, v44
	v_sub_f32_e32 v41, v42, v46
	v_pk_add_f32 v[20:21], v[20:21], v[46:47] neg_lo:[0,1] neg_hi:[0,1]
	v_sub_f32_e32 v41, v48, v41
	v_add_f32_e32 v20, v20, v41
	v_add_f32_e32 v20, v20, v21
	v_add_f32_e32 v20, v40, v20
	v_cndmask_b32_e32 v20, v226, v20, vcc
	v_cmp_ngt_f32_e32 vcc, -1.0, v19
	s_nop 1
	v_cndmask_b32_e32 v20, v227, v20, vcc
	v_cmp_neq_f32_e32 vcc, -1.0, v19
	s_nop 1
	v_cndmask_b32_e32 v20, v236, v20, vcc
	v_cmp_lt_f32_e64 vcc, |v19|, s27
	s_nop 1
	v_cndmask_b32_e32 v19, v20, v19, vcc
	v_sub_f32_e32 v20, v18, v19

.LBB0_1106:
	s_andn2_saveexec_b64 s[44:45], s[44:45]
	s_cbranch_execz .LBB0_1108
	s_mov_b32 s27, 0x33800000
	s_waitcnt vmcnt(0)
	v_mov_b32_e32 v20, v249
	v_add_f32_e32 v21, v31, v20
	v_min_f32_e32 v20, 0, v21
	v_mul_f32_e64 v21, |v21|, s29
	v_exp_f32_e32 v21, v21
	s_nop 0
	v_add_f32_e32 v42, 1.0, v21
	v_add_f32_e32 v40, -1.0, v42
	v_sub_f32_e32 v41, v40, v42
	v_add_f32_e32 v41, 1.0, v41
	v_sub_f32_e32 v40, v21, v40
	v_add_f32_e32 v43, v40, v41
	v_frexp_mant_f32_e32 v40, v42
	v_cmp_gt_f32_e32 vcc, s50, v40
	v_cvt_f64_f32_e32 v[40:41], v42
	v_frexp_exp_i32_f64_e32 v40, v[40:41]
	v_subbrev_co_u32_e32 v48, vcc, 0, v40, vcc
	v_sub_u32_e32 v40, 0, v48
	v_ldexp_f32 v41, v42, v40
	v_add_f32_e32 v42, -1.0, v41
	v_add_f32_e32 v44, 1.0, v41
	v_ldexp_f32 v40, v43, v40
	v_add_f32_e32 v43, 1.0, v42
	v_add_f32_e32 v45, -1.0, v44
	v_sub_f32_e32 v43, v41, v43
	v_sub_f32_e32 v41, v41, v45
	v_add_f32_e32 v43, v40, v43
	v_add_f32_e32 v40, v40, v41
	v_add_f32_e32 v49, v44, v40
	v_rcp_f32_e32 v51, v49
	v_sub_f32_e32 v41, v49, v44
	v_sub_f32_e32 v50, v40, v41
	v_add_f32_e32 v41, v42, v43
	v_mul_f32_e32 v53, v41, v51
	v_sub_f32_e32 v40, v41, v42
	v_mul_f32_e32 v42, v49, v53
	v_fma_f32 v44, v53, v49, -v42
	v_fmac_f32_e32 v44, v53, v50
	v_sub_f32_e32 v52, v43, v40
	v_add_f32_e32 v40, v42, v44
	v_sub_f32_e32 v43, v41, v40
	v_pk_add_f32 v[46:47], v[40:41], v[42:43] neg_lo:[0,1] neg_hi:[0,1]
	v_mov_b32_e32 v45, v40
	v_pk_add_f32 v[40:41], v[46:47], v[44:45] neg_lo:[0,1] neg_hi:[0,1]
	v_cmp_neq_f32_e32 vcc, s52, v21
	v_add_f32_e32 v41, v52, v41
	v_add_f32_e32 v40, v40, v41
	v_add_f32_e32 v41, v43, v40
	v_mul_f32_e32 v52, v51, v41
	v_mul_f32_e32 v42, v49, v52
	v_fma_f32 v44, v52, v49, -v42
	v_fmac_f32_e32 v44, v52, v50
	v_sub_f32_e32 v43, v43, v41
	v_add_f32_e32 v49, v40, v43
	v_add_f32_e32 v40, v42, v44
	v_sub_f32_e32 v43, v41, v40
	v_pk_add_f32 v[46:47], v[40:41], v[42:43] neg_lo:[0,1] neg_hi:[0,1]
	v_mov_b32_e32 v45, v40
	v_pk_add_f32 v[40:41], v[46:47], v[44:45] neg_lo:[0,1] neg_hi:[0,1]
	s_nop 0
	v_add_f32_e32 v41, v49, v41
	v_add_f32_e32 v40, v40, v41
	v_add_f32_e32 v41, v53, v52
	v_add_f32_e32 v40, v43, v40
	v_sub_f32_e32 v42, v41, v53
	v_mul_f32_e32 v40, v51, v40
	v_sub_f32_e32 v42, v52, v42
	v_add_f32_e32 v42, v42, v40
	v_add_f32_e32 v44, v41, v42
	v_mul_f32_e32 v45, v44, v44
	v_fmamk_f32 v40, v45, 0x3e9b6dac, v233
	v_fmaak_f32 v185, v45, v40, 0x3f2aaada
	v_cvt_f32_i32_e32 v40, v48
	v_sub_f32_e32 v41, v44, v41
	v_sub_f32_e32 v41, v42, v41
	v_ldexp_f32 v46, v41, 1
	v_mul_f32_e32 v41, v44, v45
	v_ldexp_f32 v43, v44, 1
	v_pk_mul_f32 v[44:45], v[40:41], v[184:185]
	s_nop 0
	v_fma_f32 v42, v40, s51, -v44
	v_fmac_f32_e32 v42, 0xb102e308, v40
	v_pk_add_f32 v[40:41], v[44:45], v[42:43]
	s_nop 0
	v_sub_f32_e32 v43, v41, v43
	v_sub_f32_e32 v43, v45, v43
	v_add_f32_e32 v47, v46, v43
	v_mov_b32_e32 v46, v44
	v_pk_add_f32 v[44:45], v[40:41], v[44:45] neg_lo:[0,1] neg_hi:[0,1]
	v_pk_add_f32 v[48:49], v[40:41], v[46:47]
	v_mov_b32_e32 v43, v40
	v_mov_b32_e32 v45, v49
	v_pk_add_f32 v[50:51], v[42:43], v[44:45] neg_lo:[0,1] neg_hi:[0,1]
	v_pk_add_f32 v[42:43], v[42:43], v[44:45]
	v_mov_b32_e32 v46, v47
	v_pk_add_f32 v[44:45], v[42:43], v[40:41] op_sel:[1,0] op_sel_hi:[0,1] neg_lo:[0,1] neg_hi:[0,1]
	v_pk_add_f32 v[52:53], v[48:49], v[44:45] op_sel_hi:[1,0] neg_lo:[0,1] neg_hi:[0,1]
	v_mov_b32_e32 v48, v49
	v_mov_b32_e32 v49, v43
	v_pk_mov_b32 v[44:45], v[40:41], v[44:45] op_sel:[1,0]
	v_mov_b32_e32 v47, v40
	v_pk_add_f32 v[44:45], v[48:49], v[44:45] neg_lo:[0,1] neg_hi:[0,1]
	v_mov_b32_e32 v52, v50
	v_pk_add_f32 v[40:41], v[46:47], v[44:45] neg_lo:[0,1] neg_hi:[0,1]
	v_mov_b32_e32 v51, v43
	v_pk_add_f32 v[44:45], v[52:53], v[40:41]
	s_nop 0
	v_pk_add_f32 v[46:47], v[44:45], v[44:45] op_sel:[0,1] op_sel_hi:[1,0]
	s_nop 0
	v_pk_add_f32 v[42:43], v[42:43], v[46:47] op_sel:[1,0] op_sel_hi:[0,1]
	v_mov_b32_e32 v45, v42
	v_pk_add_f32 v[48:49], v[44:45], v[50:51] neg_lo:[0,1] neg_hi:[0,1]
	v_mov_b32_e32 v41, v46
	v_sub_f32_e32 v43, v44, v48
	v_pk_add_f32 v[40:41], v[40:41], v[48:49] neg_lo:[0,1] neg_hi:[0,1]
	v_sub_f32_e32 v43, v50, v43
	v_add_f32_e32 v40, v40, v43
	v_add_f32_e32 v40, v40, v41
	v_add_f32_e32 v40, v42, v40
	v_cndmask_b32_e32 v40, v226, v40, vcc
	v_cmp_ngt_f32_e32 vcc, -1.0, v21
	s_nop 1
	v_cndmask_b32_e32 v40, v227, v40, vcc
	v_cmp_neq_f32_e32 vcc, -1.0, v21
	s_nop 1
	v_cndmask_b32_e32 v40, v236, v40, vcc
	v_cmp_lt_f32_e64 vcc, |v21|, s27
	s_nop 1
	v_cndmask_b32_e32 v21, v40, v21, vcc
	v_sub_f32_e32 v20, v20, v21

.LBB0_1110:
	s_andn2_saveexec_b64 s[44:45], s[44:45]
	s_cbranch_execz .LBB0_1112
	s_mov_b32 s27, 0x33800000
	s_waitcnt vmcnt(0)
	v_mov_b32_e32 v18, v250
	v_add_f32_e32 v19, v36, v18
	v_min_f32_e32 v18, 0, v19
	v_mul_f32_e64 v19, |v19|, s29
	v_exp_f32_e32 v19, v19
	s_nop 0
	v_add_f32_e32 v42, 1.0, v19
	v_add_f32_e32 v20, -1.0, v42
	v_sub_f32_e32 v21, v20, v42
	v_add_f32_e32 v21, 1.0, v21
	v_sub_f32_e32 v20, v19, v20
	v_add_f32_e32 v43, v20, v21
	v_frexp_mant_f32_e32 v20, v42
	v_cmp_gt_f32_e32 vcc, s50, v20
	v_cvt_f64_f32_e32 v[20:21], v42
	v_frexp_exp_i32_f64_e32 v20, v[20:21]
	v_subbrev_co_u32_e32 v48, vcc, 0, v20, vcc
	v_sub_u32_e32 v20, 0, v48
	v_ldexp_f32 v21, v42, v20
	v_add_f32_e32 v42, -1.0, v21
	v_add_f32_e32 v44, 1.0, v21
	v_ldexp_f32 v20, v43, v20
	v_add_f32_e32 v43, 1.0, v42
	v_add_f32_e32 v45, -1.0, v44
	v_sub_f32_e32 v43, v21, v43
	v_sub_f32_e32 v21, v21, v45
	v_add_f32_e32 v43, v20, v43
	v_add_f32_e32 v20, v20, v21
	v_add_f32_e32 v49, v44, v20
	v_rcp_f32_e32 v51, v49
	v_sub_f32_e32 v21, v49, v44
	v_sub_f32_e32 v50, v20, v21
	v_add_f32_e32 v21, v42, v43
	v_mul_f32_e32 v53, v21, v51
	v_sub_f32_e32 v20, v21, v42
	v_mul_f32_e32 v42, v49, v53
	v_fma_f32 v44, v53, v49, -v42
	v_fmac_f32_e32 v44, v53, v50
	v_sub_f32_e32 v52, v43, v20
	v_add_f32_e32 v20, v42, v44
	v_sub_f32_e32 v43, v21, v20
	v_pk_add_f32 v[46:47], v[20:21], v[42:43] neg_lo:[0,1] neg_hi:[0,1]
	v_mov_b32_e32 v45, v20
	v_pk_add_f32 v[20:21], v[46:47], v[44:45] neg_lo:[0,1] neg_hi:[0,1]
	v_cmp_neq_f32_e32 vcc, s52, v19
	v_add_f32_e32 v21, v52, v21
	v_add_f32_e32 v20, v20, v21
	v_add_f32_e32 v21, v43, v20
	v_mul_f32_e32 v52, v51, v21
	v_mul_f32_e32 v42, v49, v52
	v_fma_f32 v44, v52, v49, -v42
	v_fmac_f32_e32 v44, v52, v50
	v_sub_f32_e32 v43, v43, v21
	v_add_f32_e32 v49, v20, v43
	v_add_f32_e32 v20, v42, v44
	v_sub_f32_e32 v43, v21, v20
	v_pk_add_f32 v[46:47], v[20:21], v[42:43] neg_lo:[0,1] neg_hi:[0,1]
	v_mov_b32_e32 v45, v20
	v_pk_add_f32 v[20:21], v[46:47], v[44:45] neg_lo:[0,1] neg_hi:[0,1]
	s_nop 0
	v_add_f32_e32 v21, v49, v21
	v_add_f32_e32 v20, v20, v21
	v_add_f32_e32 v21, v53, v52
	v_add_f32_e32 v20, v43, v20
	v_sub_f32_e32 v42, v21, v53
	v_mul_f32_e32 v20, v51, v20
	v_sub_f32_e32 v42, v52, v42
	v_add_f32_e32 v42, v42, v20
	v_add_f32_e32 v44, v21, v42
	v_mul_f32_e32 v45, v44, v44
	v_fmamk_f32 v20, v45, 0x3e9b6dac, v233
	v_fmaak_f32 v185, v45, v20, 0x3f2aaada
	v_cvt_f32_i32_e32 v20, v48
	v_sub_f32_e32 v21, v44, v21
	v_sub_f32_e32 v21, v42, v21
	v_ldexp_f32 v46, v21, 1
	v_mul_f32_e32 v21, v44, v45
	v_ldexp_f32 v43, v44, 1
	v_pk_mul_f32 v[44:45], v[20:21], v[184:185]
	s_nop 0
	v_fma_f32 v42, v20, s51, -v44
	v_fmac_f32_e32 v42, 0xb102e308, v20
	v_pk_add_f32 v[20:21], v[44:45], v[42:43]
	s_nop 0
	v_sub_f32_e32 v43, v21, v43
	v_sub_f32_e32 v43, v45, v43
	v_add_f32_e32 v47, v46, v43
	v_mov_b32_e32 v46, v44
	v_pk_add_f32 v[44:45], v[20:21], v[44:45] neg_lo:[0,1] neg_hi:[0,1]
	v_pk_add_f32 v[48:49], v[20:21], v[46:47]
	v_mov_b32_e32 v43, v20
	v_mov_b32_e32 v45, v49
	v_pk_add_f32 v[50:51], v[42:43], v[44:45] neg_lo:[0,1] neg_hi:[0,1]
	v_pk_add_f32 v[42:43], v[42:43], v[44:45]
	v_mov_b32_e32 v46, v47
	v_pk_add_f32 v[44:45], v[42:43], v[20:21] op_sel:[1,0] op_sel_hi:[0,1] neg_lo:[0,1] neg_hi:[0,1]
	v_pk_add_f32 v[52:53], v[48:49], v[44:45] op_sel_hi:[1,0] neg_lo:[0,1] neg_hi:[0,1]
	v_mov_b32_e32 v48, v49
	v_mov_b32_e32 v49, v43
	v_pk_mov_b32 v[44:45], v[20:21], v[44:45] op_sel:[1,0]
	v_mov_b32_e32 v47, v20
	v_pk_add_f32 v[44:45], v[48:49], v[44:45] neg_lo:[0,1] neg_hi:[0,1]
	v_mov_b32_e32 v52, v50
	v_pk_add_f32 v[20:21], v[46:47], v[44:45] neg_lo:[0,1] neg_hi:[0,1]
	v_mov_b32_e32 v51, v43
	v_pk_add_f32 v[44:45], v[52:53], v[20:21]
	s_nop 0
	v_pk_add_f32 v[46:47], v[44:45], v[44:45] op_sel:[0,1] op_sel_hi:[1,0]
	s_nop 0
	v_pk_add_f32 v[42:43], v[42:43], v[46:47] op_sel:[1,0] op_sel_hi:[0,1]
	v_mov_b32_e32 v45, v42
	v_pk_add_f32 v[48:49], v[44:45], v[50:51] neg_lo:[0,1] neg_hi:[0,1]
	v_mov_b32_e32 v21, v46
	v_sub_f32_e32 v43, v44, v48
	v_pk_add_f32 v[20:21], v[20:21], v[48:49] neg_lo:[0,1] neg_hi:[0,1]
	v_sub_f32_e32 v43, v50, v43
	v_add_f32_e32 v20, v20, v43
	v_add_f32_e32 v20, v20, v21
	v_add_f32_e32 v20, v42, v20
	v_cndmask_b32_e32 v20, v226, v20, vcc
	v_cmp_ngt_f32_e32 vcc, -1.0, v19
	s_nop 1
	v_cndmask_b32_e32 v20, v227, v20, vcc
	v_cmp_neq_f32_e32 vcc, -1.0, v19
	s_nop 1
	v_cndmask_b32_e32 v20, v236, v20, vcc
	v_cmp_lt_f32_e64 vcc, |v19|, s27
	s_nop 1
	v_cndmask_b32_e32 v19, v20, v19, vcc
	v_sub_f32_e32 v18, v18, v19

.LBB0_1114:
	s_andn2_saveexec_b64 s[44:45], s[44:45]
	s_cbranch_execz .LBB0_1116
	s_mov_b32 s27, 0x33800000
	s_waitcnt vmcnt(0)
	v_mov_b32_e32 v18, v251
	v_add_f32_e32 v19, v37, v18
	v_min_f32_e32 v18, 0, v19
	v_mul_f32_e64 v19, |v19|, s29
	v_exp_f32_e32 v19, v19
	s_nop 0
	v_add_f32_e32 v42, 1.0, v19
	v_add_f32_e32 v20, -1.0, v42
	v_sub_f32_e32 v21, v20, v42
	v_add_f32_e32 v21, 1.0, v21
	v_sub_f32_e32 v20, v19, v20
	v_add_f32_e32 v43, v20, v21
	v_frexp_mant_f32_e32 v20, v42
	v_cmp_gt_f32_e32 vcc, s50, v20
	v_cvt_f64_f32_e32 v[20:21], v42
	v_frexp_exp_i32_f64_e32 v20, v[20:21]
	v_subbrev_co_u32_e32 v48, vcc, 0, v20, vcc
	v_sub_u32_e32 v20, 0, v48
	v_ldexp_f32 v21, v42, v20
	v_add_f32_e32 v42, -1.0, v21
	v_add_f32_e32 v44, 1.0, v21
	v_ldexp_f32 v20, v43, v20
	v_add_f32_e32 v43, 1.0, v42
	v_add_f32_e32 v45, -1.0, v44
	v_sub_f32_e32 v43, v21, v43
	v_sub_f32_e32 v21, v21, v45
	v_add_f32_e32 v43, v20, v43
	v_add_f32_e32 v20, v20, v21
	v_add_f32_e32 v49, v44, v20
	v_rcp_f32_e32 v51, v49
	v_sub_f32_e32 v21, v49, v44
	v_sub_f32_e32 v50, v20, v21
	v_add_f32_e32 v21, v42, v43
	v_mul_f32_e32 v53, v21, v51
	v_sub_f32_e32 v20, v21, v42
	v_mul_f32_e32 v42, v49, v53
	v_fma_f32 v44, v53, v49, -v42
	v_fmac_f32_e32 v44, v53, v50
	v_sub_f32_e32 v52, v43, v20
	v_add_f32_e32 v20, v42, v44
	v_sub_f32_e32 v43, v21, v20
	v_pk_add_f32 v[46:47], v[20:21], v[42:43] neg_lo:[0,1] neg_hi:[0,1]
	v_mov_b32_e32 v45, v20
	v_pk_add_f32 v[20:21], v[46:47], v[44:45] neg_lo:[0,1] neg_hi:[0,1]
	v_cmp_neq_f32_e32 vcc, s52, v19
	v_add_f32_e32 v21, v52, v21
	v_add_f32_e32 v20, v20, v21
	v_add_f32_e32 v21, v43, v20
	v_mul_f32_e32 v52, v51, v21
	v_mul_f32_e32 v42, v49, v52
	v_fma_f32 v44, v52, v49, -v42
	v_fmac_f32_e32 v44, v52, v50
	v_sub_f32_e32 v43, v43, v21
	v_add_f32_e32 v49, v20, v43
	v_add_f32_e32 v20, v42, v44
	v_sub_f32_e32 v43, v21, v20
	v_pk_add_f32 v[46:47], v[20:21], v[42:43] neg_lo:[0,1] neg_hi:[0,1]
	v_mov_b32_e32 v45, v20
	v_pk_add_f32 v[20:21], v[46:47], v[44:45] neg_lo:[0,1] neg_hi:[0,1]
	s_nop 0
	v_add_f32_e32 v21, v49, v21
	v_add_f32_e32 v20, v20, v21
	v_add_f32_e32 v21, v53, v52
	v_add_f32_e32 v20, v43, v20
	v_sub_f32_e32 v42, v21, v53
	v_mul_f32_e32 v20, v51, v20
	v_sub_f32_e32 v42, v52, v42
	v_add_f32_e32 v42, v42, v20
	v_add_f32_e32 v44, v21, v42
	v_mul_f32_e32 v45, v44, v44
	v_fmamk_f32 v20, v45, 0x3e9b6dac, v233
	v_fmaak_f32 v185, v45, v20, 0x3f2aaada
	v_cvt_f32_i32_e32 v20, v48
	v_sub_f32_e32 v21, v44, v21
	v_sub_f32_e32 v21, v42, v21
	v_ldexp_f32 v46, v21, 1
	v_mul_f32_e32 v21, v44, v45
	v_ldexp_f32 v43, v44, 1
	v_pk_mul_f32 v[44:45], v[20:21], v[184:185]
	s_nop 0
	v_fma_f32 v42, v20, s51, -v44
	v_fmac_f32_e32 v42, 0xb102e308, v20
	v_pk_add_f32 v[20:21], v[44:45], v[42:43]
	s_nop 0
	v_sub_f32_e32 v43, v21, v43
	v_sub_f32_e32 v43, v45, v43
	v_add_f32_e32 v47, v46, v43
	v_mov_b32_e32 v46, v44
	v_pk_add_f32 v[44:45], v[20:21], v[44:45] neg_lo:[0,1] neg_hi:[0,1]
	v_pk_add_f32 v[48:49], v[20:21], v[46:47]
	v_mov_b32_e32 v43, v20
	v_mov_b32_e32 v45, v49
	v_pk_add_f32 v[50:51], v[42:43], v[44:45] neg_lo:[0,1] neg_hi:[0,1]
	v_pk_add_f32 v[42:43], v[42:43], v[44:45]
	v_mov_b32_e32 v46, v47
	v_pk_add_f32 v[44:45], v[42:43], v[20:21] op_sel:[1,0] op_sel_hi:[0,1] neg_lo:[0,1] neg_hi:[0,1]
	v_pk_add_f32 v[52:53], v[48:49], v[44:45] op_sel_hi:[1,0] neg_lo:[0,1] neg_hi:[0,1]
	v_mov_b32_e32 v48, v49
	v_mov_b32_e32 v49, v43
	v_pk_mov_b32 v[44:45], v[20:21], v[44:45] op_sel:[1,0]
	v_mov_b32_e32 v47, v20
	v_pk_add_f32 v[44:45], v[48:49], v[44:45] neg_lo:[0,1] neg_hi:[0,1]
	v_mov_b32_e32 v52, v50
	v_pk_add_f32 v[20:21], v[46:47], v[44:45] neg_lo:[0,1] neg_hi:[0,1]
	v_mov_b32_e32 v51, v43
	v_pk_add_f32 v[44:45], v[52:53], v[20:21]
	s_nop 0
	v_pk_add_f32 v[46:47], v[44:45], v[44:45] op_sel:[0,1] op_sel_hi:[1,0]
	s_nop 0
	v_pk_add_f32 v[42:43], v[42:43], v[46:47] op_sel:[1,0] op_sel_hi:[0,1]
	v_mov_b32_e32 v45, v42
	v_pk_add_f32 v[48:49], v[44:45], v[50:51] neg_lo:[0,1] neg_hi:[0,1]
	v_mov_b32_e32 v21, v46
	v_sub_f32_e32 v43, v44, v48
	v_pk_add_f32 v[20:21], v[20:21], v[48:49] neg_lo:[0,1] neg_hi:[0,1]
	v_sub_f32_e32 v43, v50, v43
	v_add_f32_e32 v20, v20, v43
	v_add_f32_e32 v20, v20, v21
	v_add_f32_e32 v20, v42, v20
	v_cndmask_b32_e32 v20, v226, v20, vcc
	v_cmp_ngt_f32_e32 vcc, -1.0, v19
	s_nop 1
	v_cndmask_b32_e32 v20, v227, v20, vcc
	v_cmp_neq_f32_e32 vcc, -1.0, v19
	s_nop 1
	v_cndmask_b32_e32 v20, v236, v20, vcc
	v_cmp_lt_f32_e64 vcc, |v19|, s27
	s_nop 1
	v_cndmask_b32_e32 v19, v20, v19, vcc
	v_sub_f32_e32 v18, v18, v19

.LBB0_1128:
	s_andn2_saveexec_b64 s[8:9], s[8:9]
	s_cbranch_execz .LBB0_1130
	s_mov_b32 s10, 0x33800000
	s_waitcnt vmcnt(0)
	v_mov_b32_e32 v2, v248
	v_add_f32_e32 v3, v14, v2
	v_min_f32_e32 v2, 0, v3
	v_mul_f32_e64 v3, |v3|, s29
	v_exp_f32_e32 v3, v3
	s_nop 0
	v_add_f32_e32 v24, 1.0, v3
	v_add_f32_e32 v4, -1.0, v24
	v_sub_f32_e32 v5, v4, v24
	v_add_f32_e32 v5, 1.0, v5
	v_sub_f32_e32 v4, v3, v4
	v_add_f32_e32 v25, v4, v5
	v_frexp_mant_f32_e32 v4, v24
	v_cmp_gt_f32_e32 vcc, s50, v4
	v_cvt_f64_f32_e32 v[4:5], v24
	v_frexp_exp_i32_f64_e32 v4, v[4:5]
	v_subbrev_co_u32_e32 v30, vcc, 0, v4, vcc
	v_sub_u32_e32 v4, 0, v30
	v_ldexp_f32 v5, v24, v4
	v_add_f32_e32 v24, -1.0, v5
	v_add_f32_e32 v26, 1.0, v5
	v_ldexp_f32 v4, v25, v4
	v_add_f32_e32 v25, 1.0, v24
	v_add_f32_e32 v27, -1.0, v26
	v_sub_f32_e32 v25, v5, v25
	v_sub_f32_e32 v5, v5, v27
	v_add_f32_e32 v25, v4, v25
	v_add_f32_e32 v4, v4, v5
	v_add_f32_e32 v31, v26, v4
	v_rcp_f32_e32 v33, v31
	v_sub_f32_e32 v5, v31, v26
	v_sub_f32_e32 v32, v4, v5
	v_add_f32_e32 v5, v24, v25
	v_mul_f32_e32 v35, v5, v33
	v_sub_f32_e32 v4, v5, v24
	v_mul_f32_e32 v24, v31, v35
	v_fma_f32 v26, v35, v31, -v24
	v_fmac_f32_e32 v26, v35, v32
	v_sub_f32_e32 v34, v25, v4
	v_add_f32_e32 v4, v24, v26
	v_sub_f32_e32 v25, v5, v4
	v_pk_add_f32 v[28:29], v[4:5], v[24:25] neg_lo:[0,1] neg_hi:[0,1]
	v_mov_b32_e32 v27, v4
	v_pk_add_f32 v[4:5], v[28:29], v[26:27] neg_lo:[0,1] neg_hi:[0,1]
	v_cmp_neq_f32_e32 vcc, s52, v3
	v_add_f32_e32 v5, v34, v5
	v_add_f32_e32 v4, v4, v5
	v_add_f32_e32 v5, v25, v4
	v_mul_f32_e32 v34, v33, v5
	v_mul_f32_e32 v24, v31, v34
	v_fma_f32 v26, v34, v31, -v24
	v_fmac_f32_e32 v26, v34, v32
	v_sub_f32_e32 v25, v25, v5
	v_add_f32_e32 v31, v4, v25
	v_add_f32_e32 v4, v24, v26
	v_sub_f32_e32 v25, v5, v4
	v_pk_add_f32 v[28:29], v[4:5], v[24:25] neg_lo:[0,1] neg_hi:[0,1]
	v_mov_b32_e32 v27, v4
	v_pk_add_f32 v[4:5], v[28:29], v[26:27] neg_lo:[0,1] neg_hi:[0,1]
	s_nop 0
	v_add_f32_e32 v5, v31, v5
	v_add_f32_e32 v4, v4, v5
	v_add_f32_e32 v5, v35, v34
	v_add_f32_e32 v4, v25, v4
	v_sub_f32_e32 v24, v5, v35
	v_mul_f32_e32 v4, v33, v4
	v_sub_f32_e32 v24, v34, v24
	v_add_f32_e32 v24, v24, v4
	v_add_f32_e32 v26, v5, v24
	v_mul_f32_e32 v27, v26, v26
	v_fmamk_f32 v4, v27, 0x3e9b6dac, v233
	v_fmaak_f32 v185, v27, v4, 0x3f2aaada
	v_cvt_f32_i32_e32 v4, v30
	v_sub_f32_e32 v5, v26, v5
	v_sub_f32_e32 v5, v24, v5
	v_ldexp_f32 v28, v5, 1
	v_mul_f32_e32 v5, v26, v27
	v_ldexp_f32 v25, v26, 1
	v_pk_mul_f32 v[26:27], v[4:5], v[184:185]
	s_nop 0
	v_fma_f32 v24, v4, s51, -v26
	v_fmac_f32_e32 v24, 0xb102e308, v4
	v_pk_add_f32 v[4:5], v[26:27], v[24:25]
	s_nop 0
	v_sub_f32_e32 v25, v5, v25
	v_sub_f32_e32 v25, v27, v25
	v_add_f32_e32 v29, v28, v25
	v_mov_b32_e32 v28, v26
	v_pk_add_f32 v[26:27], v[4:5], v[26:27] neg_lo:[0,1] neg_hi:[0,1]
	v_pk_add_f32 v[30:31], v[4:5], v[28:29]
	v_mov_b32_e32 v25, v4
	v_mov_b32_e32 v27, v31
	v_pk_add_f32 v[32:33], v[24:25], v[26:27] neg_lo:[0,1] neg_hi:[0,1]
	v_pk_add_f32 v[24:25], v[24:25], v[26:27]
	v_mov_b32_e32 v28, v29
	v_pk_add_f32 v[26:27], v[24:25], v[4:5] op_sel:[1,0] op_sel_hi:[0,1] neg_lo:[0,1] neg_hi:[0,1]
	v_pk_add_f32 v[34:35], v[30:31], v[26:27] op_sel_hi:[1,0] neg_lo:[0,1] neg_hi:[0,1]
	v_mov_b32_e32 v30, v31
	v_mov_b32_e32 v31, v25
	v_pk_mov_b32 v[26:27], v[4:5], v[26:27] op_sel:[1,0]
	v_mov_b32_e32 v29, v4
	v_pk_add_f32 v[26:27], v[30:31], v[26:27] neg_lo:[0,1] neg_hi:[0,1]
	v_mov_b32_e32 v34, v32
	v_pk_add_f32 v[4:5], v[28:29], v[26:27] neg_lo:[0,1] neg_hi:[0,1]
	v_mov_b32_e32 v33, v25
	v_pk_add_f32 v[26:27], v[34:35], v[4:5]
	s_nop 0
	v_pk_add_f32 v[28:29], v[26:27], v[26:27] op_sel:[0,1] op_sel_hi:[1,0]
	s_nop 0
	v_pk_add_f32 v[24:25], v[24:25], v[28:29] op_sel:[1,0] op_sel_hi:[0,1]
	v_mov_b32_e32 v27, v24
	v_pk_add_f32 v[30:31], v[26:27], v[32:33] neg_lo:[0,1] neg_hi:[0,1]
	v_mov_b32_e32 v5, v28
	v_sub_f32_e32 v25, v26, v30
	v_pk_add_f32 v[4:5], v[4:5], v[30:31] neg_lo:[0,1] neg_hi:[0,1]
	v_sub_f32_e32 v25, v32, v25
	v_add_f32_e32 v4, v4, v25
	v_add_f32_e32 v4, v4, v5
	v_add_f32_e32 v4, v24, v4
	v_cndmask_b32_e32 v4, v226, v4, vcc
	v_cmp_ngt_f32_e32 vcc, -1.0, v3
	s_nop 1
	v_cndmask_b32_e32 v4, v227, v4, vcc
	v_cmp_neq_f32_e32 vcc, -1.0, v3
	s_nop 1
	v_cndmask_b32_e32 v4, v236, v4, vcc
	v_cmp_lt_f32_e64 vcc, |v3|, s10
	s_nop 1
	v_cndmask_b32_e32 v3, v4, v3, vcc
	v_sub_f32_e32 v4, v2, v3

.LBB0_1132:
	s_andn2_saveexec_b64 s[8:9], s[8:9]
	s_cbranch_execz .LBB0_1134
	s_mov_b32 s10, 0x33800000
	s_waitcnt vmcnt(0)
	v_mov_b32_e32 v4, v249
	v_add_f32_e32 v5, v15, v4
	v_min_f32_e32 v4, 0, v5
	v_mul_f32_e64 v5, |v5|, s29
	v_exp_f32_e32 v5, v5
	s_nop 0
	v_add_f32_e32 v26, 1.0, v5
	v_add_f32_e32 v24, -1.0, v26
	v_sub_f32_e32 v25, v24, v26
	v_add_f32_e32 v25, 1.0, v25
	v_sub_f32_e32 v24, v5, v24
	v_add_f32_e32 v27, v24, v25
	v_frexp_mant_f32_e32 v24, v26
	v_cmp_gt_f32_e32 vcc, s50, v24
	v_cvt_f64_f32_e32 v[24:25], v26
	v_frexp_exp_i32_f64_e32 v24, v[24:25]
	v_subbrev_co_u32_e32 v32, vcc, 0, v24, vcc
	v_sub_u32_e32 v24, 0, v32
	v_ldexp_f32 v25, v26, v24
	v_add_f32_e32 v26, -1.0, v25
	v_add_f32_e32 v28, 1.0, v25
	v_ldexp_f32 v24, v27, v24
	v_add_f32_e32 v27, 1.0, v26
	v_add_f32_e32 v29, -1.0, v28
	v_sub_f32_e32 v27, v25, v27
	v_sub_f32_e32 v25, v25, v29
	v_add_f32_e32 v27, v24, v27
	v_add_f32_e32 v24, v24, v25
	v_add_f32_e32 v33, v28, v24
	v_rcp_f32_e32 v35, v33
	v_sub_f32_e32 v25, v33, v28
	v_sub_f32_e32 v34, v24, v25
	v_add_f32_e32 v25, v26, v27
	v_mul_f32_e32 v37, v25, v35
	v_sub_f32_e32 v24, v25, v26
	v_mul_f32_e32 v26, v33, v37
	v_fma_f32 v28, v37, v33, -v26
	v_fmac_f32_e32 v28, v37, v34
	v_sub_f32_e32 v36, v27, v24
	v_add_f32_e32 v24, v26, v28
	v_sub_f32_e32 v27, v25, v24
	v_pk_add_f32 v[30:31], v[24:25], v[26:27] neg_lo:[0,1] neg_hi:[0,1]
	v_mov_b32_e32 v29, v24
	v_pk_add_f32 v[24:25], v[30:31], v[28:29] neg_lo:[0,1] neg_hi:[0,1]
	v_cmp_neq_f32_e32 vcc, s52, v5
	v_add_f32_e32 v25, v36, v25
	v_add_f32_e32 v24, v24, v25
	v_add_f32_e32 v25, v27, v24
	v_mul_f32_e32 v36, v35, v25
	v_mul_f32_e32 v26, v33, v36
	v_fma_f32 v28, v36, v33, -v26
	v_fmac_f32_e32 v28, v36, v34
	v_sub_f32_e32 v27, v27, v25
	v_add_f32_e32 v33, v24, v27
	v_add_f32_e32 v24, v26, v28
	v_sub_f32_e32 v27, v25, v24
	v_pk_add_f32 v[30:31], v[24:25], v[26:27] neg_lo:[0,1] neg_hi:[0,1]
	v_mov_b32_e32 v29, v24
	v_pk_add_f32 v[24:25], v[30:31], v[28:29] neg_lo:[0,1] neg_hi:[0,1]
	s_nop 0
	v_add_f32_e32 v25, v33, v25
	v_add_f32_e32 v24, v24, v25
	v_add_f32_e32 v25, v37, v36
	v_add_f32_e32 v24, v27, v24
	v_sub_f32_e32 v26, v25, v37
	v_mul_f32_e32 v24, v35, v24
	v_sub_f32_e32 v26, v36, v26
	v_add_f32_e32 v26, v26, v24
	v_add_f32_e32 v28, v25, v26
	v_mul_f32_e32 v29, v28, v28
	v_fmamk_f32 v24, v29, 0x3e9b6dac, v233
	v_fmaak_f32 v185, v29, v24, 0x3f2aaada
	v_cvt_f32_i32_e32 v24, v32
	v_sub_f32_e32 v25, v28, v25
	v_sub_f32_e32 v25, v26, v25
	v_ldexp_f32 v30, v25, 1
	v_mul_f32_e32 v25, v28, v29
	v_ldexp_f32 v27, v28, 1
	v_pk_mul_f32 v[28:29], v[24:25], v[184:185]
	s_nop 0
	v_fma_f32 v26, v24, s51, -v28
	v_fmac_f32_e32 v26, 0xb102e308, v24
	v_pk_add_f32 v[24:25], v[28:29], v[26:27]
	s_nop 0
	v_sub_f32_e32 v27, v25, v27
	v_sub_f32_e32 v27, v29, v27
	v_add_f32_e32 v31, v30, v27
	v_mov_b32_e32 v30, v28
	v_pk_add_f32 v[28:29], v[24:25], v[28:29] neg_lo:[0,1] neg_hi:[0,1]
	v_pk_add_f32 v[32:33], v[24:25], v[30:31]
	v_mov_b32_e32 v27, v24
	v_mov_b32_e32 v29, v33
	v_pk_add_f32 v[34:35], v[26:27], v[28:29] neg_lo:[0,1] neg_hi:[0,1]
	v_pk_add_f32 v[26:27], v[26:27], v[28:29]
	v_mov_b32_e32 v30, v31
	v_pk_add_f32 v[28:29], v[26:27], v[24:25] op_sel:[1,0] op_sel_hi:[0,1] neg_lo:[0,1] neg_hi:[0,1]
	v_pk_add_f32 v[36:37], v[32:33], v[28:29] op_sel_hi:[1,0] neg_lo:[0,1] neg_hi:[0,1]
	v_mov_b32_e32 v32, v33
	v_mov_b32_e32 v33, v27
	v_pk_mov_b32 v[28:29], v[24:25], v[28:29] op_sel:[1,0]
	v_mov_b32_e32 v31, v24
	v_pk_add_f32 v[28:29], v[32:33], v[28:29] neg_lo:[0,1] neg_hi:[0,1]
	v_mov_b32_e32 v36, v34
	v_pk_add_f32 v[24:25], v[30:31], v[28:29] neg_lo:[0,1] neg_hi:[0,1]
	v_mov_b32_e32 v35, v27
	v_pk_add_f32 v[28:29], v[36:37], v[24:25]
	s_nop 0
	v_pk_add_f32 v[30:31], v[28:29], v[28:29] op_sel:[0,1] op_sel_hi:[1,0]
	s_nop 0
	v_pk_add_f32 v[26:27], v[26:27], v[30:31] op_sel:[1,0] op_sel_hi:[0,1]
	v_mov_b32_e32 v29, v26
	v_pk_add_f32 v[32:33], v[28:29], v[34:35] neg_lo:[0,1] neg_hi:[0,1]
	v_mov_b32_e32 v25, v30
	v_sub_f32_e32 v27, v28, v32
	v_pk_add_f32 v[24:25], v[24:25], v[32:33] neg_lo:[0,1] neg_hi:[0,1]
	v_sub_f32_e32 v27, v34, v27
	v_add_f32_e32 v24, v24, v27
	v_add_f32_e32 v24, v24, v25
	v_add_f32_e32 v24, v26, v24
	v_cndmask_b32_e32 v24, v226, v24, vcc
	v_cmp_ngt_f32_e32 vcc, -1.0, v5
	s_nop 1
	v_cndmask_b32_e32 v24, v227, v24, vcc
	v_cmp_neq_f32_e32 vcc, -1.0, v5
	s_nop 1
	v_cndmask_b32_e32 v24, v236, v24, vcc
	v_cmp_lt_f32_e64 vcc, |v5|, s10
	s_nop 1
	v_cndmask_b32_e32 v5, v24, v5, vcc
	v_sub_f32_e32 v4, v4, v5

.LBB0_1136:
	s_andn2_saveexec_b64 s[8:9], s[8:9]
	s_cbranch_execz .LBB0_1138
	s_mov_b32 s10, 0x33800000
	s_waitcnt vmcnt(0)
	v_mov_b32_e32 v2, v250
	v_add_f32_e32 v3, v20, v2
	v_min_f32_e32 v2, 0, v3
	v_mul_f32_e64 v3, |v3|, s29
	v_exp_f32_e32 v3, v3
	s_nop 0
	v_add_f32_e32 v26, 1.0, v3
	v_add_f32_e32 v4, -1.0, v26
	v_sub_f32_e32 v5, v4, v26
	v_add_f32_e32 v5, 1.0, v5
	v_sub_f32_e32 v4, v3, v4
	v_add_f32_e32 v27, v4, v5
	v_frexp_mant_f32_e32 v4, v26
	v_cmp_gt_f32_e32 vcc, s50, v4
	v_cvt_f64_f32_e32 v[4:5], v26
	v_frexp_exp_i32_f64_e32 v4, v[4:5]
	v_subbrev_co_u32_e32 v32, vcc, 0, v4, vcc
	v_sub_u32_e32 v4, 0, v32
	v_ldexp_f32 v5, v26, v4
	v_add_f32_e32 v26, -1.0, v5
	v_add_f32_e32 v28, 1.0, v5
	v_ldexp_f32 v4, v27, v4
	v_add_f32_e32 v27, 1.0, v26
	v_add_f32_e32 v29, -1.0, v28
	v_sub_f32_e32 v27, v5, v27
	v_sub_f32_e32 v5, v5, v29
	v_add_f32_e32 v27, v4, v27
	v_add_f32_e32 v4, v4, v5
	v_add_f32_e32 v33, v28, v4
	v_rcp_f32_e32 v35, v33
	v_sub_f32_e32 v5, v33, v28
	v_sub_f32_e32 v34, v4, v5
	v_add_f32_e32 v5, v26, v27
	v_mul_f32_e32 v37, v5, v35
	v_sub_f32_e32 v4, v5, v26
	v_mul_f32_e32 v26, v33, v37
	v_fma_f32 v28, v37, v33, -v26
	v_fmac_f32_e32 v28, v37, v34
	v_sub_f32_e32 v36, v27, v4
	v_add_f32_e32 v4, v26, v28
	v_sub_f32_e32 v27, v5, v4
	v_pk_add_f32 v[30:31], v[4:5], v[26:27] neg_lo:[0,1] neg_hi:[0,1]
	v_mov_b32_e32 v29, v4
	v_pk_add_f32 v[4:5], v[30:31], v[28:29] neg_lo:[0,1] neg_hi:[0,1]
	v_cmp_neq_f32_e32 vcc, s52, v3
	v_add_f32_e32 v5, v36, v5
	v_add_f32_e32 v4, v4, v5
	v_add_f32_e32 v5, v27, v4
	v_mul_f32_e32 v36, v35, v5
	v_mul_f32_e32 v26, v33, v36
	v_fma_f32 v28, v36, v33, -v26
	v_fmac_f32_e32 v28, v36, v34
	v_sub_f32_e32 v27, v27, v5
	v_add_f32_e32 v33, v4, v27
	v_add_f32_e32 v4, v26, v28
	v_sub_f32_e32 v27, v5, v4
	v_pk_add_f32 v[30:31], v[4:5], v[26:27] neg_lo:[0,1] neg_hi:[0,1]
	v_mov_b32_e32 v29, v4
	v_pk_add_f32 v[4:5], v[30:31], v[28:29] neg_lo:[0,1] neg_hi:[0,1]
	s_nop 0
	v_add_f32_e32 v5, v33, v5
	v_add_f32_e32 v4, v4, v5
	v_add_f32_e32 v5, v37, v36
	v_add_f32_e32 v4, v27, v4
	v_sub_f32_e32 v26, v5, v37
	v_mul_f32_e32 v4, v35, v4
	v_sub_f32_e32 v26, v36, v26
	v_add_f32_e32 v26, v26, v4
	v_add_f32_e32 v28, v5, v26
	v_mul_f32_e32 v29, v28, v28
	v_fmamk_f32 v4, v29, 0x3e9b6dac, v233
	v_fmaak_f32 v185, v29, v4, 0x3f2aaada
	v_cvt_f32_i32_e32 v4, v32
	v_sub_f32_e32 v5, v28, v5
	v_sub_f32_e32 v5, v26, v5
	v_ldexp_f32 v30, v5, 1
	v_mul_f32_e32 v5, v28, v29
	v_ldexp_f32 v27, v28, 1
	v_pk_mul_f32 v[28:29], v[4:5], v[184:185]
	s_nop 0
	v_fma_f32 v26, v4, s51, -v28
	v_fmac_f32_e32 v26, 0xb102e308, v4
	v_pk_add_f32 v[4:5], v[28:29], v[26:27]
	s_nop 0
	v_sub_f32_e32 v27, v5, v27
	v_sub_f32_e32 v27, v29, v27
	v_add_f32_e32 v31, v30, v27
	v_mov_b32_e32 v30, v28
	v_pk_add_f32 v[28:29], v[4:5], v[28:29] neg_lo:[0,1] neg_hi:[0,1]
	v_pk_add_f32 v[32:33], v[4:5], v[30:31]
	v_mov_b32_e32 v27, v4
	v_mov_b32_e32 v29, v33
	v_pk_add_f32 v[34:35], v[26:27], v[28:29] neg_lo:[0,1] neg_hi:[0,1]
	v_pk_add_f32 v[26:27], v[26:27], v[28:29]
	v_mov_b32_e32 v30, v31
	v_pk_add_f32 v[28:29], v[26:27], v[4:5] op_sel:[1,0] op_sel_hi:[0,1] neg_lo:[0,1] neg_hi:[0,1]
	v_pk_add_f32 v[36:37], v[32:33], v[28:29] op_sel_hi:[1,0] neg_lo:[0,1] neg_hi:[0,1]
	v_mov_b32_e32 v32, v33
	v_mov_b32_e32 v33, v27
	v_pk_mov_b32 v[28:29], v[4:5], v[28:29] op_sel:[1,0]
	v_mov_b32_e32 v31, v4
	v_pk_add_f32 v[28:29], v[32:33], v[28:29] neg_lo:[0,1] neg_hi:[0,1]
	v_mov_b32_e32 v36, v34
	v_pk_add_f32 v[4:5], v[30:31], v[28:29] neg_lo:[0,1] neg_hi:[0,1]
	v_mov_b32_e32 v35, v27
	v_pk_add_f32 v[28:29], v[36:37], v[4:5]
	s_nop 0
	v_pk_add_f32 v[30:31], v[28:29], v[28:29] op_sel:[0,1] op_sel_hi:[1,0]
	s_nop 0
	v_pk_add_f32 v[26:27], v[26:27], v[30:31] op_sel:[1,0] op_sel_hi:[0,1]
	v_mov_b32_e32 v29, v26
	v_pk_add_f32 v[32:33], v[28:29], v[34:35] neg_lo:[0,1] neg_hi:[0,1]
	v_mov_b32_e32 v5, v30
	v_sub_f32_e32 v27, v28, v32
	v_pk_add_f32 v[4:5], v[4:5], v[32:33] neg_lo:[0,1] neg_hi:[0,1]
	v_sub_f32_e32 v27, v34, v27
	v_add_f32_e32 v4, v4, v27
	v_add_f32_e32 v4, v4, v5
	v_add_f32_e32 v4, v26, v4
	v_cndmask_b32_e32 v4, v226, v4, vcc
	v_cmp_ngt_f32_e32 vcc, -1.0, v3
	s_nop 1
	v_cndmask_b32_e32 v4, v227, v4, vcc
	v_cmp_neq_f32_e32 vcc, -1.0, v3
	s_nop 1
	v_cndmask_b32_e32 v4, v236, v4, vcc
	v_cmp_lt_f32_e64 vcc, |v3|, s10
	s_nop 1
	v_cndmask_b32_e32 v3, v4, v3, vcc
	v_sub_f32_e32 v2, v2, v3

.LBB0_1140:
	s_andn2_saveexec_b64 s[8:9], s[8:9]
	s_cbranch_execz .LBB0_1142
	s_mov_b32 s10, 0x33800000
	s_waitcnt vmcnt(0)
	v_mov_b32_e32 v2, v251
	v_add_f32_e32 v3, v21, v2
	v_min_f32_e32 v2, 0, v3
	v_mul_f32_e64 v3, |v3|, s29
	v_exp_f32_e32 v3, v3
	s_nop 0
	v_add_f32_e32 v26, 1.0, v3
	v_add_f32_e32 v4, -1.0, v26
	v_sub_f32_e32 v5, v4, v26
	v_add_f32_e32 v5, 1.0, v5
	v_sub_f32_e32 v4, v3, v4
	v_add_f32_e32 v27, v4, v5
	v_frexp_mant_f32_e32 v4, v26
	v_cmp_gt_f32_e32 vcc, s50, v4
	v_cvt_f64_f32_e32 v[4:5], v26
	v_frexp_exp_i32_f64_e32 v4, v[4:5]
	v_subbrev_co_u32_e32 v32, vcc, 0, v4, vcc
	v_sub_u32_e32 v4, 0, v32
	v_ldexp_f32 v5, v26, v4
	v_add_f32_e32 v26, -1.0, v5
	v_add_f32_e32 v28, 1.0, v5
	v_ldexp_f32 v4, v27, v4
	v_add_f32_e32 v27, 1.0, v26
	v_add_f32_e32 v29, -1.0, v28
	v_sub_f32_e32 v27, v5, v27
	v_sub_f32_e32 v5, v5, v29
	v_add_f32_e32 v27, v4, v27
	v_add_f32_e32 v4, v4, v5
	v_add_f32_e32 v33, v28, v4
	v_rcp_f32_e32 v35, v33
	v_sub_f32_e32 v5, v33, v28
	v_sub_f32_e32 v34, v4, v5
	v_add_f32_e32 v5, v26, v27
	v_mul_f32_e32 v37, v5, v35
	v_sub_f32_e32 v4, v5, v26
	v_mul_f32_e32 v26, v33, v37
	v_fma_f32 v28, v37, v33, -v26
	v_fmac_f32_e32 v28, v37, v34
	v_sub_f32_e32 v36, v27, v4
	v_add_f32_e32 v4, v26, v28
	v_sub_f32_e32 v27, v5, v4
	v_pk_add_f32 v[30:31], v[4:5], v[26:27] neg_lo:[0,1] neg_hi:[0,1]
	v_mov_b32_e32 v29, v4
	v_pk_add_f32 v[4:5], v[30:31], v[28:29] neg_lo:[0,1] neg_hi:[0,1]
	v_cmp_neq_f32_e32 vcc, s52, v3
	v_add_f32_e32 v5, v36, v5
	v_add_f32_e32 v4, v4, v5
	v_add_f32_e32 v5, v27, v4
	v_mul_f32_e32 v36, v35, v5
	v_mul_f32_e32 v26, v33, v36
	v_fma_f32 v28, v36, v33, -v26
	v_fmac_f32_e32 v28, v36, v34
	v_sub_f32_e32 v27, v27, v5
	v_add_f32_e32 v33, v4, v27
	v_add_f32_e32 v4, v26, v28
	v_sub_f32_e32 v27, v5, v4
	v_pk_add_f32 v[30:31], v[4:5], v[26:27] neg_lo:[0,1] neg_hi:[0,1]
	v_mov_b32_e32 v29, v4
	v_pk_add_f32 v[4:5], v[30:31], v[28:29] neg_lo:[0,1] neg_hi:[0,1]
	s_nop 0
	v_add_f32_e32 v5, v33, v5
	v_add_f32_e32 v4, v4, v5
	v_add_f32_e32 v5, v37, v36
	v_add_f32_e32 v4, v27, v4
	v_sub_f32_e32 v26, v5, v37
	v_mul_f32_e32 v4, v35, v4
	v_sub_f32_e32 v26, v36, v26
	v_add_f32_e32 v26, v26, v4
	v_add_f32_e32 v28, v5, v26
	v_mul_f32_e32 v29, v28, v28
	v_fmamk_f32 v4, v29, 0x3e9b6dac, v233
	v_fmaak_f32 v185, v29, v4, 0x3f2aaada
	v_cvt_f32_i32_e32 v4, v32
	v_sub_f32_e32 v5, v28, v5
	v_sub_f32_e32 v5, v26, v5
	v_ldexp_f32 v30, v5, 1
	v_mul_f32_e32 v5, v28, v29
	v_ldexp_f32 v27, v28, 1
	v_pk_mul_f32 v[28:29], v[4:5], v[184:185]
	s_nop 0
	v_fma_f32 v26, v4, s51, -v28
	v_fmac_f32_e32 v26, 0xb102e308, v4
	v_pk_add_f32 v[4:5], v[28:29], v[26:27]
	s_nop 0
	v_sub_f32_e32 v27, v5, v27
	v_sub_f32_e32 v27, v29, v27
	v_add_f32_e32 v31, v30, v27
	v_mov_b32_e32 v30, v28
	v_pk_add_f32 v[28:29], v[4:5], v[28:29] neg_lo:[0,1] neg_hi:[0,1]
	v_pk_add_f32 v[32:33], v[4:5], v[30:31]
	v_mov_b32_e32 v27, v4
	v_mov_b32_e32 v29, v33
	v_pk_add_f32 v[34:35], v[26:27], v[28:29] neg_lo:[0,1] neg_hi:[0,1]
	v_pk_add_f32 v[26:27], v[26:27], v[28:29]
	v_mov_b32_e32 v30, v31
	v_pk_add_f32 v[28:29], v[26:27], v[4:5] op_sel:[1,0] op_sel_hi:[0,1] neg_lo:[0,1] neg_hi:[0,1]
	v_pk_add_f32 v[36:37], v[32:33], v[28:29] op_sel_hi:[1,0] neg_lo:[0,1] neg_hi:[0,1]
	v_mov_b32_e32 v32, v33
	v_mov_b32_e32 v33, v27
	v_pk_mov_b32 v[28:29], v[4:5], v[28:29] op_sel:[1,0]
	v_mov_b32_e32 v31, v4
	v_pk_add_f32 v[28:29], v[32:33], v[28:29] neg_lo:[0,1] neg_hi:[0,1]
	v_mov_b32_e32 v36, v34
	v_pk_add_f32 v[4:5], v[30:31], v[28:29] neg_lo:[0,1] neg_hi:[0,1]
	v_mov_b32_e32 v35, v27
	v_pk_add_f32 v[28:29], v[36:37], v[4:5]
	s_nop 0
	v_pk_add_f32 v[30:31], v[28:29], v[28:29] op_sel:[0,1] op_sel_hi:[1,0]
	s_nop 0
	v_pk_add_f32 v[26:27], v[26:27], v[30:31] op_sel:[1,0] op_sel_hi:[0,1]
	v_mov_b32_e32 v29, v26
	v_pk_add_f32 v[32:33], v[28:29], v[34:35] neg_lo:[0,1] neg_hi:[0,1]
	v_mov_b32_e32 v5, v30
	v_sub_f32_e32 v27, v28, v32
	v_pk_add_f32 v[4:5], v[4:5], v[32:33] neg_lo:[0,1] neg_hi:[0,1]
	v_sub_f32_e32 v27, v34, v27
	v_add_f32_e32 v4, v4, v27
	v_add_f32_e32 v4, v4, v5
	v_add_f32_e32 v4, v26, v4
	v_cndmask_b32_e32 v4, v226, v4, vcc
	v_cmp_ngt_f32_e32 vcc, -1.0, v3
	s_nop 1
	v_cndmask_b32_e32 v4, v227, v4, vcc
	v_cmp_neq_f32_e32 vcc, -1.0, v3
	s_nop 1
	v_cndmask_b32_e32 v4, v236, v4, vcc
	v_cmp_lt_f32_e64 vcc, |v3|, s10
	s_nop 1
	v_cndmask_b32_e32 v3, v4, v3, vcc
	v_sub_f32_e32 v2, v2, v3
